# kept version plus nt hint on the in-proj epilogue stores of the read-once activations (qb, kb, vb, gates, log-decay) so the re-read Q/K/V stay cache-resident
# baseline (speedup 1.0000x reference)
; __device__ __forceinline__ v4u pack8(const f32x4 a, const f32x4 b) { v4u w; w.x = pk2(a[0], a[1]); w.y = pk2(a[2], a[3]); w.z = pk2(b[0], b[1]); w.w = pk2(b[2], b[3]); return w; }
; __device__ __forceinline__ float fast_exp(float x) { return __builtin_amdgcn_exp2f(x * LOG2E); }
;     __device__ __forceinline__ void operator()(const f32x4 (&acc)[2][2][4][2], const pg8::Unit& u, int wr, int wc, int fr, int fq) const {
;     ...
;         TileT tt; tt.init(stg, wr * 4 + wc, fr, fq);
;         float rs8[2][4];
; #pragma unroll
;         for (int ai = 0; ai < 2; ++ai)
; #pragma unroll
;             for (int m = 0; m < 4; ++m) rs8[ai][m] = rstd[256 * pm + 128 * ai + 64 * wr + 16 * m + fr];
;         if (pn < 4) {
;     ...
;         } else {
;             f32x4 bg[2][2];
; #pragma unroll
;             for (int bj = 0; bj < 2; ++bj)
; #pragma unroll
;                 for (int n = 0; n < 2; ++n) bg[bj][n] = *(const f32x4*)(bgate + 64 * wc + 32 * bj + 8 * fq + 4 * n);
; #pragma unroll
;             for (int ai = 0; ai < 2; ++ai)
; #pragma unroll
;                 for (int m = 0; m < 4; ++m) {
;                     const int rowa = 256 * pm + 128 * ai + 64 * wr + 16 * m + tt.rr;
;                     const float rs = rs8[ai][m];
;                     v4u pk[2];
; #pragma unroll
;                     for (int bj = 0; bj < 2; ++bj) {
;                         f32x4 r2[2];
; #pragma unroll
;                         for (int n = 0; n < 2; ++n) {
;                             const f32x4 z = acc[ai][bj][m][n] * rs + bg[bj][n];
; #pragma unroll
;                             for (int j = 0; j < 4; ++j) { const float az = fabsf(z[j]); r2[n][j] = (fminf(z[j], 0.f) - __logf(1.0f + fast_exp(-az))) * (1.0f / 16.0f); }
;                         }
;                         pk[bj] = pack8(r2[0], r2[1]);
;                     }
;                     v4u a, b; tt.bf(pk[0], pk[1], a, b);
;                     bf16* d = (bf16*)(ws + WS_LOGA) + (size_t)rowa * 256 + 64 * wc + 8 * tt.p; *(v4u*)d = a; *(v4u*)(d + 8 * 256) = b;
;                 }
.LBB0_414:
	v_mov_b32_e32 v158, v216
	v_mov_b32_e32 v146, v1
	s_lshl_b32 s9, s8, 8
	v_add_u32_e32 v159, s66, v146
	v_add_u32_e32 v130, s9, v159
	v_ashrrev_i32_e32 v131, 31, v130
	v_lshl_add_u64 v[132:133], v[130:131], 2, s[16:17]
	v_add_u32_e32 v134, 16, v130
	v_add_u32_e32 v136, 32, v130
	v_add_u32_e32 v138, 48, v130
	v_add_u32_e32 v140, 0x80, v130
	v_add_u32_e32 v142, 0x90, v130
	v_add_u32_e32 v144, 0xa0, v130
	v_add_u32_e32 v130, 0xb0, v130
	v_ashrrev_i32_e32 v135, 31, v134
	v_ashrrev_i32_e32 v137, 31, v136
	v_ashrrev_i32_e32 v139, 31, v138
	v_ashrrev_i32_e32 v141, 31, v140
	v_ashrrev_i32_e32 v143, 31, v142
	v_ashrrev_i32_e32 v145, 31, v144
	v_ashrrev_i32_e32 v131, 31, v130
	v_lshl_add_u64 v[134:135], v[134:135], 2, s[16:17]
	v_lshl_add_u64 v[136:137], v[136:137], 2, s[16:17]
	v_lshl_add_u64 v[138:139], v[138:139], 2, s[16:17]
	v_lshl_add_u64 v[140:141], v[140:141], 2, s[16:17]
	v_lshl_add_u64 v[142:143], v[142:143], 2, s[16:17]
	v_lshl_add_u64 v[144:145], v[144:145], 2, s[16:17]
	v_lshl_add_u64 v[130:131], v[130:131], 2, s[16:17]
	global_load_dword v162, v[132:133], off
	global_load_dword v210, v[134:135], off
	global_load_dword v208, v[136:137], off
	global_load_dword v206, v[138:139], off
	global_load_dword v204, v[140:141], off
	global_load_dword v202, v[142:143], off
	global_load_dword v198, v[144:145], off
	global_load_dword v196, v[130:131], off
	v_lshlrev_b32_e32 v200, 4, v158
	v_add_u32_e32 v130, v200, v146
	v_and_b32_e32 v213, 7, v146
	v_add_u32_e32 v132, 4, v158
	v_lshlrev_b32_e32 v133, 1, v158
	v_ashrrev_i32_e32 v227, 3, v130
	v_lshlrev_b32_e32 v130, 7, v146
	v_bitop3_b32 v131, v146, v158, 7 bitop3:0x6c
	v_bitop3_b32 v132, v132, v146, 7 bitop3:0x78
	v_bitop3_b32 v134, v133, v146, 7 bitop3:0x78
	v_bitop3_b32 v133, v133, v213, 1 bitop3:0x36
	v_lshl_add_u32 v225, v133, 4, v130
	v_bitop3_b32 v133, v227, v146, 7 bitop3:0x78
	s_cmpk_gt_i32 s8, 0xff
	v_lshl_add_u32 v229, v131, 4, v130
	v_lshl_add_u32 v228, v132, 4, v130
	v_lshl_add_u32 v226, v134, 4, v130
	v_lshlrev_b32_e32 v130, 7, v227
	s_cselect_b64 s[4:5], -1, 0
	v_lshl_add_u32 v230, v133, 4, v130
	s_cmp_gt_i32 s42, 3
	s_mov_b64 s[6:7], -1
	s_cbranch_scc0 .LBB0_475
	s_cmp_gt_u32 s42, 5
	s_cbranch_scc0 .LBB0_457
	s_cmp_gt_u32 s42, 7
	s_cbranch_scc0 .LBB0_454
	s_add_i32 s0, s9, s66
	v_add_u32_e32 v150, s0, v227
	s_cmp_gt_u32 s42, 13
	v_ashrrev_i32_e32 v151, 31, v150
	s_cbranch_scc0 .LBB0_419
	v_lshlrev_b32_e32 v130, 3, v158
	v_ashrrev_i32_e32 v131, 31, v130
	v_lshl_add_u64 v[130:131], v[130:131], 2, v[186:187]
	flat_load_dwordx4 v[142:145], v[130:131]
	flat_load_dwordx4 v[138:141], v[130:131] offset:16
	flat_load_dwordx4 v[134:137], v[130:131] offset:128
	s_nop 0
	flat_load_dwordx4 v[130:133], v[130:131] offset:144
	v_lshlrev_b32_e32 v184, 4, v213
	s_waitcnt vmcnt(0) lgkmcnt(0)
	v_fma_f32 v147, v126, v162, v142
	v_min_f32_e32 v146, 0, v147
	v_mul_f32_e64 v147, |v147|, s88
	v_exp_f32_e32 v147, v147
	v_fma_f32 v149, v127, v162, v143
	v_fma_f32 v153, v129, v162, v145
	v_fma_f32 v155, v123, v162, v139
	v_add_f32_e32 v147, 1.0, v147
	v_cmp_gt_f32_e32 vcc, s89, v147
	v_fma_f32 v157, v125, v162, v141
	v_fma_f32 v161, v115, v162, v131
	v_cndmask_b32_e64 v148, 0, 32, vcc
	v_ldexp_f32 v147, v147, v148
	v_log_f32_e32 v147, v147
	v_fma_f32 v167, v101, v210, v133
	v_mul_f32_e32 v148, 0x3f317217, v147
	v_fma_f32 v148, v147, s90, -v148
	v_fmac_f32_e32 v148, 0x3377d1cf, v147
	v_fmac_f32_e32 v148, 0x3f317217, v147
	v_cmp_lt_f32_e64 s[6:7], |v147|, s91
	s_nop 1
	v_cndmask_b32_e64 v147, v147, v148, s[6:7]
	v_cndmask_b32_e32 v148, 0, v222, vcc
	v_sub_f32_e32 v148, v147, v148
	v_min_f32_e32 v147, 0, v149
	v_mul_f32_e64 v149, |v149|, s88
	v_exp_f32_e32 v149, v149
	s_nop 0
	v_add_f32_e32 v149, 1.0, v149
	v_cmp_gt_f32_e32 vcc, s89, v149
	s_nop 1
	v_cndmask_b32_e64 v152, 0, 32, vcc
	v_ldexp_f32 v149, v149, v152
	v_log_f32_e32 v149, v149
	s_nop 0
	v_mul_f32_e32 v152, 0x3f317217, v149
	v_fma_f32 v152, v149, s90, -v152
	v_fmac_f32_e32 v152, 0x3377d1cf, v149
	v_fmac_f32_e32 v152, 0x3f317217, v149
	v_cmp_lt_f32_e64 s[6:7], |v149|, s91
	s_nop 1
	v_cndmask_b32_e64 v149, v149, v152, s[6:7]
	v_cndmask_b32_e32 v152, 0, v222, vcc
	v_sub_f32_e32 v149, v149, v152
	v_pk_add_f32 v[146:147], v[146:147], v[148:149] neg_lo:[0,1] neg_hi:[0,1]
	v_fma_f32 v149, v128, v162, v144
	v_min_f32_e32 v148, 0, v149
	v_mul_f32_e64 v149, |v149|, s88
	v_exp_f32_e32 v149, v149
	v_pk_mul_f32 v[146:147], v[146:147], s[28:29] op_sel_hi:[1,0]
	v_add_f32_e32 v149, 1.0, v149
	v_cmp_gt_f32_e32 vcc, s89, v149
	v_cvt_pk_bf16_f32 v146, v146, v147
	s_nop 0
	v_cndmask_b32_e64 v152, 0, 32, vcc
	v_ldexp_f32 v149, v149, v152
	v_log_f32_e32 v149, v149
	s_nop 0
	v_mul_f32_e32 v152, 0x3f317217, v149
	v_fma_f32 v152, v149, s90, -v152
	v_fmac_f32_e32 v152, 0x3377d1cf, v149
	v_fmac_f32_e32 v152, 0x3f317217, v149
	v_cmp_lt_f32_e64 s[6:7], |v149|, s91
	s_nop 1
	v_cndmask_b32_e64 v149, v149, v152, s[6:7]
	v_cndmask_b32_e32 v152, 0, v222, vcc
	v_sub_f32_e32 v152, v149, v152
	v_min_f32_e32 v149, 0, v153
	v_mul_f32_e64 v153, |v153|, s88
	v_exp_f32_e32 v153, v153
	s_nop 0
	v_add_f32_e32 v153, 1.0, v153
	v_cmp_gt_f32_e32 vcc, s89, v153
	s_nop 1
	v_cndmask_b32_e64 v154, 0, 32, vcc
	v_ldexp_f32 v153, v153, v154
	v_log_f32_e32 v153, v153
	s_nop 0
	v_mul_f32_e32 v154, 0x3f317217, v153
	v_fma_f32 v154, v153, s90, -v154
	v_fmac_f32_e32 v154, 0x3377d1cf, v153
	v_fmac_f32_e32 v154, 0x3f317217, v153
	v_cmp_lt_f32_e64 s[6:7], |v153|, s91
	s_nop 1
	v_cndmask_b32_e64 v153, v153, v154, s[6:7]
	v_cndmask_b32_e32 v154, 0, v222, vcc
	v_sub_f32_e32 v153, v153, v154
	v_pk_add_f32 v[148:149], v[148:149], v[152:153] neg_lo:[0,1] neg_hi:[0,1]
	v_fma_f32 v153, v122, v162, v138
; __device__ __forceinline__ v4u pack8(const f32x4 a, const f32x4 b) { v4u w; w.x = pk2(a[0], a[1]); w.y = pk2(a[2], a[3]); w.z = pk2(b[0], b[1]); w.w = pk2(b[2], b[3]); return w; }
; __device__ __forceinline__ float fast_exp(float x) { return __builtin_amdgcn_exp2f(x * LOG2E); }
;     __device__ __forceinline__ void operator()(const f32x4 (&acc)[2][2][4][2], const pg8::Unit& u, int wr, int wc, int fr, int fq) const {
;     ...
;                     for (int bj = 0; bj < 2; ++bj) {
;                         f32x4 r2[2];
; #pragma unroll
;                         for (int n = 0; n < 2; ++n) {
;                             const f32x4 z = acc[ai][bj][m][n] * rs + bg[bj][n];
; #pragma unroll
;                             for (int j = 0; j < 4; ++j) { const float az = fabsf(z[j]); r2[n][j] = (fminf(z[j], 0.f) - __logf(1.0f + fast_exp(-az))) * (1.0f / 16.0f); }
;                         }
;                         pk[bj] = pack8(r2[0], r2[1]);
;                     }
;                     v4u a, b; tt.bf(pk[0], pk[1], a, b);
;                     bf16* d = (bf16*)(ws + WS_LOGA) + (size_t)rowa * 256 + 64 * wc + 8 * tt.p; *(v4u*)d = a; *(v4u*)(d + 8 * 256) = b;
	v_min_f32_e32 v152, 0, v153
	v_mul_f32_e64 v153, |v153|, s88
	v_exp_f32_e32 v153, v153
	v_pk_mul_f32 v[148:149], v[148:149], s[28:29] op_sel_hi:[1,0]
	v_add_f32_e32 v153, 1.0, v153
	v_cmp_gt_f32_e32 vcc, s89, v153
	v_cvt_pk_bf16_f32 v147, v148, v149
	s_nop 0
	v_cndmask_b32_e64 v154, 0, 32, vcc
	v_ldexp_f32 v153, v153, v154
	v_log_f32_e32 v153, v153
	s_nop 0
	v_mul_f32_e32 v154, 0x3f317217, v153
	v_fma_f32 v154, v153, s90, -v154
	v_fmac_f32_e32 v154, 0x3377d1cf, v153
	v_fmac_f32_e32 v154, 0x3f317217, v153
	v_cmp_lt_f32_e64 s[6:7], |v153|, s91
	s_nop 1
	v_cndmask_b32_e64 v153, v153, v154, s[6:7]
	v_cndmask_b32_e32 v154, 0, v222, vcc
	v_sub_f32_e32 v154, v153, v154
	v_min_f32_e32 v153, 0, v155
	v_mul_f32_e64 v155, |v155|, s88
	v_exp_f32_e32 v155, v155
	s_nop 0
	v_add_f32_e32 v155, 1.0, v155
	v_cmp_gt_f32_e32 vcc, s89, v155
	s_nop 1
	v_cndmask_b32_e64 v156, 0, 32, vcc
	v_ldexp_f32 v155, v155, v156
	v_log_f32_e32 v155, v155
	s_nop 0
	v_mul_f32_e32 v156, 0x3f317217, v155
	v_fma_f32 v156, v155, s90, -v156
	v_fmac_f32_e32 v156, 0x3377d1cf, v155
	v_fmac_f32_e32 v156, 0x3f317217, v155
	v_cmp_lt_f32_e64 s[6:7], |v155|, s91
	s_nop 1
	v_cndmask_b32_e64 v155, v155, v156, s[6:7]
	v_cndmask_b32_e32 v156, 0, v222, vcc
	v_sub_f32_e32 v155, v155, v156
	v_pk_add_f32 v[152:153], v[152:153], v[154:155] neg_lo:[0,1] neg_hi:[0,1]
	v_fma_f32 v155, v124, v162, v140
	v_min_f32_e32 v154, 0, v155
	v_mul_f32_e64 v155, |v155|, s88
	v_exp_f32_e32 v155, v155
	v_pk_mul_f32 v[152:153], v[152:153], s[28:29] op_sel_hi:[1,0]
	v_add_f32_e32 v155, 1.0, v155
	v_cmp_gt_f32_e32 vcc, s89, v155
	v_cvt_pk_bf16_f32 v148, v152, v153
	v_fma_f32 v153, v118, v162, v134
	v_cndmask_b32_e64 v156, 0, 32, vcc
	v_ldexp_f32 v155, v155, v156
	v_log_f32_e32 v155, v155
	v_min_f32_e32 v152, 0, v153
	v_mul_f32_e64 v153, |v153|, s88
	v_exp_f32_e32 v153, v153
	v_mul_f32_e32 v156, 0x3f317217, v155
	v_fma_f32 v156, v155, s90, -v156
	v_fmac_f32_e32 v156, 0x3377d1cf, v155
	v_fmac_f32_e32 v156, 0x3f317217, v155
	v_cmp_lt_f32_e64 s[6:7], |v155|, s91
	v_add_f32_e32 v153, 1.0, v153
	s_nop 0
	v_cndmask_b32_e64 v155, v155, v156, s[6:7]
	v_cndmask_b32_e32 v156, 0, v222, vcc
	v_sub_f32_e32 v156, v155, v156
	v_min_f32_e32 v155, 0, v157
	v_mul_f32_e64 v157, |v157|, s88
	v_exp_f32_e32 v157, v157
	s_nop 0
	v_add_f32_e32 v157, 1.0, v157
	v_cmp_gt_f32_e32 vcc, s89, v157
	s_nop 1
	v_cndmask_b32_e64 v160, 0, 32, vcc
	v_ldexp_f32 v157, v157, v160
	v_log_f32_e32 v157, v157
	s_nop 0
	v_mul_f32_e32 v160, 0x3f317217, v157
	v_fma_f32 v160, v157, s90, -v160
	v_fmac_f32_e32 v160, 0x3377d1cf, v157
	v_fmac_f32_e32 v160, 0x3f317217, v157
	v_cmp_lt_f32_e64 s[6:7], |v157|, s91
	s_nop 1
	v_cndmask_b32_e64 v157, v157, v160, s[6:7]
	v_cndmask_b32_e32 v160, 0, v222, vcc
	v_sub_f32_e32 v157, v157, v160
	v_pk_add_f32 v[154:155], v[154:155], v[156:157] neg_lo:[0,1] neg_hi:[0,1]
	v_cmp_gt_f32_e32 vcc, s89, v153
	v_pk_mul_f32 v[154:155], v[154:155], s[28:29] op_sel_hi:[1,0]
	v_fma_f32 v157, v121, v162, v137
	v_cvt_pk_bf16_f32 v149, v154, v155
	v_cndmask_b32_e64 v154, 0, 32, vcc
	v_ldexp_f32 v153, v153, v154
	v_log_f32_e32 v153, v153
	v_fma_f32 v155, v119, v162, v135
	v_mul_f32_e32 v154, 0x3f317217, v153
	v_fma_f32 v154, v153, s90, -v154
	v_fmac_f32_e32 v154, 0x3377d1cf, v153
	v_fmac_f32_e32 v154, 0x3f317217, v153
	v_cmp_lt_f32_e64 s[6:7], |v153|, s91
	s_nop 1
	v_cndmask_b32_e64 v153, v153, v154, s[6:7]
	v_cndmask_b32_e32 v154, 0, v222, vcc
	v_sub_f32_e32 v154, v153, v154
	v_min_f32_e32 v153, 0, v155
	v_mul_f32_e64 v155, |v155|, s88
	v_exp_f32_e32 v155, v155
	s_nop 0
	v_add_f32_e32 v155, 1.0, v155
	v_cmp_gt_f32_e32 vcc, s89, v155
	s_nop 1
	v_cndmask_b32_e64 v156, 0, 32, vcc
	v_ldexp_f32 v155, v155, v156
	v_log_f32_e32 v155, v155
	s_nop 0
	v_mul_f32_e32 v156, 0x3f317217, v155
	v_fma_f32 v156, v155, s90, -v156
	v_fmac_f32_e32 v156, 0x3377d1cf, v155
	v_fmac_f32_e32 v156, 0x3f317217, v155
	v_cmp_lt_f32_e64 s[6:7], |v155|, s91
	s_nop 1
	v_cndmask_b32_e64 v155, v155, v156, s[6:7]
	v_cndmask_b32_e32 v156, 0, v222, vcc
	v_sub_f32_e32 v155, v155, v156
	v_pk_add_f32 v[152:153], v[152:153], v[154:155] neg_lo:[0,1] neg_hi:[0,1]
	v_fma_f32 v155, v120, v162, v136
	v_min_f32_e32 v154, 0, v155
	v_mul_f32_e64 v155, |v155|, s88
	v_exp_f32_e32 v155, v155
	v_pk_mul_f32 v[152:153], v[152:153], s[28:29] op_sel_hi:[1,0]
	v_add_f32_e32 v155, 1.0, v155
	v_cmp_gt_f32_e32 vcc, s89, v155
	v_cvt_pk_bf16_f32 v152, v152, v153
	s_nop 0
	v_cndmask_b32_e64 v156, 0, 32, vcc
	v_ldexp_f32 v155, v155, v156
	v_log_f32_e32 v155, v155
	s_nop 0
	v_mul_f32_e32 v156, 0x3f317217, v155
	v_fma_f32 v156, v155, s90, -v156
	v_fmac_f32_e32 v156, 0x3377d1cf, v155
	v_fmac_f32_e32 v156, 0x3f317217, v155
	v_cmp_lt_f32_e64 s[6:7], |v155|, s91
	s_nop 1
	v_cndmask_b32_e64 v155, v155, v156, s[6:7]
	v_cndmask_b32_e32 v156, 0, v222, vcc
	v_sub_f32_e32 v156, v155, v156
	v_min_f32_e32 v155, 0, v157
	v_mul_f32_e64 v157, |v157|, s88
	v_exp_f32_e32 v157, v157
	s_nop 0
	v_add_f32_e32 v157, 1.0, v157
	v_cmp_gt_f32_e32 vcc, s89, v157
	s_nop 1
	v_cndmask_b32_e64 v160, 0, 32, vcc
	v_ldexp_f32 v157, v157, v160
	v_log_f32_e32 v157, v157
	s_nop 0
	v_mul_f32_e32 v160, 0x3f317217, v157
	v_fma_f32 v160, v157, s90, -v160
	v_fmac_f32_e32 v160, 0x3377d1cf, v157
	v_fmac_f32_e32 v160, 0x3f317217, v157
	v_cmp_lt_f32_e64 s[6:7], |v157|, s91
	s_nop 1
	v_cndmask_b32_e64 v157, v157, v160, s[6:7]
	v_cndmask_b32_e32 v160, 0, v222, vcc
	v_sub_f32_e32 v157, v157, v160
	v_pk_add_f32 v[154:155], v[154:155], v[156:157] neg_lo:[0,1] neg_hi:[0,1]
	v_fma_f32 v157, v114, v162, v130
	v_min_f32_e32 v156, 0, v157
	v_mul_f32_e64 v157, |v157|, s88
	v_exp_f32_e32 v157, v157
	v_pk_mul_f32 v[154:155], v[154:155], s[28:29] op_sel_hi:[1,0]
; __device__ __forceinline__ v4u pack8(const f32x4 a, const f32x4 b) { v4u w; w.x = pk2(a[0], a[1]); w.y = pk2(a[2], a[3]); w.z = pk2(b[0], b[1]); w.w = pk2(b[2], b[3]); return w; }
; __device__ __forceinline__ float fast_exp(float x) { return __builtin_amdgcn_exp2f(x * LOG2E); }
;     __device__ __forceinline__ void operator()(const f32x4 (&acc)[2][2][4][2], const pg8::Unit& u, int wr, int wc, int fr, int fq) const {
;     ...
;                     for (int bj = 0; bj < 2; ++bj) {
;                         f32x4 r2[2];
; #pragma unroll
;                         for (int n = 0; n < 2; ++n) {
;                             const f32x4 z = acc[ai][bj][m][n] * rs + bg[bj][n];
; #pragma unroll
;                             for (int j = 0; j < 4; ++j) { const float az = fabsf(z[j]); r2[n][j] = (fminf(z[j], 0.f) - __logf(1.0f + fast_exp(-az))) * (1.0f / 16.0f); }
;                         }
;                         pk[bj] = pack8(r2[0], r2[1]);
;                     }
;                     v4u a, b; tt.bf(pk[0], pk[1], a, b);
;                     bf16* d = (bf16*)(ws + WS_LOGA) + (size_t)rowa * 256 + 64 * wc + 8 * tt.p; *(v4u*)d = a; *(v4u*)(d + 8 * 256) = b;
	v_add_f32_e32 v157, 1.0, v157
	v_cmp_gt_f32_e32 vcc, s89, v157
	v_cvt_pk_bf16_f32 v153, v154, v155
	s_nop 0
	v_cndmask_b32_e64 v160, 0, 32, vcc
	v_ldexp_f32 v157, v157, v160
	v_log_f32_e32 v157, v157
	s_nop 0
	v_mul_f32_e32 v160, 0x3f317217, v157
	v_fma_f32 v160, v157, s90, -v160
	v_fmac_f32_e32 v160, 0x3377d1cf, v157
	v_fmac_f32_e32 v160, 0x3f317217, v157
	v_cmp_lt_f32_e64 s[6:7], |v157|, s91
	s_nop 1
	v_cndmask_b32_e64 v157, v157, v160, s[6:7]
	v_cndmask_b32_e32 v160, 0, v222, vcc
	v_sub_f32_e32 v160, v157, v160
	v_min_f32_e32 v157, 0, v161
	v_mul_f32_e64 v161, |v161|, s88
	v_exp_f32_e32 v161, v161
	s_nop 0
	v_add_f32_e32 v161, 1.0, v161
	v_cmp_gt_f32_e32 vcc, s89, v161
	s_nop 1
	v_cndmask_b32_e64 v163, 0, 32, vcc
	v_ldexp_f32 v161, v161, v163
	v_log_f32_e32 v161, v161
	s_nop 0
	v_mul_f32_e32 v163, 0x3f317217, v161
	v_fma_f32 v163, v161, s90, -v163
	v_fmac_f32_e32 v163, 0x3377d1cf, v161
	v_fmac_f32_e32 v163, 0x3f317217, v161
	v_cmp_lt_f32_e64 s[6:7], |v161|, s91
	s_nop 1
	v_cndmask_b32_e64 v161, v161, v163, s[6:7]
	v_cndmask_b32_e32 v163, 0, v222, vcc
	v_sub_f32_e32 v161, v161, v163
	v_pk_add_f32 v[156:157], v[156:157], v[160:161] neg_lo:[0,1] neg_hi:[0,1]
	v_fma_f32 v161, v116, v162, v132
	v_min_f32_e32 v160, 0, v161
	v_mul_f32_e64 v161, |v161|, s88
	v_exp_f32_e32 v161, v161
	v_pk_mul_f32 v[156:157], v[156:157], s[28:29] op_sel_hi:[1,0]
	v_add_f32_e32 v161, 1.0, v161
	v_cmp_gt_f32_e32 vcc, s89, v161
	v_cvt_pk_bf16_f32 v154, v156, v157
	v_lshlrev_b64 v[156:157], 9, v[150:151]
	v_cndmask_b32_e64 v163, 0, 32, vcc
	v_ldexp_f32 v161, v161, v163
	v_log_f32_e32 v161, v161
	v_lshl_add_u64 v[156:157], s[24:25], 0, v[156:157]
	v_lshl_add_u64 v[156:157], v[156:157], 0, v[184:185]
	v_mul_f32_e32 v163, 0x3f317217, v161
	v_fma_f32 v163, v161, s90, -v163
	v_fmac_f32_e32 v163, 0x3377d1cf, v161
	v_fmac_f32_e32 v163, 0x3f317217, v161
	v_cmp_lt_f32_e64 s[6:7], |v161|, s91
	s_nop 1
	v_cndmask_b32_e64 v161, v161, v163, s[6:7]
	v_cndmask_b32_e32 v163, 0, v222, vcc
	v_sub_f32_e32 v164, v161, v163
	v_fma_f32 v163, v117, v162, v133
	v_min_f32_e32 v161, 0, v163
	v_mul_f32_e64 v163, |v163|, s88
	v_exp_f32_e32 v163, v163
	s_nop 0
	v_add_f32_e32 v163, 1.0, v163
	v_cmp_gt_f32_e32 vcc, s89, v163
	s_nop 1
	v_cndmask_b32_e64 v165, 0, 32, vcc
	v_ldexp_f32 v163, v163, v165
	v_log_f32_e32 v163, v163
	s_nop 0
	v_mul_f32_e32 v165, 0x3f317217, v163
	v_fma_f32 v165, v163, s90, -v165
	v_fmac_f32_e32 v165, 0x3377d1cf, v163
	v_fmac_f32_e32 v165, 0x3f317217, v163
	v_cmp_lt_f32_e64 s[6:7], |v163|, s91
	s_nop 1
	v_cndmask_b32_e64 v163, v163, v165, s[6:7]
	v_cndmask_b32_e32 v165, 0, v222, vcc
	v_sub_f32_e32 v165, v163, v165
	v_pk_add_f32 v[160:161], v[160:161], v[164:165] neg_lo:[0,1] neg_hi:[0,1]
	v_add_u32_e32 v163, s77, v230
	v_pk_mul_f32 v[160:161], v[160:161], s[28:29] op_sel_hi:[1,0]
	v_fma_f32 v165, v99, v210, v131
	v_cvt_pk_bf16_f32 v155, v160, v161
	v_add_u32_e32 v160, s77, v229
	v_add_u32_e32 v161, s77, v228
	ds_write_b128 v160, v[146:149]
	ds_write_b128 v161, v[152:155]
	ds_read_b128 v[146:149], v163
	ds_read_b128 v[152:155], v163 offset:1024
	s_waitcnt lgkmcnt(1)
	global_store_dwordx4 v[156:157], v[146:149], off nt
	s_nop 1
	v_add_co_u32_e32 v146, vcc, s92, v156
	v_fma_f32 v149, v111, v210, v143
	s_nop 0
	v_addc_co_u32_e32 v147, vcc, 0, v157, vcc
	s_waitcnt lgkmcnt(0)
	global_store_dwordx4 v[146:147], v[152:155], off nt
	v_fma_f32 v147, v110, v210, v142
	v_min_f32_e32 v146, 0, v147
	v_mul_f32_e64 v147, |v147|, s88
	v_exp_f32_e32 v147, v147
	v_fma_f32 v153, v113, v210, v145
	v_fma_f32 v155, v107, v210, v139
	v_fma_f32 v157, v109, v210, v141
	v_add_f32_e32 v147, 1.0, v147
	v_cmp_gt_f32_e32 vcc, s89, v147
	s_nop 1
	v_cndmask_b32_e64 v148, 0, 32, vcc
	v_ldexp_f32 v147, v147, v148
	v_log_f32_e32 v147, v147
	s_nop 0
	v_mul_f32_e32 v148, 0x3f317217, v147
	v_fma_f32 v148, v147, s90, -v148
	v_fmac_f32_e32 v148, 0x3377d1cf, v147
	v_fmac_f32_e32 v148, 0x3f317217, v147
	v_cmp_lt_f32_e64 s[6:7], |v147|, s91
	s_nop 1
	v_cndmask_b32_e64 v147, v147, v148, s[6:7]
	v_cndmask_b32_e32 v148, 0, v222, vcc
	v_sub_f32_e32 v148, v147, v148
	v_min_f32_e32 v147, 0, v149
	v_mul_f32_e64 v149, |v149|, s88
	v_exp_f32_e32 v149, v149
	s_nop 0
	v_add_f32_e32 v149, 1.0, v149
	v_cmp_gt_f32_e32 vcc, s89, v149
	s_nop 1
	v_cndmask_b32_e64 v152, 0, 32, vcc
	v_ldexp_f32 v149, v149, v152
	v_log_f32_e32 v149, v149
	s_nop 0
	v_mul_f32_e32 v152, 0x3f317217, v149
	v_fma_f32 v152, v149, s90, -v152
	v_fmac_f32_e32 v152, 0x3377d1cf, v149
	v_fmac_f32_e32 v152, 0x3f317217, v149
	v_cmp_lt_f32_e64 s[6:7], |v149|, s91
	s_nop 1
	v_cndmask_b32_e64 v149, v149, v152, s[6:7]
	v_cndmask_b32_e32 v152, 0, v222, vcc
	v_sub_f32_e32 v149, v149, v152
	v_pk_add_f32 v[146:147], v[146:147], v[148:149] neg_lo:[0,1] neg_hi:[0,1]
	v_fma_f32 v149, v112, v210, v144
	v_min_f32_e32 v148, 0, v149
	v_mul_f32_e64 v149, |v149|, s88
	v_exp_f32_e32 v149, v149
	v_pk_mul_f32 v[146:147], v[146:147], s[28:29] op_sel_hi:[1,0]
	v_add_f32_e32 v149, 1.0, v149
	v_cmp_gt_f32_e32 vcc, s89, v149
	v_cvt_pk_bf16_f32 v146, v146, v147
	s_nop 0
	v_cndmask_b32_e64 v152, 0, 32, vcc
	v_ldexp_f32 v149, v149, v152
	v_log_f32_e32 v149, v149
	s_nop 0
	v_mul_f32_e32 v152, 0x3f317217, v149
	v_fma_f32 v152, v149, s90, -v152
	v_fmac_f32_e32 v152, 0x3377d1cf, v149
	v_fmac_f32_e32 v152, 0x3f317217, v149
	v_cmp_lt_f32_e64 s[6:7], |v149|, s91
	s_nop 1
	v_cndmask_b32_e64 v149, v149, v152, s[6:7]
	v_cndmask_b32_e32 v152, 0, v222, vcc
	v_sub_f32_e32 v152, v149, v152
	v_min_f32_e32 v149, 0, v153
	v_mul_f32_e64 v153, |v153|, s88
	v_exp_f32_e32 v153, v153
	s_nop 0
	v_add_f32_e32 v153, 1.0, v153
	v_cmp_gt_f32_e32 vcc, s89, v153
	s_nop 1
	v_cndmask_b32_e64 v154, 0, 32, vcc
; __device__ __forceinline__ v4u pack8(const f32x4 a, const f32x4 b) { v4u w; w.x = pk2(a[0], a[1]); w.y = pk2(a[2], a[3]); w.z = pk2(b[0], b[1]); w.w = pk2(b[2], b[3]); return w; }
; __device__ __forceinline__ float fast_exp(float x) { return __builtin_amdgcn_exp2f(x * LOG2E); }
;     __device__ __forceinline__ void operator()(const f32x4 (&acc)[2][2][4][2], const pg8::Unit& u, int wr, int wc, int fr, int fq) const {
;     ...
;                     for (int bj = 0; bj < 2; ++bj) {
;                         f32x4 r2[2];
; #pragma unroll
;                         for (int n = 0; n < 2; ++n) {
;                             const f32x4 z = acc[ai][bj][m][n] * rs + bg[bj][n];
; #pragma unroll
;                             for (int j = 0; j < 4; ++j) { const float az = fabsf(z[j]); r2[n][j] = (fminf(z[j], 0.f) - __logf(1.0f + fast_exp(-az))) * (1.0f / 16.0f); }
;                         }
;                         pk[bj] = pack8(r2[0], r2[1]);
;                     }
;                     v4u a, b; tt.bf(pk[0], pk[1], a, b);
;                     bf16* d = (bf16*)(ws + WS_LOGA) + (size_t)rowa * 256 + 64 * wc + 8 * tt.p; *(v4u*)d = a; *(v4u*)(d + 8 * 256) = b;
	v_ldexp_f32 v153, v153, v154
	v_log_f32_e32 v153, v153
	s_nop 0
	v_mul_f32_e32 v154, 0x3f317217, v153
	v_fma_f32 v154, v153, s90, -v154
	v_fmac_f32_e32 v154, 0x3377d1cf, v153
	v_fmac_f32_e32 v154, 0x3f317217, v153
	v_cmp_lt_f32_e64 s[6:7], |v153|, s91
	s_nop 1
	v_cndmask_b32_e64 v153, v153, v154, s[6:7]
	v_cndmask_b32_e32 v154, 0, v222, vcc
	v_sub_f32_e32 v153, v153, v154
	v_pk_add_f32 v[148:149], v[148:149], v[152:153] neg_lo:[0,1] neg_hi:[0,1]
	v_fma_f32 v153, v106, v210, v138
	v_min_f32_e32 v152, 0, v153
	v_mul_f32_e64 v153, |v153|, s88
	v_exp_f32_e32 v153, v153
	v_pk_mul_f32 v[148:149], v[148:149], s[28:29] op_sel_hi:[1,0]
	v_add_f32_e32 v153, 1.0, v153
	v_cmp_gt_f32_e32 vcc, s89, v153
	v_cvt_pk_bf16_f32 v147, v148, v149
	s_nop 0
	v_cndmask_b32_e64 v154, 0, 32, vcc
	v_ldexp_f32 v153, v153, v154
	v_log_f32_e32 v153, v153
	s_nop 0
	v_mul_f32_e32 v154, 0x3f317217, v153
	v_fma_f32 v154, v153, s90, -v154
	v_fmac_f32_e32 v154, 0x3377d1cf, v153
	v_fmac_f32_e32 v154, 0x3f317217, v153
	v_cmp_lt_f32_e64 s[6:7], |v153|, s91
	s_nop 1
	v_cndmask_b32_e64 v153, v153, v154, s[6:7]
	v_cndmask_b32_e32 v154, 0, v222, vcc
	v_sub_f32_e32 v154, v153, v154
	v_min_f32_e32 v153, 0, v155
	v_mul_f32_e64 v155, |v155|, s88
	v_exp_f32_e32 v155, v155
	s_nop 0
	v_add_f32_e32 v155, 1.0, v155
	v_cmp_gt_f32_e32 vcc, s89, v155
	s_nop 1
	v_cndmask_b32_e64 v156, 0, 32, vcc
	v_ldexp_f32 v155, v155, v156
	v_log_f32_e32 v155, v155
	s_nop 0
	v_mul_f32_e32 v156, 0x3f317217, v155
	v_fma_f32 v156, v155, s90, -v156
	v_fmac_f32_e32 v156, 0x3377d1cf, v155
	v_fmac_f32_e32 v156, 0x3f317217, v155
	v_cmp_lt_f32_e64 s[6:7], |v155|, s91
	s_nop 1
	v_cndmask_b32_e64 v155, v155, v156, s[6:7]
	v_cndmask_b32_e32 v156, 0, v222, vcc
	v_sub_f32_e32 v155, v155, v156
	v_pk_add_f32 v[152:153], v[152:153], v[154:155] neg_lo:[0,1] neg_hi:[0,1]
	v_fma_f32 v155, v108, v210, v140
	v_min_f32_e32 v154, 0, v155
	v_mul_f32_e64 v155, |v155|, s88
	v_exp_f32_e32 v155, v155
	v_pk_mul_f32 v[152:153], v[152:153], s[28:29] op_sel_hi:[1,0]
	v_add_f32_e32 v155, 1.0, v155
	v_cmp_gt_f32_e32 vcc, s89, v155
	v_cvt_pk_bf16_f32 v148, v152, v153
	v_fma_f32 v153, v102, v210, v134
	v_cndmask_b32_e64 v156, 0, 32, vcc
	v_ldexp_f32 v155, v155, v156
	v_log_f32_e32 v155, v155
	v_min_f32_e32 v152, 0, v153
	v_mul_f32_e64 v153, |v153|, s88
	v_exp_f32_e32 v153, v153
	v_mul_f32_e32 v156, 0x3f317217, v155
	v_fma_f32 v156, v155, s90, -v156
	v_fmac_f32_e32 v156, 0x3377d1cf, v155
	v_fmac_f32_e32 v156, 0x3f317217, v155
	v_cmp_lt_f32_e64 s[6:7], |v155|, s91
	v_add_f32_e32 v153, 1.0, v153
	s_nop 0
	v_cndmask_b32_e64 v155, v155, v156, s[6:7]
	v_cndmask_b32_e32 v156, 0, v222, vcc
	v_sub_f32_e32 v156, v155, v156
	v_min_f32_e32 v155, 0, v157
	v_mul_f32_e64 v157, |v157|, s88
	v_exp_f32_e32 v157, v157
	s_nop 0
	v_add_f32_e32 v157, 1.0, v157
	v_cmp_gt_f32_e32 vcc, s89, v157
	s_nop 1
	v_cndmask_b32_e64 v164, 0, 32, vcc
	v_ldexp_f32 v157, v157, v164
	v_log_f32_e32 v157, v157
	s_nop 0
	v_mul_f32_e32 v164, 0x3f317217, v157
	v_fma_f32 v164, v157, s90, -v164
	v_fmac_f32_e32 v164, 0x3377d1cf, v157
	v_fmac_f32_e32 v164, 0x3f317217, v157
	v_cmp_lt_f32_e64 s[6:7], |v157|, s91
	s_nop 1
	v_cndmask_b32_e64 v157, v157, v164, s[6:7]
	v_cndmask_b32_e32 v164, 0, v222, vcc
	v_sub_f32_e32 v157, v157, v164
	v_pk_add_f32 v[154:155], v[154:155], v[156:157] neg_lo:[0,1] neg_hi:[0,1]
	v_cmp_gt_f32_e32 vcc, s89, v153
	v_pk_mul_f32 v[154:155], v[154:155], s[28:29] op_sel_hi:[1,0]
	v_fma_f32 v157, v105, v210, v137
	v_cvt_pk_bf16_f32 v149, v154, v155
	v_cndmask_b32_e64 v154, 0, 32, vcc
	v_ldexp_f32 v153, v153, v154
	v_log_f32_e32 v153, v153
	v_fma_f32 v155, v103, v210, v135
	v_mul_f32_e32 v154, 0x3f317217, v153
	v_fma_f32 v154, v153, s90, -v154
	v_fmac_f32_e32 v154, 0x3377d1cf, v153
	v_fmac_f32_e32 v154, 0x3f317217, v153
	v_cmp_lt_f32_e64 s[6:7], |v153|, s91
	s_nop 1
	v_cndmask_b32_e64 v153, v153, v154, s[6:7]
	v_cndmask_b32_e32 v154, 0, v222, vcc
	v_sub_f32_e32 v154, v153, v154
	v_min_f32_e32 v153, 0, v155
	v_mul_f32_e64 v155, |v155|, s88
	v_exp_f32_e32 v155, v155
	s_nop 0
	v_add_f32_e32 v155, 1.0, v155
	v_cmp_gt_f32_e32 vcc, s89, v155
	s_nop 1
	v_cndmask_b32_e64 v156, 0, 32, vcc
	v_ldexp_f32 v155, v155, v156
	v_log_f32_e32 v155, v155
	s_nop 0
	v_mul_f32_e32 v156, 0x3f317217, v155
	v_fma_f32 v156, v155, s90, -v156
	v_fmac_f32_e32 v156, 0x3377d1cf, v155
	v_fmac_f32_e32 v156, 0x3f317217, v155
	v_cmp_lt_f32_e64 s[6:7], |v155|, s91
	s_nop 1
	v_cndmask_b32_e64 v155, v155, v156, s[6:7]
	v_cndmask_b32_e32 v156, 0, v222, vcc
	v_sub_f32_e32 v155, v155, v156
	v_pk_add_f32 v[152:153], v[152:153], v[154:155] neg_lo:[0,1] neg_hi:[0,1]
	v_fma_f32 v155, v104, v210, v136
	v_min_f32_e32 v154, 0, v155
	v_mul_f32_e64 v155, |v155|, s88
	v_exp_f32_e32 v155, v155
	v_pk_mul_f32 v[152:153], v[152:153], s[28:29] op_sel_hi:[1,0]
	v_add_f32_e32 v155, 1.0, v155
	v_cmp_gt_f32_e32 vcc, s89, v155
	v_cvt_pk_bf16_f32 v152, v152, v153
	s_nop 0
	v_cndmask_b32_e64 v156, 0, 32, vcc
	v_ldexp_f32 v155, v155, v156
	v_log_f32_e32 v155, v155
	s_nop 0
	v_mul_f32_e32 v156, 0x3f317217, v155
	v_fma_f32 v156, v155, s90, -v156
	v_fmac_f32_e32 v156, 0x3377d1cf, v155
	v_fmac_f32_e32 v156, 0x3f317217, v155
	v_cmp_lt_f32_e64 s[6:7], |v155|, s91
	s_nop 1
	v_cndmask_b32_e64 v155, v155, v156, s[6:7]
	v_cndmask_b32_e32 v156, 0, v222, vcc
	v_sub_f32_e32 v156, v155, v156
	v_min_f32_e32 v155, 0, v157
	v_mul_f32_e64 v157, |v157|, s88
	v_exp_f32_e32 v157, v157
	s_nop 0
	v_add_f32_e32 v157, 1.0, v157
	v_cmp_gt_f32_e32 vcc, s89, v157
	s_nop 1
	v_cndmask_b32_e64 v164, 0, 32, vcc
	v_ldexp_f32 v157, v157, v164
	v_log_f32_e32 v157, v157
	s_nop 0
	v_mul_f32_e32 v164, 0x3f317217, v157
	v_fma_f32 v164, v157, s90, -v164
; __device__ __forceinline__ v4u pack8(const f32x4 a, const f32x4 b) { v4u w; w.x = pk2(a[0], a[1]); w.y = pk2(a[2], a[3]); w.z = pk2(b[0], b[1]); w.w = pk2(b[2], b[3]); return w; }
; __device__ __forceinline__ float fast_exp(float x) { return __builtin_amdgcn_exp2f(x * LOG2E); }
;     __device__ __forceinline__ void operator()(const f32x4 (&acc)[2][2][4][2], const pg8::Unit& u, int wr, int wc, int fr, int fq) const {
;     ...
;                     for (int bj = 0; bj < 2; ++bj) {
;                         f32x4 r2[2];
; #pragma unroll
;                         for (int n = 0; n < 2; ++n) {
;                             const f32x4 z = acc[ai][bj][m][n] * rs + bg[bj][n];
; #pragma unroll
;                             for (int j = 0; j < 4; ++j) { const float az = fabsf(z[j]); r2[n][j] = (fminf(z[j], 0.f) - __logf(1.0f + fast_exp(-az))) * (1.0f / 16.0f); }
;                         }
;                         pk[bj] = pack8(r2[0], r2[1]);
;                     }
;                     v4u a, b; tt.bf(pk[0], pk[1], a, b);
;                     bf16* d = (bf16*)(ws + WS_LOGA) + (size_t)rowa * 256 + 64 * wc + 8 * tt.p; *(v4u*)d = a; *(v4u*)(d + 8 * 256) = b;
	v_fmac_f32_e32 v164, 0x3377d1cf, v157
	v_fmac_f32_e32 v164, 0x3f317217, v157
	v_cmp_lt_f32_e64 s[6:7], |v157|, s91
	s_nop 1
	v_cndmask_b32_e64 v157, v157, v164, s[6:7]
	v_cndmask_b32_e32 v164, 0, v222, vcc
	v_sub_f32_e32 v157, v157, v164
	v_pk_add_f32 v[154:155], v[154:155], v[156:157] neg_lo:[0,1] neg_hi:[0,1]
	v_fma_f32 v157, v98, v210, v130
	v_min_f32_e32 v156, 0, v157
	v_mul_f32_e64 v157, |v157|, s88
	v_exp_f32_e32 v157, v157
	v_pk_mul_f32 v[154:155], v[154:155], s[28:29] op_sel_hi:[1,0]
	v_add_f32_e32 v157, 1.0, v157
	v_cmp_gt_f32_e32 vcc, s89, v157
	v_cvt_pk_bf16_f32 v153, v154, v155
	s_nop 0
	v_cndmask_b32_e64 v164, 0, 32, vcc
	v_ldexp_f32 v157, v157, v164
	v_log_f32_e32 v157, v157
	s_nop 0
	v_mul_f32_e32 v164, 0x3f317217, v157
	v_fma_f32 v164, v157, s90, -v164
	v_fmac_f32_e32 v164, 0x3377d1cf, v157
	v_fmac_f32_e32 v164, 0x3f317217, v157
	v_cmp_lt_f32_e64 s[6:7], |v157|, s91
	s_nop 1
	v_cndmask_b32_e64 v157, v157, v164, s[6:7]
	v_cndmask_b32_e32 v164, 0, v222, vcc
	v_sub_f32_e32 v164, v157, v164
	v_min_f32_e32 v157, 0, v165
	v_mul_f32_e64 v165, |v165|, s88
	v_exp_f32_e32 v165, v165
	s_nop 0
	v_add_f32_e32 v165, 1.0, v165
	v_cmp_gt_f32_e32 vcc, s89, v165
	s_nop 1
	v_cndmask_b32_e64 v166, 0, 32, vcc
	v_ldexp_f32 v165, v165, v166
	v_log_f32_e32 v165, v165
	s_nop 0
	v_mul_f32_e32 v166, 0x3f317217, v165
	v_fma_f32 v166, v165, s90, -v166
	v_fmac_f32_e32 v166, 0x3377d1cf, v165
	v_fmac_f32_e32 v166, 0x3f317217, v165
	v_cmp_lt_f32_e64 s[6:7], |v165|, s91
	s_nop 1
	v_cndmask_b32_e64 v165, v165, v166, s[6:7]
	v_cndmask_b32_e32 v166, 0, v222, vcc
	v_sub_f32_e32 v165, v165, v166
	v_pk_add_f32 v[156:157], v[156:157], v[164:165] neg_lo:[0,1] neg_hi:[0,1]
	v_fma_f32 v165, v100, v210, v132
	v_min_f32_e32 v164, 0, v165
	v_mul_f32_e64 v165, |v165|, s88
	v_exp_f32_e32 v165, v165
	v_pk_mul_f32 v[156:157], v[156:157], s[28:29] op_sel_hi:[1,0]
	v_add_f32_e32 v165, 1.0, v165
	v_cmp_gt_f32_e32 vcc, s89, v165
	v_cvt_pk_bf16_f32 v154, v156, v157
	v_add_u32_e32 v156, 16, v150
	v_cndmask_b32_e64 v166, 0, 32, vcc
	v_ldexp_f32 v165, v165, v166
	v_log_f32_e32 v165, v165
	v_ashrrev_i32_e32 v157, 31, v156
	v_lshlrev_b64 v[156:157], 9, v[156:157]
	v_lshl_add_u64 v[156:157], s[24:25], 0, v[156:157]
	v_mul_f32_e32 v166, 0x3f317217, v165
	v_fma_f32 v166, v165, s90, -v166
	v_fmac_f32_e32 v166, 0x3377d1cf, v165
	v_fmac_f32_e32 v166, 0x3f317217, v165
	v_cmp_lt_f32_e64 s[6:7], |v165|, s91
	v_lshl_add_u64 v[156:157], v[156:157], 0, v[184:185]
	s_nop 0
	v_cndmask_b32_e64 v165, v165, v166, s[6:7]
	v_cndmask_b32_e32 v166, 0, v222, vcc
	v_sub_f32_e32 v166, v165, v166
	v_min_f32_e32 v165, 0, v167
	v_mul_f32_e64 v167, |v167|, s88
	v_exp_f32_e32 v167, v167
	s_nop 0
	v_add_f32_e32 v167, 1.0, v167
	v_cmp_gt_f32_e32 vcc, s89, v167
	s_nop 1
	v_cndmask_b32_e64 v168, 0, 32, vcc
	v_ldexp_f32 v167, v167, v168
	v_log_f32_e32 v167, v167
	s_nop 0
	v_mul_f32_e32 v168, 0x3f317217, v167
	v_fma_f32 v168, v167, s90, -v168
	v_fmac_f32_e32 v168, 0x3377d1cf, v167
	v_fmac_f32_e32 v168, 0x3f317217, v167
	v_cmp_lt_f32_e64 s[6:7], |v167|, s91
	s_nop 1
	v_cndmask_b32_e64 v167, v167, v168, s[6:7]
	v_cndmask_b32_e32 v168, 0, v222, vcc
	v_sub_f32_e32 v167, v167, v168
	v_pk_add_f32 v[164:165], v[164:165], v[166:167] neg_lo:[0,1] neg_hi:[0,1]
	v_fma_f32 v167, v85, v208, v133
	v_pk_mul_f32 v[164:165], v[164:165], s[28:29] op_sel_hi:[1,0]
	s_nop 0
	v_cvt_pk_bf16_f32 v155, v164, v165
	ds_write_b128 v160, v[146:149]
	ds_write_b128 v161, v[152:155]
	ds_read_b128 v[146:149], v163
	ds_read_b128 v[152:155], v163 offset:1024
	v_fma_f32 v165, v83, v208, v131
	s_waitcnt lgkmcnt(1)
	global_store_dwordx4 v[156:157], v[146:149], off nt
	s_nop 1
	v_add_co_u32_e32 v146, vcc, s92, v156
	v_fma_f32 v149, v95, v208, v143
	s_nop 0
	v_addc_co_u32_e32 v147, vcc, 0, v157, vcc
	s_waitcnt lgkmcnt(0)
	global_store_dwordx4 v[146:147], v[152:155], off nt
	v_fma_f32 v147, v94, v208, v142
	v_min_f32_e32 v146, 0, v147
	v_mul_f32_e64 v147, |v147|, s88
	v_exp_f32_e32 v147, v147
	v_fma_f32 v153, v97, v208, v145
	v_fma_f32 v155, v91, v208, v139
	v_fma_f32 v157, v93, v208, v141
	v_add_f32_e32 v147, 1.0, v147
	v_cmp_gt_f32_e32 vcc, s89, v147
	s_nop 1
	v_cndmask_b32_e64 v148, 0, 32, vcc
	v_ldexp_f32 v147, v147, v148
	v_log_f32_e32 v147, v147
	s_nop 0
	v_mul_f32_e32 v148, 0x3f317217, v147
	v_fma_f32 v148, v147, s90, -v148
	v_fmac_f32_e32 v148, 0x3377d1cf, v147
	v_fmac_f32_e32 v148, 0x3f317217, v147
	v_cmp_lt_f32_e64 s[6:7], |v147|, s91
	s_nop 1
	v_cndmask_b32_e64 v147, v147, v148, s[6:7]
	v_cndmask_b32_e32 v148, 0, v222, vcc
	v_sub_f32_e32 v148, v147, v148
	v_min_f32_e32 v147, 0, v149
	v_mul_f32_e64 v149, |v149|, s88
	v_exp_f32_e32 v149, v149
	s_nop 0
	v_add_f32_e32 v149, 1.0, v149
	v_cmp_gt_f32_e32 vcc, s89, v149
	s_nop 1
	v_cndmask_b32_e64 v152, 0, 32, vcc
	v_ldexp_f32 v149, v149, v152
	v_log_f32_e32 v149, v149
	s_nop 0
	v_mul_f32_e32 v152, 0x3f317217, v149
	v_fma_f32 v152, v149, s90, -v152
	v_fmac_f32_e32 v152, 0x3377d1cf, v149
	v_fmac_f32_e32 v152, 0x3f317217, v149
	v_cmp_lt_f32_e64 s[6:7], |v149|, s91
	s_nop 1
	v_cndmask_b32_e64 v149, v149, v152, s[6:7]
	v_cndmask_b32_e32 v152, 0, v222, vcc
	v_sub_f32_e32 v149, v149, v152
	v_pk_add_f32 v[146:147], v[146:147], v[148:149] neg_lo:[0,1] neg_hi:[0,1]
	v_fma_f32 v149, v96, v208, v144
	v_min_f32_e32 v148, 0, v149
	v_mul_f32_e64 v149, |v149|, s88
	v_exp_f32_e32 v149, v149
	v_pk_mul_f32 v[146:147], v[146:147], s[28:29] op_sel_hi:[1,0]
	v_add_f32_e32 v149, 1.0, v149
	v_cmp_gt_f32_e32 vcc, s89, v149
	v_cvt_pk_bf16_f32 v146, v146, v147
	s_nop 0
	v_cndmask_b32_e64 v152, 0, 32, vcc
	v_ldexp_f32 v149, v149, v152
	v_log_f32_e32 v149, v149
	s_nop 0
	v_mul_f32_e32 v152, 0x3f317217, v149
	v_fma_f32 v152, v149, s90, -v152
; __device__ __forceinline__ v4u pack8(const f32x4 a, const f32x4 b) { v4u w; w.x = pk2(a[0], a[1]); w.y = pk2(a[2], a[3]); w.z = pk2(b[0], b[1]); w.w = pk2(b[2], b[3]); return w; }
; __device__ __forceinline__ float fast_exp(float x) { return __builtin_amdgcn_exp2f(x * LOG2E); }
;     __device__ __forceinline__ void operator()(const f32x4 (&acc)[2][2][4][2], const pg8::Unit& u, int wr, int wc, int fr, int fq) const {
;     ...
;                     for (int bj = 0; bj < 2; ++bj) {
;                         f32x4 r2[2];
; #pragma unroll
;                         for (int n = 0; n < 2; ++n) {
;                             const f32x4 z = acc[ai][bj][m][n] * rs + bg[bj][n];
; #pragma unroll
;                             for (int j = 0; j < 4; ++j) { const float az = fabsf(z[j]); r2[n][j] = (fminf(z[j], 0.f) - __logf(1.0f + fast_exp(-az))) * (1.0f / 16.0f); }
;                         }
;                         pk[bj] = pack8(r2[0], r2[1]);
;                     }
;                     v4u a, b; tt.bf(pk[0], pk[1], a, b);
;                     bf16* d = (bf16*)(ws + WS_LOGA) + (size_t)rowa * 256 + 64 * wc + 8 * tt.p; *(v4u*)d = a; *(v4u*)(d + 8 * 256) = b;
	v_fmac_f32_e32 v152, 0x3377d1cf, v149
	v_fmac_f32_e32 v152, 0x3f317217, v149
	v_cmp_lt_f32_e64 s[6:7], |v149|, s91
	s_nop 1
	v_cndmask_b32_e64 v149, v149, v152, s[6:7]
	v_cndmask_b32_e32 v152, 0, v222, vcc
	v_sub_f32_e32 v152, v149, v152
	v_min_f32_e32 v149, 0, v153
	v_mul_f32_e64 v153, |v153|, s88
	v_exp_f32_e32 v153, v153
	s_nop 0
	v_add_f32_e32 v153, 1.0, v153
	v_cmp_gt_f32_e32 vcc, s89, v153
	s_nop 1
	v_cndmask_b32_e64 v154, 0, 32, vcc
	v_ldexp_f32 v153, v153, v154
	v_log_f32_e32 v153, v153
	s_nop 0
	v_mul_f32_e32 v154, 0x3f317217, v153
	v_fma_f32 v154, v153, s90, -v154
	v_fmac_f32_e32 v154, 0x3377d1cf, v153
	v_fmac_f32_e32 v154, 0x3f317217, v153
	v_cmp_lt_f32_e64 s[6:7], |v153|, s91
	s_nop 1
	v_cndmask_b32_e64 v153, v153, v154, s[6:7]
	v_cndmask_b32_e32 v154, 0, v222, vcc
	v_sub_f32_e32 v153, v153, v154
	v_pk_add_f32 v[148:149], v[148:149], v[152:153] neg_lo:[0,1] neg_hi:[0,1]
	v_fma_f32 v153, v90, v208, v138
	v_min_f32_e32 v152, 0, v153
	v_mul_f32_e64 v153, |v153|, s88
	v_exp_f32_e32 v153, v153
	v_pk_mul_f32 v[148:149], v[148:149], s[28:29] op_sel_hi:[1,0]
	v_add_f32_e32 v153, 1.0, v153
	v_cmp_gt_f32_e32 vcc, s89, v153
	v_cvt_pk_bf16_f32 v147, v148, v149
	s_nop 0
	v_cndmask_b32_e64 v154, 0, 32, vcc
	v_ldexp_f32 v153, v153, v154
	v_log_f32_e32 v153, v153
	s_nop 0
	v_mul_f32_e32 v154, 0x3f317217, v153
	v_fma_f32 v154, v153, s90, -v154
	v_fmac_f32_e32 v154, 0x3377d1cf, v153
	v_fmac_f32_e32 v154, 0x3f317217, v153
	v_cmp_lt_f32_e64 s[6:7], |v153|, s91
	s_nop 1
	v_cndmask_b32_e64 v153, v153, v154, s[6:7]
	v_cndmask_b32_e32 v154, 0, v222, vcc
	v_sub_f32_e32 v154, v153, v154
	v_min_f32_e32 v153, 0, v155
	v_mul_f32_e64 v155, |v155|, s88
	v_exp_f32_e32 v155, v155
	s_nop 0
	v_add_f32_e32 v155, 1.0, v155
	v_cmp_gt_f32_e32 vcc, s89, v155
	s_nop 1
	v_cndmask_b32_e64 v156, 0, 32, vcc
	v_ldexp_f32 v155, v155, v156
	v_log_f32_e32 v155, v155
	s_nop 0
	v_mul_f32_e32 v156, 0x3f317217, v155
	v_fma_f32 v156, v155, s90, -v156
	v_fmac_f32_e32 v156, 0x3377d1cf, v155
	v_fmac_f32_e32 v156, 0x3f317217, v155
	v_cmp_lt_f32_e64 s[6:7], |v155|, s91
	s_nop 1
	v_cndmask_b32_e64 v155, v155, v156, s[6:7]
	v_cndmask_b32_e32 v156, 0, v222, vcc
	v_sub_f32_e32 v155, v155, v156
	v_pk_add_f32 v[152:153], v[152:153], v[154:155] neg_lo:[0,1] neg_hi:[0,1]
	v_fma_f32 v155, v92, v208, v140
	v_min_f32_e32 v154, 0, v155
	v_mul_f32_e64 v155, |v155|, s88
	v_exp_f32_e32 v155, v155
	v_pk_mul_f32 v[152:153], v[152:153], s[28:29] op_sel_hi:[1,0]
	v_add_f32_e32 v155, 1.0, v155
	v_cmp_gt_f32_e32 vcc, s89, v155
	v_cvt_pk_bf16_f32 v148, v152, v153
	v_fma_f32 v153, v86, v208, v134
	v_cndmask_b32_e64 v156, 0, 32, vcc
	v_ldexp_f32 v155, v155, v156
	v_log_f32_e32 v155, v155
	v_min_f32_e32 v152, 0, v153
	v_mul_f32_e64 v153, |v153|, s88
	v_exp_f32_e32 v153, v153
	v_mul_f32_e32 v156, 0x3f317217, v155
	v_fma_f32 v156, v155, s90, -v156
	v_fmac_f32_e32 v156, 0x3377d1cf, v155
	v_fmac_f32_e32 v156, 0x3f317217, v155
	v_cmp_lt_f32_e64 s[6:7], |v155|, s91
	v_add_f32_e32 v153, 1.0, v153
	s_nop 0
	v_cndmask_b32_e64 v155, v155, v156, s[6:7]
	v_cndmask_b32_e32 v156, 0, v222, vcc
	v_sub_f32_e32 v156, v155, v156
	v_min_f32_e32 v155, 0, v157
	v_mul_f32_e64 v157, |v157|, s88
	v_exp_f32_e32 v157, v157
	s_nop 0
	v_add_f32_e32 v157, 1.0, v157
	v_cmp_gt_f32_e32 vcc, s89, v157
	s_nop 1
	v_cndmask_b32_e64 v164, 0, 32, vcc
	v_ldexp_f32 v157, v157, v164
	v_log_f32_e32 v157, v157
	s_nop 0
	v_mul_f32_e32 v164, 0x3f317217, v157
	v_fma_f32 v164, v157, s90, -v164
	v_fmac_f32_e32 v164, 0x3377d1cf, v157
	v_fmac_f32_e32 v164, 0x3f317217, v157
	v_cmp_lt_f32_e64 s[6:7], |v157|, s91
	s_nop 1
	v_cndmask_b32_e64 v157, v157, v164, s[6:7]
	v_cndmask_b32_e32 v164, 0, v222, vcc
	v_sub_f32_e32 v157, v157, v164
	v_pk_add_f32 v[154:155], v[154:155], v[156:157] neg_lo:[0,1] neg_hi:[0,1]
	v_cmp_gt_f32_e32 vcc, s89, v153
	v_pk_mul_f32 v[154:155], v[154:155], s[28:29] op_sel_hi:[1,0]
	v_fma_f32 v157, v89, v208, v137
	v_cvt_pk_bf16_f32 v149, v154, v155
	v_cndmask_b32_e64 v154, 0, 32, vcc
	v_ldexp_f32 v153, v153, v154
	v_log_f32_e32 v153, v153
	v_fma_f32 v155, v87, v208, v135
	v_mul_f32_e32 v154, 0x3f317217, v153
	v_fma_f32 v154, v153, s90, -v154
	v_fmac_f32_e32 v154, 0x3377d1cf, v153
	v_fmac_f32_e32 v154, 0x3f317217, v153
	v_cmp_lt_f32_e64 s[6:7], |v153|, s91
	s_nop 1
	v_cndmask_b32_e64 v153, v153, v154, s[6:7]
	v_cndmask_b32_e32 v154, 0, v222, vcc
	v_sub_f32_e32 v154, v153, v154
	v_min_f32_e32 v153, 0, v155
	v_mul_f32_e64 v155, |v155|, s88
	v_exp_f32_e32 v155, v155
	s_nop 0
	v_add_f32_e32 v155, 1.0, v155
	v_cmp_gt_f32_e32 vcc, s89, v155
	s_nop 1
	v_cndmask_b32_e64 v156, 0, 32, vcc
	v_ldexp_f32 v155, v155, v156
	v_log_f32_e32 v155, v155
	s_nop 0
	v_mul_f32_e32 v156, 0x3f317217, v155
	v_fma_f32 v156, v155, s90, -v156
	v_fmac_f32_e32 v156, 0x3377d1cf, v155
	v_fmac_f32_e32 v156, 0x3f317217, v155
	v_cmp_lt_f32_e64 s[6:7], |v155|, s91
	s_nop 1
	v_cndmask_b32_e64 v155, v155, v156, s[6:7]
	v_cndmask_b32_e32 v156, 0, v222, vcc
	v_sub_f32_e32 v155, v155, v156
	v_pk_add_f32 v[152:153], v[152:153], v[154:155] neg_lo:[0,1] neg_hi:[0,1]
	v_fma_f32 v155, v88, v208, v136
	v_min_f32_e32 v154, 0, v155
	v_mul_f32_e64 v155, |v155|, s88
	v_exp_f32_e32 v155, v155
	v_pk_mul_f32 v[152:153], v[152:153], s[28:29] op_sel_hi:[1,0]
	v_add_f32_e32 v155, 1.0, v155
	v_cmp_gt_f32_e32 vcc, s89, v155
	v_cvt_pk_bf16_f32 v152, v152, v153
	s_nop 0
	v_cndmask_b32_e64 v156, 0, 32, vcc
	v_ldexp_f32 v155, v155, v156
	v_log_f32_e32 v155, v155
	s_nop 0
	v_mul_f32_e32 v156, 0x3f317217, v155
	v_fma_f32 v156, v155, s90, -v156
	v_fmac_f32_e32 v156, 0x3377d1cf, v155
	v_fmac_f32_e32 v156, 0x3f317217, v155
	v_cmp_lt_f32_e64 s[6:7], |v155|, s91
	s_nop 1
	v_cndmask_b32_e64 v155, v155, v156, s[6:7]
; __device__ __forceinline__ v4u pack8(const f32x4 a, const f32x4 b) { v4u w; w.x = pk2(a[0], a[1]); w.y = pk2(a[2], a[3]); w.z = pk2(b[0], b[1]); w.w = pk2(b[2], b[3]); return w; }
; __device__ __forceinline__ float fast_exp(float x) { return __builtin_amdgcn_exp2f(x * LOG2E); }
;     __device__ __forceinline__ void operator()(const f32x4 (&acc)[2][2][4][2], const pg8::Unit& u, int wr, int wc, int fr, int fq) const {
;     ...
;                     for (int bj = 0; bj < 2; ++bj) {
;                         f32x4 r2[2];
; #pragma unroll
;                         for (int n = 0; n < 2; ++n) {
;                             const f32x4 z = acc[ai][bj][m][n] * rs + bg[bj][n];
; #pragma unroll
;                             for (int j = 0; j < 4; ++j) { const float az = fabsf(z[j]); r2[n][j] = (fminf(z[j], 0.f) - __logf(1.0f + fast_exp(-az))) * (1.0f / 16.0f); }
;                         }
;                         pk[bj] = pack8(r2[0], r2[1]);
;                     }
;                     v4u a, b; tt.bf(pk[0], pk[1], a, b);
;                     bf16* d = (bf16*)(ws + WS_LOGA) + (size_t)rowa * 256 + 64 * wc + 8 * tt.p; *(v4u*)d = a; *(v4u*)(d + 8 * 256) = b;
	v_cndmask_b32_e32 v156, 0, v222, vcc
	v_sub_f32_e32 v156, v155, v156
	v_min_f32_e32 v155, 0, v157
	v_mul_f32_e64 v157, |v157|, s88
	v_exp_f32_e32 v157, v157
	s_nop 0
	v_add_f32_e32 v157, 1.0, v157
	v_cmp_gt_f32_e32 vcc, s89, v157
	s_nop 1
	v_cndmask_b32_e64 v164, 0, 32, vcc
	v_ldexp_f32 v157, v157, v164
	v_log_f32_e32 v157, v157
	s_nop 0
	v_mul_f32_e32 v164, 0x3f317217, v157
	v_fma_f32 v164, v157, s90, -v164
	v_fmac_f32_e32 v164, 0x3377d1cf, v157
	v_fmac_f32_e32 v164, 0x3f317217, v157
	v_cmp_lt_f32_e64 s[6:7], |v157|, s91
	s_nop 1
	v_cndmask_b32_e64 v157, v157, v164, s[6:7]
	v_cndmask_b32_e32 v164, 0, v222, vcc
	v_sub_f32_e32 v157, v157, v164
	v_pk_add_f32 v[154:155], v[154:155], v[156:157] neg_lo:[0,1] neg_hi:[0,1]
	v_fma_f32 v157, v82, v208, v130
	v_min_f32_e32 v156, 0, v157
	v_mul_f32_e64 v157, |v157|, s88
	v_exp_f32_e32 v157, v157
	v_pk_mul_f32 v[154:155], v[154:155], s[28:29] op_sel_hi:[1,0]
	v_add_f32_e32 v157, 1.0, v157
	v_cmp_gt_f32_e32 vcc, s89, v157
	v_cvt_pk_bf16_f32 v153, v154, v155
	s_nop 0
	v_cndmask_b32_e64 v164, 0, 32, vcc
	v_ldexp_f32 v157, v157, v164
	v_log_f32_e32 v157, v157
	s_nop 0
	v_mul_f32_e32 v164, 0x3f317217, v157
	v_fma_f32 v164, v157, s90, -v164
	v_fmac_f32_e32 v164, 0x3377d1cf, v157
	v_fmac_f32_e32 v164, 0x3f317217, v157
	v_cmp_lt_f32_e64 s[6:7], |v157|, s91
	s_nop 1
	v_cndmask_b32_e64 v157, v157, v164, s[6:7]
	v_cndmask_b32_e32 v164, 0, v222, vcc
	v_sub_f32_e32 v164, v157, v164
	v_min_f32_e32 v157, 0, v165
	v_mul_f32_e64 v165, |v165|, s88
	v_exp_f32_e32 v165, v165
	s_nop 0
	v_add_f32_e32 v165, 1.0, v165
	v_cmp_gt_f32_e32 vcc, s89, v165
	s_nop 1
	v_cndmask_b32_e64 v166, 0, 32, vcc
	v_ldexp_f32 v165, v165, v166
	v_log_f32_e32 v165, v165
	s_nop 0
	v_mul_f32_e32 v166, 0x3f317217, v165
	v_fma_f32 v166, v165, s90, -v166
	v_fmac_f32_e32 v166, 0x3377d1cf, v165
	v_fmac_f32_e32 v166, 0x3f317217, v165
	v_cmp_lt_f32_e64 s[6:7], |v165|, s91
	s_nop 1
	v_cndmask_b32_e64 v165, v165, v166, s[6:7]
	v_cndmask_b32_e32 v166, 0, v222, vcc
	v_sub_f32_e32 v165, v165, v166
	v_pk_add_f32 v[156:157], v[156:157], v[164:165] neg_lo:[0,1] neg_hi:[0,1]
	v_fma_f32 v165, v84, v208, v132
	v_min_f32_e32 v164, 0, v165
	v_mul_f32_e64 v165, |v165|, s88
	v_exp_f32_e32 v165, v165
	v_pk_mul_f32 v[156:157], v[156:157], s[28:29] op_sel_hi:[1,0]
	v_add_f32_e32 v165, 1.0, v165
	v_cmp_gt_f32_e32 vcc, s89, v165
	v_cvt_pk_bf16_f32 v154, v156, v157
	v_add_u32_e32 v156, 32, v150
	v_cndmask_b32_e64 v166, 0, 32, vcc
	v_ldexp_f32 v165, v165, v166
	v_log_f32_e32 v165, v165
	v_ashrrev_i32_e32 v157, 31, v156
	v_lshlrev_b64 v[156:157], 9, v[156:157]
	v_lshl_add_u64 v[156:157], s[24:25], 0, v[156:157]
	v_mul_f32_e32 v166, 0x3f317217, v165
	v_fma_f32 v166, v165, s90, -v166
	v_fmac_f32_e32 v166, 0x3377d1cf, v165
	v_fmac_f32_e32 v166, 0x3f317217, v165
	v_cmp_lt_f32_e64 s[6:7], |v165|, s91
	v_lshl_add_u64 v[156:157], v[156:157], 0, v[184:185]
	s_nop 0
	v_cndmask_b32_e64 v165, v165, v166, s[6:7]
	v_cndmask_b32_e32 v166, 0, v222, vcc
	v_sub_f32_e32 v166, v165, v166
	v_min_f32_e32 v165, 0, v167
	v_mul_f32_e64 v167, |v167|, s88
	v_exp_f32_e32 v167, v167
	s_nop 0
	v_add_f32_e32 v167, 1.0, v167
	v_cmp_gt_f32_e32 vcc, s89, v167
	s_nop 1
	v_cndmask_b32_e64 v168, 0, 32, vcc
	v_ldexp_f32 v167, v167, v168
	v_log_f32_e32 v167, v167
	s_nop 0
	v_mul_f32_e32 v168, 0x3f317217, v167
	v_fma_f32 v168, v167, s90, -v168
	v_fmac_f32_e32 v168, 0x3377d1cf, v167
	v_fmac_f32_e32 v168, 0x3f317217, v167
	v_cmp_lt_f32_e64 s[6:7], |v167|, s91
	s_nop 1
	v_cndmask_b32_e64 v167, v167, v168, s[6:7]
	v_cndmask_b32_e32 v168, 0, v222, vcc
	v_sub_f32_e32 v167, v167, v168
	v_pk_add_f32 v[164:165], v[164:165], v[166:167] neg_lo:[0,1] neg_hi:[0,1]
	v_fma_f32 v167, v69, v206, v133
	v_pk_mul_f32 v[164:165], v[164:165], s[28:29] op_sel_hi:[1,0]
	s_nop 0
	v_cvt_pk_bf16_f32 v155, v164, v165
	ds_write_b128 v160, v[146:149]
	ds_write_b128 v161, v[152:155]
	ds_read_b128 v[146:149], v163
	ds_read_b128 v[152:155], v163 offset:1024
	v_fma_f32 v165, v67, v206, v131
	s_waitcnt lgkmcnt(1)
	global_store_dwordx4 v[156:157], v[146:149], off nt
	s_nop 1
	v_add_co_u32_e32 v146, vcc, s92, v156
	v_fma_f32 v149, v79, v206, v143
	s_nop 0
	v_addc_co_u32_e32 v147, vcc, 0, v157, vcc
	s_waitcnt lgkmcnt(0)
	global_store_dwordx4 v[146:147], v[152:155], off nt
	v_fma_f32 v147, v78, v206, v142
	v_min_f32_e32 v146, 0, v147
	v_mul_f32_e64 v147, |v147|, s88
	v_exp_f32_e32 v147, v147
	v_fma_f32 v153, v81, v206, v145
	v_fma_f32 v155, v75, v206, v139
	v_fma_f32 v157, v77, v206, v141
	v_add_f32_e32 v147, 1.0, v147
	v_cmp_gt_f32_e32 vcc, s89, v147
	s_nop 1
	v_cndmask_b32_e64 v148, 0, 32, vcc
	v_ldexp_f32 v147, v147, v148
	v_log_f32_e32 v147, v147
	s_nop 0
	v_mul_f32_e32 v148, 0x3f317217, v147
	v_fma_f32 v148, v147, s90, -v148
	v_fmac_f32_e32 v148, 0x3377d1cf, v147
	v_fmac_f32_e32 v148, 0x3f317217, v147
	v_cmp_lt_f32_e64 s[6:7], |v147|, s91
	s_nop 1
	v_cndmask_b32_e64 v147, v147, v148, s[6:7]
	v_cndmask_b32_e32 v148, 0, v222, vcc
	v_sub_f32_e32 v148, v147, v148
	v_min_f32_e32 v147, 0, v149
	v_mul_f32_e64 v149, |v149|, s88
	v_exp_f32_e32 v149, v149
	s_nop 0
	v_add_f32_e32 v149, 1.0, v149
	v_cmp_gt_f32_e32 vcc, s89, v149
	s_nop 1
	v_cndmask_b32_e64 v152, 0, 32, vcc
	v_ldexp_f32 v149, v149, v152
	v_log_f32_e32 v149, v149
	s_nop 0
	v_mul_f32_e32 v152, 0x3f317217, v149
	v_fma_f32 v152, v149, s90, -v152
	v_fmac_f32_e32 v152, 0x3377d1cf, v149
	v_fmac_f32_e32 v152, 0x3f317217, v149
	v_cmp_lt_f32_e64 s[6:7], |v149|, s91
	s_nop 1
	v_cndmask_b32_e64 v149, v149, v152, s[6:7]
	v_cndmask_b32_e32 v152, 0, v222, vcc
	v_sub_f32_e32 v149, v149, v152
	v_pk_add_f32 v[146:147], v[146:147], v[148:149] neg_lo:[0,1] neg_hi:[0,1]
	v_fma_f32 v149, v80, v206, v144
; __device__ __forceinline__ v4u pack8(const f32x4 a, const f32x4 b) { v4u w; w.x = pk2(a[0], a[1]); w.y = pk2(a[2], a[3]); w.z = pk2(b[0], b[1]); w.w = pk2(b[2], b[3]); return w; }
; __device__ __forceinline__ float fast_exp(float x) { return __builtin_amdgcn_exp2f(x * LOG2E); }
;     __device__ __forceinline__ void operator()(const f32x4 (&acc)[2][2][4][2], const pg8::Unit& u, int wr, int wc, int fr, int fq) const {
;     ...
;                     for (int bj = 0; bj < 2; ++bj) {
;                         f32x4 r2[2];
; #pragma unroll
;                         for (int n = 0; n < 2; ++n) {
;                             const f32x4 z = acc[ai][bj][m][n] * rs + bg[bj][n];
; #pragma unroll
;                             for (int j = 0; j < 4; ++j) { const float az = fabsf(z[j]); r2[n][j] = (fminf(z[j], 0.f) - __logf(1.0f + fast_exp(-az))) * (1.0f / 16.0f); }
;                         }
;                         pk[bj] = pack8(r2[0], r2[1]);
;                     }
;                     v4u a, b; tt.bf(pk[0], pk[1], a, b);
;                     bf16* d = (bf16*)(ws + WS_LOGA) + (size_t)rowa * 256 + 64 * wc + 8 * tt.p; *(v4u*)d = a; *(v4u*)(d + 8 * 256) = b;
	v_min_f32_e32 v148, 0, v149
	v_mul_f32_e64 v149, |v149|, s88
	v_exp_f32_e32 v149, v149
	v_pk_mul_f32 v[146:147], v[146:147], s[28:29] op_sel_hi:[1,0]
	v_add_f32_e32 v149, 1.0, v149
	v_cmp_gt_f32_e32 vcc, s89, v149
	v_cvt_pk_bf16_f32 v146, v146, v147
	s_nop 0
	v_cndmask_b32_e64 v152, 0, 32, vcc
	v_ldexp_f32 v149, v149, v152
	v_log_f32_e32 v149, v149
	s_nop 0
	v_mul_f32_e32 v152, 0x3f317217, v149
	v_fma_f32 v152, v149, s90, -v152
	v_fmac_f32_e32 v152, 0x3377d1cf, v149
	v_fmac_f32_e32 v152, 0x3f317217, v149
	v_cmp_lt_f32_e64 s[6:7], |v149|, s91
	s_nop 1
	v_cndmask_b32_e64 v149, v149, v152, s[6:7]
	v_cndmask_b32_e32 v152, 0, v222, vcc
	v_sub_f32_e32 v152, v149, v152
	v_min_f32_e32 v149, 0, v153
	v_mul_f32_e64 v153, |v153|, s88
	v_exp_f32_e32 v153, v153
	s_nop 0
	v_add_f32_e32 v153, 1.0, v153
	v_cmp_gt_f32_e32 vcc, s89, v153
	s_nop 1
	v_cndmask_b32_e64 v154, 0, 32, vcc
	v_ldexp_f32 v153, v153, v154
	v_log_f32_e32 v153, v153
	s_nop 0
	v_mul_f32_e32 v154, 0x3f317217, v153
	v_fma_f32 v154, v153, s90, -v154
	v_fmac_f32_e32 v154, 0x3377d1cf, v153
	v_fmac_f32_e32 v154, 0x3f317217, v153
	v_cmp_lt_f32_e64 s[6:7], |v153|, s91
	s_nop 1
	v_cndmask_b32_e64 v153, v153, v154, s[6:7]
	v_cndmask_b32_e32 v154, 0, v222, vcc
	v_sub_f32_e32 v153, v153, v154
	v_pk_add_f32 v[148:149], v[148:149], v[152:153] neg_lo:[0,1] neg_hi:[0,1]
	v_fma_f32 v153, v74, v206, v138
	v_min_f32_e32 v152, 0, v153
	v_mul_f32_e64 v153, |v153|, s88
	v_exp_f32_e32 v153, v153
	v_pk_mul_f32 v[148:149], v[148:149], s[28:29] op_sel_hi:[1,0]
	v_add_f32_e32 v153, 1.0, v153
	v_cmp_gt_f32_e32 vcc, s89, v153
	v_cvt_pk_bf16_f32 v147, v148, v149
	s_nop 0
	v_cndmask_b32_e64 v154, 0, 32, vcc
	v_ldexp_f32 v153, v153, v154
	v_log_f32_e32 v153, v153
	s_nop 0
	v_mul_f32_e32 v154, 0x3f317217, v153
	v_fma_f32 v154, v153, s90, -v154
	v_fmac_f32_e32 v154, 0x3377d1cf, v153
	v_fmac_f32_e32 v154, 0x3f317217, v153
	v_cmp_lt_f32_e64 s[6:7], |v153|, s91
	s_nop 1
	v_cndmask_b32_e64 v153, v153, v154, s[6:7]
	v_cndmask_b32_e32 v154, 0, v222, vcc
	v_sub_f32_e32 v154, v153, v154
	v_min_f32_e32 v153, 0, v155
	v_mul_f32_e64 v155, |v155|, s88
	v_exp_f32_e32 v155, v155
	s_nop 0
	v_add_f32_e32 v155, 1.0, v155
	v_cmp_gt_f32_e32 vcc, s89, v155
	s_nop 1
	v_cndmask_b32_e64 v156, 0, 32, vcc
	v_ldexp_f32 v155, v155, v156
	v_log_f32_e32 v155, v155
	s_nop 0
	v_mul_f32_e32 v156, 0x3f317217, v155
	v_fma_f32 v156, v155, s90, -v156
	v_fmac_f32_e32 v156, 0x3377d1cf, v155
	v_fmac_f32_e32 v156, 0x3f317217, v155
	v_cmp_lt_f32_e64 s[6:7], |v155|, s91
	s_nop 1
	v_cndmask_b32_e64 v155, v155, v156, s[6:7]
	v_cndmask_b32_e32 v156, 0, v222, vcc
	v_sub_f32_e32 v155, v155, v156
	v_pk_add_f32 v[152:153], v[152:153], v[154:155] neg_lo:[0,1] neg_hi:[0,1]
	v_fma_f32 v155, v76, v206, v140
	v_min_f32_e32 v154, 0, v155
	v_mul_f32_e64 v155, |v155|, s88
	v_exp_f32_e32 v155, v155
	v_pk_mul_f32 v[152:153], v[152:153], s[28:29] op_sel_hi:[1,0]
	v_add_f32_e32 v155, 1.0, v155
	v_cmp_gt_f32_e32 vcc, s89, v155
	v_cvt_pk_bf16_f32 v148, v152, v153
	v_fma_f32 v153, v70, v206, v134
	v_cndmask_b32_e64 v156, 0, 32, vcc
	v_ldexp_f32 v155, v155, v156
	v_log_f32_e32 v155, v155
	v_min_f32_e32 v152, 0, v153
	v_mul_f32_e64 v153, |v153|, s88
	v_exp_f32_e32 v153, v153
	v_mul_f32_e32 v156, 0x3f317217, v155
	v_fma_f32 v156, v155, s90, -v156
	v_fmac_f32_e32 v156, 0x3377d1cf, v155
	v_fmac_f32_e32 v156, 0x3f317217, v155
	v_cmp_lt_f32_e64 s[6:7], |v155|, s91
	v_add_f32_e32 v153, 1.0, v153
	s_nop 0
	v_cndmask_b32_e64 v155, v155, v156, s[6:7]
	v_cndmask_b32_e32 v156, 0, v222, vcc
	v_sub_f32_e32 v156, v155, v156
	v_min_f32_e32 v155, 0, v157
	v_mul_f32_e64 v157, |v157|, s88
	v_exp_f32_e32 v157, v157
	s_nop 0
	v_add_f32_e32 v157, 1.0, v157
	v_cmp_gt_f32_e32 vcc, s89, v157
	s_nop 1
	v_cndmask_b32_e64 v164, 0, 32, vcc
	v_ldexp_f32 v157, v157, v164
	v_log_f32_e32 v157, v157
	s_nop 0
	v_mul_f32_e32 v164, 0x3f317217, v157
	v_fma_f32 v164, v157, s90, -v164
	v_fmac_f32_e32 v164, 0x3377d1cf, v157
	v_fmac_f32_e32 v164, 0x3f317217, v157
	v_cmp_lt_f32_e64 s[6:7], |v157|, s91
	s_nop 1
	v_cndmask_b32_e64 v157, v157, v164, s[6:7]
	v_cndmask_b32_e32 v164, 0, v222, vcc
	v_sub_f32_e32 v157, v157, v164
	v_pk_add_f32 v[154:155], v[154:155], v[156:157] neg_lo:[0,1] neg_hi:[0,1]
	v_cmp_gt_f32_e32 vcc, s89, v153
	v_pk_mul_f32 v[154:155], v[154:155], s[28:29] op_sel_hi:[1,0]
	v_fma_f32 v157, v73, v206, v137
	v_cvt_pk_bf16_f32 v149, v154, v155
	v_cndmask_b32_e64 v154, 0, 32, vcc
	v_ldexp_f32 v153, v153, v154
	v_log_f32_e32 v153, v153
	v_fma_f32 v155, v71, v206, v135
	v_mul_f32_e32 v154, 0x3f317217, v153
	v_fma_f32 v154, v153, s90, -v154
	v_fmac_f32_e32 v154, 0x3377d1cf, v153
	v_fmac_f32_e32 v154, 0x3f317217, v153
	v_cmp_lt_f32_e64 s[6:7], |v153|, s91
	s_nop 1
	v_cndmask_b32_e64 v153, v153, v154, s[6:7]
	v_cndmask_b32_e32 v154, 0, v222, vcc
	v_sub_f32_e32 v154, v153, v154
	v_min_f32_e32 v153, 0, v155
	v_mul_f32_e64 v155, |v155|, s88
	v_exp_f32_e32 v155, v155
	s_nop 0
	v_add_f32_e32 v155, 1.0, v155
	v_cmp_gt_f32_e32 vcc, s89, v155
	s_nop 1
	v_cndmask_b32_e64 v156, 0, 32, vcc
	v_ldexp_f32 v155, v155, v156
	v_log_f32_e32 v155, v155
	s_nop 0
	v_mul_f32_e32 v156, 0x3f317217, v155
	v_fma_f32 v156, v155, s90, -v156
	v_fmac_f32_e32 v156, 0x3377d1cf, v155
	v_fmac_f32_e32 v156, 0x3f317217, v155
	v_cmp_lt_f32_e64 s[6:7], |v155|, s91
	s_nop 1
	v_cndmask_b32_e64 v155, v155, v156, s[6:7]
	v_cndmask_b32_e32 v156, 0, v222, vcc
	v_sub_f32_e32 v155, v155, v156
	v_pk_add_f32 v[152:153], v[152:153], v[154:155] neg_lo:[0,1] neg_hi:[0,1]
	v_fma_f32 v155, v72, v206, v136
	v_min_f32_e32 v154, 0, v155
	v_mul_f32_e64 v155, |v155|, s88
	v_exp_f32_e32 v155, v155
	v_pk_mul_f32 v[152:153], v[152:153], s[28:29] op_sel_hi:[1,0]
; __device__ __forceinline__ v4u pack8(const f32x4 a, const f32x4 b) { v4u w; w.x = pk2(a[0], a[1]); w.y = pk2(a[2], a[3]); w.z = pk2(b[0], b[1]); w.w = pk2(b[2], b[3]); return w; }
; __device__ __forceinline__ float fast_exp(float x) { return __builtin_amdgcn_exp2f(x * LOG2E); }
;     __device__ __forceinline__ void operator()(const f32x4 (&acc)[2][2][4][2], const pg8::Unit& u, int wr, int wc, int fr, int fq) const {
;     ...
;                     for (int bj = 0; bj < 2; ++bj) {
;                         f32x4 r2[2];
; #pragma unroll
;                         for (int n = 0; n < 2; ++n) {
;                             const f32x4 z = acc[ai][bj][m][n] * rs + bg[bj][n];
; #pragma unroll
;                             for (int j = 0; j < 4; ++j) { const float az = fabsf(z[j]); r2[n][j] = (fminf(z[j], 0.f) - __logf(1.0f + fast_exp(-az))) * (1.0f / 16.0f); }
;                         }
;                         pk[bj] = pack8(r2[0], r2[1]);
;                     }
;                     v4u a, b; tt.bf(pk[0], pk[1], a, b);
;                     bf16* d = (bf16*)(ws + WS_LOGA) + (size_t)rowa * 256 + 64 * wc + 8 * tt.p; *(v4u*)d = a; *(v4u*)(d + 8 * 256) = b;
	v_add_f32_e32 v155, 1.0, v155
	v_cmp_gt_f32_e32 vcc, s89, v155
	v_cvt_pk_bf16_f32 v152, v152, v153
	s_nop 0
	v_cndmask_b32_e64 v156, 0, 32, vcc
	v_ldexp_f32 v155, v155, v156
	v_log_f32_e32 v155, v155
	s_nop 0
	v_mul_f32_e32 v156, 0x3f317217, v155
	v_fma_f32 v156, v155, s90, -v156
	v_fmac_f32_e32 v156, 0x3377d1cf, v155
	v_fmac_f32_e32 v156, 0x3f317217, v155
	v_cmp_lt_f32_e64 s[6:7], |v155|, s91
	s_nop 1
	v_cndmask_b32_e64 v155, v155, v156, s[6:7]
	v_cndmask_b32_e32 v156, 0, v222, vcc
	v_sub_f32_e32 v156, v155, v156
	v_min_f32_e32 v155, 0, v157
	v_mul_f32_e64 v157, |v157|, s88
	v_exp_f32_e32 v157, v157
	s_nop 0
	v_add_f32_e32 v157, 1.0, v157
	v_cmp_gt_f32_e32 vcc, s89, v157
	s_nop 1
	v_cndmask_b32_e64 v164, 0, 32, vcc
	v_ldexp_f32 v157, v157, v164
	v_log_f32_e32 v157, v157
	s_nop 0
	v_mul_f32_e32 v164, 0x3f317217, v157
	v_fma_f32 v164, v157, s90, -v164
	v_fmac_f32_e32 v164, 0x3377d1cf, v157
	v_fmac_f32_e32 v164, 0x3f317217, v157
	v_cmp_lt_f32_e64 s[6:7], |v157|, s91
	s_nop 1
	v_cndmask_b32_e64 v157, v157, v164, s[6:7]
	v_cndmask_b32_e32 v164, 0, v222, vcc
	v_sub_f32_e32 v157, v157, v164
	v_pk_add_f32 v[154:155], v[154:155], v[156:157] neg_lo:[0,1] neg_hi:[0,1]
	v_fma_f32 v157, v66, v206, v130
	v_min_f32_e32 v156, 0, v157
	v_mul_f32_e64 v157, |v157|, s88
	v_exp_f32_e32 v157, v157
	v_pk_mul_f32 v[154:155], v[154:155], s[28:29] op_sel_hi:[1,0]
	v_add_f32_e32 v157, 1.0, v157
	v_cmp_gt_f32_e32 vcc, s89, v157
	v_cvt_pk_bf16_f32 v153, v154, v155
	s_nop 0
	v_cndmask_b32_e64 v164, 0, 32, vcc
	v_ldexp_f32 v157, v157, v164
	v_log_f32_e32 v157, v157
	s_nop 0
	v_mul_f32_e32 v164, 0x3f317217, v157
	v_fma_f32 v164, v157, s90, -v164
	v_fmac_f32_e32 v164, 0x3377d1cf, v157
	v_fmac_f32_e32 v164, 0x3f317217, v157
	v_cmp_lt_f32_e64 s[6:7], |v157|, s91
	s_nop 1
	v_cndmask_b32_e64 v157, v157, v164, s[6:7]
	v_cndmask_b32_e32 v164, 0, v222, vcc
	v_sub_f32_e32 v164, v157, v164
	v_min_f32_e32 v157, 0, v165
	v_mul_f32_e64 v165, |v165|, s88
	v_exp_f32_e32 v165, v165
	s_nop 0
	v_add_f32_e32 v165, 1.0, v165
	v_cmp_gt_f32_e32 vcc, s89, v165
	s_nop 1
	v_cndmask_b32_e64 v166, 0, 32, vcc
	v_ldexp_f32 v165, v165, v166
	v_log_f32_e32 v165, v165
	s_nop 0
	v_mul_f32_e32 v166, 0x3f317217, v165
	v_fma_f32 v166, v165, s90, -v166
	v_fmac_f32_e32 v166, 0x3377d1cf, v165
	v_fmac_f32_e32 v166, 0x3f317217, v165
	v_cmp_lt_f32_e64 s[6:7], |v165|, s91
	s_nop 1
	v_cndmask_b32_e64 v165, v165, v166, s[6:7]
	v_cndmask_b32_e32 v166, 0, v222, vcc
	v_sub_f32_e32 v165, v165, v166
	v_pk_add_f32 v[156:157], v[156:157], v[164:165] neg_lo:[0,1] neg_hi:[0,1]
	v_fma_f32 v165, v68, v206, v132
	v_min_f32_e32 v164, 0, v165
	v_mul_f32_e64 v165, |v165|, s88
	v_exp_f32_e32 v165, v165
	v_pk_mul_f32 v[156:157], v[156:157], s[28:29] op_sel_hi:[1,0]
	v_add_f32_e32 v165, 1.0, v165
	v_cmp_gt_f32_e32 vcc, s89, v165
	v_cvt_pk_bf16_f32 v154, v156, v157
	v_add_u32_e32 v156, 48, v150
	v_cndmask_b32_e64 v166, 0, 32, vcc
	v_ldexp_f32 v165, v165, v166
	v_log_f32_e32 v165, v165
	v_ashrrev_i32_e32 v157, 31, v156
	v_lshlrev_b64 v[156:157], 9, v[156:157]
	v_lshl_add_u64 v[156:157], s[24:25], 0, v[156:157]
	v_mul_f32_e32 v166, 0x3f317217, v165
	v_fma_f32 v166, v165, s90, -v166
	v_fmac_f32_e32 v166, 0x3377d1cf, v165
	v_fmac_f32_e32 v166, 0x3f317217, v165
	v_cmp_lt_f32_e64 s[6:7], |v165|, s91
	v_lshl_add_u64 v[156:157], v[156:157], 0, v[184:185]
	s_nop 0
	v_cndmask_b32_e64 v165, v165, v166, s[6:7]
	v_cndmask_b32_e32 v166, 0, v222, vcc
	v_sub_f32_e32 v166, v165, v166
	v_min_f32_e32 v165, 0, v167
	v_mul_f32_e64 v167, |v167|, s88
	v_exp_f32_e32 v167, v167
	s_nop 0
	v_add_f32_e32 v167, 1.0, v167
	v_cmp_gt_f32_e32 vcc, s89, v167
	s_nop 1
	v_cndmask_b32_e64 v168, 0, 32, vcc
	v_ldexp_f32 v167, v167, v168
	v_log_f32_e32 v167, v167
	s_nop 0
	v_mul_f32_e32 v168, 0x3f317217, v167
	v_fma_f32 v168, v167, s90, -v168
	v_fmac_f32_e32 v168, 0x3377d1cf, v167
	v_fmac_f32_e32 v168, 0x3f317217, v167
	v_cmp_lt_f32_e64 s[6:7], |v167|, s91
	s_nop 1
	v_cndmask_b32_e64 v167, v167, v168, s[6:7]
	v_cndmask_b32_e32 v168, 0, v222, vcc
	v_sub_f32_e32 v167, v167, v168
	v_pk_add_f32 v[164:165], v[164:165], v[166:167] neg_lo:[0,1] neg_hi:[0,1]
	s_nop 0
	v_pk_mul_f32 v[164:165], v[164:165], s[28:29] op_sel_hi:[1,0]
	s_nop 0
	v_cvt_pk_bf16_f32 v155, v164, v165
	ds_write_b128 v160, v[146:149]
	ds_write_b128 v161, v[152:155]
	ds_read_b128 v[146:149], v163
	ds_read_b128 v[152:155], v163 offset:1024
	s_waitcnt lgkmcnt(1)
	global_store_dwordx4 v[156:157], v[146:149], off nt
	s_nop 1
	v_add_co_u32_e32 v146, vcc, s92, v156
	v_fma_f32 v149, v63, v204, v143
	s_nop 0
	v_addc_co_u32_e32 v147, vcc, 0, v157, vcc
	s_waitcnt lgkmcnt(0)
; __device__ __forceinline__ v4u pack8(const f32x4 a, const f32x4 b) { v4u w; w.x = pk2(a[0], a[1]); w.y = pk2(a[2], a[3]); w.z = pk2(b[0], b[1]); w.w = pk2(b[2], b[3]); return w; }
; __device__ __forceinline__ float fast_exp(float x) { return __builtin_amdgcn_exp2f(x * LOG2E); }
;     __device__ __forceinline__ void operator()(const f32x4 (&acc)[2][2][4][2], const pg8::Unit& u, int wr, int wc, int fr, int fq) const {
;     ...
;                     for (int bj = 0; bj < 2; ++bj) {
;                         f32x4 r2[2];
; #pragma unroll
;                         for (int n = 0; n < 2; ++n) {
;                             const f32x4 z = acc[ai][bj][m][n] * rs + bg[bj][n];
; #pragma unroll
;                             for (int j = 0; j < 4; ++j) { const float az = fabsf(z[j]); r2[n][j] = (fminf(z[j], 0.f) - __logf(1.0f + fast_exp(-az))) * (1.0f / 16.0f); }
;                         }
;                         pk[bj] = pack8(r2[0], r2[1]);
;                     }
;                     v4u a, b; tt.bf(pk[0], pk[1], a, b);
;                     bf16* d = (bf16*)(ws + WS_LOGA) + (size_t)rowa * 256 + 64 * wc + 8 * tt.p; *(v4u*)d = a; *(v4u*)(d + 8 * 256) = b;
	global_store_dwordx4 v[146:147], v[152:155], off nt
	v_fma_f32 v147, v62, v204, v142
	v_min_f32_e32 v146, 0, v147
	v_mul_f32_e64 v147, |v147|, s88
	v_exp_f32_e32 v147, v147
	v_add_u32_e32 v152, 0x80, v150
	v_add_f32_e32 v147, 1.0, v147
	v_cmp_gt_f32_e32 vcc, s89, v147
	s_nop 1
	v_cndmask_b32_e64 v148, 0, 32, vcc
	v_ldexp_f32 v147, v147, v148
	v_log_f32_e32 v147, v147
	s_nop 0
	v_mul_f32_e32 v148, 0x3f317217, v147
	v_fma_f32 v148, v147, s90, -v148
	v_fmac_f32_e32 v148, 0x3377d1cf, v147
	v_fmac_f32_e32 v148, 0x3f317217, v147
	v_cmp_lt_f32_e64 s[6:7], |v147|, s91
	s_nop 1
	v_cndmask_b32_e64 v147, v147, v148, s[6:7]
	v_cndmask_b32_e32 v148, 0, v222, vcc
	v_sub_f32_e32 v148, v147, v148
	v_min_f32_e32 v147, 0, v149
	v_mul_f32_e64 v149, |v149|, s88
	v_exp_f32_e32 v149, v149
	s_nop 0
	v_add_f32_e32 v149, 1.0, v149
	v_cmp_gt_f32_e32 vcc, s89, v149
	s_nop 1
	v_cndmask_b32_e64 v153, 0, 32, vcc
	v_ldexp_f32 v149, v149, v153
	v_log_f32_e32 v149, v149
	s_nop 0
	v_mul_f32_e32 v153, 0x3f317217, v149
	v_fma_f32 v153, v149, s90, -v153
	v_fmac_f32_e32 v153, 0x3377d1cf, v149
	v_fmac_f32_e32 v153, 0x3f317217, v149
	v_cmp_lt_f32_e64 s[6:7], |v149|, s91
	s_nop 1
	v_cndmask_b32_e64 v149, v149, v153, s[6:7]
	v_cndmask_b32_e32 v153, 0, v222, vcc
	v_sub_f32_e32 v149, v149, v153
	v_pk_add_f32 v[146:147], v[146:147], v[148:149] neg_lo:[0,1] neg_hi:[0,1]
	v_fma_f32 v149, v64, v204, v144
	v_min_f32_e32 v148, 0, v149
	v_mul_f32_e64 v149, |v149|, s88
	v_exp_f32_e32 v149, v149
	v_pk_mul_f32 v[146:147], v[146:147], s[28:29] op_sel_hi:[1,0]
	v_add_f32_e32 v149, 1.0, v149
	v_cmp_gt_f32_e32 vcc, s89, v149
	v_cvt_pk_bf16_f32 v146, v146, v147
	s_nop 0
	v_cndmask_b32_e64 v153, 0, 32, vcc
	v_ldexp_f32 v149, v149, v153
	v_log_f32_e32 v149, v149
	s_nop 0
	v_mul_f32_e32 v153, 0x3f317217, v149
	v_fma_f32 v153, v149, s90, -v153
	v_fmac_f32_e32 v153, 0x3377d1cf, v149
	v_fmac_f32_e32 v153, 0x3f317217, v149
	v_cmp_lt_f32_e64 s[6:7], |v149|, s91
	s_nop 1
	v_cndmask_b32_e64 v149, v149, v153, s[6:7]
	v_cndmask_b32_e32 v153, 0, v222, vcc
	v_sub_f32_e32 v154, v149, v153
	v_fma_f32 v153, v65, v204, v145
	v_min_f32_e32 v149, 0, v153
	v_mul_f32_e64 v153, |v153|, s88
	v_exp_f32_e32 v153, v153
	s_nop 0
	v_add_f32_e32 v153, 1.0, v153
	v_cmp_gt_f32_e32 vcc, s89, v153
	s_nop 1
	v_cndmask_b32_e64 v155, 0, 32, vcc
	v_ldexp_f32 v153, v153, v155
	v_log_f32_e32 v153, v153
	s_nop 0
	v_mul_f32_e32 v155, 0x3f317217, v153
	v_fma_f32 v155, v153, s90, -v155
	v_fmac_f32_e32 v155, 0x3377d1cf, v153
	v_fmac_f32_e32 v155, 0x3f317217, v153
	v_cmp_lt_f32_e64 s[6:7], |v153|, s91
	s_nop 1
	v_cndmask_b32_e64 v153, v153, v155, s[6:7]
	v_cndmask_b32_e32 v155, 0, v222, vcc
	v_sub_f32_e32 v155, v153, v155
	v_fma_f32 v153, v58, v204, v138
	v_pk_add_f32 v[148:149], v[148:149], v[154:155] neg_lo:[0,1] neg_hi:[0,1]
	v_min_f32_e32 v154, 0, v153
	v_mul_f32_e64 v153, |v153|, s88
	v_exp_f32_e32 v153, v153
	v_pk_mul_f32 v[148:149], v[148:149], s[28:29] op_sel_hi:[1,0]
	v_add_f32_e32 v153, 1.0, v153
	v_cmp_gt_f32_e32 vcc, s89, v153
	v_cvt_pk_bf16_f32 v147, v148, v149
	s_nop 0
	v_cndmask_b32_e64 v155, 0, 32, vcc
	v_ldexp_f32 v153, v153, v155
	v_log_f32_e32 v153, v153
	s_nop 0
	v_mul_f32_e32 v155, 0x3f317217, v153
	v_fma_f32 v155, v153, s90, -v155
	v_fmac_f32_e32 v155, 0x3377d1cf, v153
	v_fmac_f32_e32 v155, 0x3f317217, v153
	v_cmp_lt_f32_e64 s[6:7], |v153|, s91
	s_nop 1
	v_cndmask_b32_e64 v153, v153, v155, s[6:7]
	v_cndmask_b32_e32 v155, 0, v222, vcc
	v_sub_f32_e32 v156, v153, v155
	v_fma_f32 v153, v59, v204, v139
	v_min_f32_e32 v155, 0, v153
	v_mul_f32_e64 v153, |v153|, s88
	v_exp_f32_e32 v153, v153
	s_nop 0
	v_add_f32_e32 v153, 1.0, v153
	v_cmp_gt_f32_e32 vcc, s89, v153
	s_nop 1
	v_cndmask_b32_e64 v157, 0, 32, vcc
	v_ldexp_f32 v153, v153, v157
	v_log_f32_e32 v153, v153
	s_nop 0
	v_mul_f32_e32 v157, 0x3f317217, v153
	v_fma_f32 v157, v153, s90, -v157
	v_fmac_f32_e32 v157, 0x3377d1cf, v153
	v_fmac_f32_e32 v157, 0x3f317217, v153
	v_cmp_lt_f32_e64 s[6:7], |v153|, s91
	s_nop 1
	v_cndmask_b32_e64 v153, v153, v157, s[6:7]
	v_cndmask_b32_e32 v157, 0, v222, vcc
	v_sub_f32_e32 v157, v153, v157
	v_fma_f32 v153, v60, v204, v140
	v_pk_add_f32 v[154:155], v[154:155], v[156:157] neg_lo:[0,1] neg_hi:[0,1]
	v_min_f32_e32 v156, 0, v153
	v_mul_f32_e64 v153, |v153|, s88
	v_exp_f32_e32 v153, v153
	v_pk_mul_f32 v[154:155], v[154:155], s[28:29] op_sel_hi:[1,0]
	v_add_f32_e32 v153, 1.0, v153
	v_cmp_gt_f32_e32 vcc, s89, v153
	v_cvt_pk_bf16_f32 v148, v154, v155
	s_nop 0
	v_cndmask_b32_e64 v157, 0, 32, vcc
	v_ldexp_f32 v153, v153, v157
	v_log_f32_e32 v153, v153
	s_nop 0
	v_mul_f32_e32 v157, 0x3f317217, v153
	v_fma_f32 v157, v153, s90, -v157
	v_fmac_f32_e32 v157, 0x3377d1cf, v153
	v_fmac_f32_e32 v157, 0x3f317217, v153
	v_cmp_lt_f32_e64 s[6:7], |v153|, s91
	s_nop 1
	v_cndmask_b32_e64 v153, v153, v157, s[6:7]
	v_cndmask_b32_e32 v157, 0, v222, vcc
	v_sub_f32_e32 v164, v153, v157
	v_fma_f32 v153, v61, v204, v141
	v_min_f32_e32 v157, 0, v153
	v_mul_f32_e64 v153, |v153|, s88
	v_exp_f32_e32 v153, v153
	s_nop 0
	v_add_f32_e32 v153, 1.0, v153
	v_cmp_gt_f32_e32 vcc, s89, v153
	s_nop 1
	v_cndmask_b32_e64 v165, 0, 32, vcc
	v_ldexp_f32 v153, v153, v165
	v_log_f32_e32 v153, v153
	s_nop 0
	v_mul_f32_e32 v165, 0x3f317217, v153
	v_fma_f32 v165, v153, s90, -v165
	v_fmac_f32_e32 v165, 0x3377d1cf, v153
	v_fmac_f32_e32 v165, 0x3f317217, v153
	v_cmp_lt_f32_e64 s[6:7], |v153|, s91
	s_nop 1
	v_cndmask_b32_e64 v153, v153, v165, s[6:7]
	v_cndmask_b32_e32 v165, 0, v222, vcc
	v_sub_f32_e32 v165, v153, v165
	v_fma_f32 v153, v54, v204, v134
	v_min_f32_e32 v154, 0, v153
	v_mul_f32_e64 v153, |v153|, s88
	v_exp_f32_e32 v153, v153
	v_pk_add_f32 v[156:157], v[156:157], v[164:165] neg_lo:[0,1] neg_hi:[0,1]
; __device__ __forceinline__ v4u pack8(const f32x4 a, const f32x4 b) { v4u w; w.x = pk2(a[0], a[1]); w.y = pk2(a[2], a[3]); w.z = pk2(b[0], b[1]); w.w = pk2(b[2], b[3]); return w; }
; __device__ __forceinline__ float fast_exp(float x) { return __builtin_amdgcn_exp2f(x * LOG2E); }
;     __device__ __forceinline__ void operator()(const f32x4 (&acc)[2][2][4][2], const pg8::Unit& u, int wr, int wc, int fr, int fq) const {
;     ...
;                             const f32x4 z = acc[ai][bj][m][n] * rs + bg[bj][n];
; #pragma unroll
;                             for (int j = 0; j < 4; ++j) { const float az = fabsf(z[j]); r2[n][j] = (fminf(z[j], 0.f) - __logf(1.0f + fast_exp(-az))) * (1.0f / 16.0f); }
;                         }
;                         pk[bj] = pack8(r2[0], r2[1]);
;                     }
;                     v4u a, b; tt.bf(pk[0], pk[1], a, b);
;                     bf16* d = (bf16*)(ws + WS_LOGA) + (size_t)rowa * 256 + 64 * wc + 8 * tt.p; *(v4u*)d = a; *(v4u*)(d + 8 * 256) = b;
	v_add_f32_e32 v153, 1.0, v153
	v_cmp_gt_f32_e32 vcc, s89, v153
	v_pk_mul_f32 v[156:157], v[156:157], s[28:29] op_sel_hi:[1,0]
	s_nop 0
	v_cndmask_b32_e64 v155, 0, 32, vcc
	v_ldexp_f32 v153, v153, v155
	v_log_f32_e32 v153, v153
	v_cvt_pk_bf16_f32 v149, v156, v157
	v_mul_f32_e32 v155, 0x3f317217, v153
	v_fma_f32 v155, v153, s90, -v155
	v_fmac_f32_e32 v155, 0x3377d1cf, v153
	v_fmac_f32_e32 v155, 0x3f317217, v153
	v_cmp_lt_f32_e64 s[6:7], |v153|, s91
	s_nop 1
	v_cndmask_b32_e64 v153, v153, v155, s[6:7]
	v_cndmask_b32_e32 v155, 0, v222, vcc
	v_sub_f32_e32 v156, v153, v155
	v_fma_f32 v153, v55, v204, v135
	v_min_f32_e32 v155, 0, v153
	v_mul_f32_e64 v153, |v153|, s88
	v_exp_f32_e32 v153, v153
	s_nop 0
	v_add_f32_e32 v153, 1.0, v153
	v_cmp_gt_f32_e32 vcc, s89, v153
	s_nop 1
	v_cndmask_b32_e64 v157, 0, 32, vcc
	v_ldexp_f32 v153, v153, v157
	v_log_f32_e32 v153, v153
	s_nop 0
	v_mul_f32_e32 v157, 0x3f317217, v153
	v_fma_f32 v157, v153, s90, -v157
	v_fmac_f32_e32 v157, 0x3377d1cf, v153
	v_fmac_f32_e32 v157, 0x3f317217, v153
	v_cmp_lt_f32_e64 s[6:7], |v153|, s91
	s_nop 1
	v_cndmask_b32_e64 v153, v153, v157, s[6:7]
	v_cndmask_b32_e32 v157, 0, v222, vcc
	v_sub_f32_e32 v157, v153, v157
	v_fma_f32 v153, v56, v204, v136
	v_pk_add_f32 v[154:155], v[154:155], v[156:157] neg_lo:[0,1] neg_hi:[0,1]
	v_min_f32_e32 v156, 0, v153
	v_mul_f32_e64 v153, |v153|, s88
	v_exp_f32_e32 v153, v153
	v_pk_mul_f32 v[154:155], v[154:155], s[28:29] op_sel_hi:[1,0]
	v_add_f32_e32 v153, 1.0, v153
	v_cmp_gt_f32_e32 vcc, s89, v153
	v_cvt_pk_bf16_f32 v154, v154, v155
	s_nop 0
	v_cndmask_b32_e64 v157, 0, 32, vcc
	v_ldexp_f32 v153, v153, v157
	v_log_f32_e32 v153, v153
	s_nop 0
	v_mul_f32_e32 v157, 0x3f317217, v153
	v_fma_f32 v157, v153, s90, -v157
	v_fmac_f32_e32 v157, 0x3377d1cf, v153
	v_fmac_f32_e32 v157, 0x3f317217, v153
	v_cmp_lt_f32_e64 s[6:7], |v153|, s91
	s_nop 1
	v_cndmask_b32_e64 v153, v153, v157, s[6:7]
	v_cndmask_b32_e32 v157, 0, v222, vcc
	v_sub_f32_e32 v164, v153, v157
	v_fma_f32 v153, v57, v204, v137
	v_min_f32_e32 v157, 0, v153
	v_mul_f32_e64 v153, |v153|, s88
	v_exp_f32_e32 v153, v153
	s_nop 0
	v_add_f32_e32 v153, 1.0, v153
	v_cmp_gt_f32_e32 vcc, s89, v153
	s_nop 1
	v_cndmask_b32_e64 v165, 0, 32, vcc
	v_ldexp_f32 v153, v153, v165
	v_log_f32_e32 v153, v153
	s_nop 0
	v_mul_f32_e32 v165, 0x3f317217, v153
	v_fma_f32 v165, v153, s90, -v165
	v_fmac_f32_e32 v165, 0x3377d1cf, v153
	v_fmac_f32_e32 v165, 0x3f317217, v153
	v_cmp_lt_f32_e64 s[6:7], |v153|, s91
	s_nop 1
	v_cndmask_b32_e64 v153, v153, v165, s[6:7]
	v_cndmask_b32_e32 v165, 0, v222, vcc
	v_sub_f32_e32 v165, v153, v165
	v_fma_f32 v153, v50, v204, v130
	v_pk_add_f32 v[156:157], v[156:157], v[164:165] neg_lo:[0,1] neg_hi:[0,1]
	v_min_f32_e32 v164, 0, v153
	v_mul_f32_e64 v153, |v153|, s88
	v_exp_f32_e32 v153, v153
	v_pk_mul_f32 v[156:157], v[156:157], s[28:29] op_sel_hi:[1,0]
	v_add_f32_e32 v153, 1.0, v153
	v_cmp_gt_f32_e32 vcc, s89, v153
	v_cvt_pk_bf16_f32 v155, v156, v157
	s_nop 0
	v_cndmask_b32_e64 v165, 0, 32, vcc
	v_ldexp_f32 v153, v153, v165
	v_log_f32_e32 v153, v153
	s_nop 0
	v_mul_f32_e32 v165, 0x3f317217, v153
	v_fma_f32 v165, v153, s90, -v165
	v_fmac_f32_e32 v165, 0x3377d1cf, v153
	v_fmac_f32_e32 v165, 0x3f317217, v153
	v_cmp_lt_f32_e64 s[6:7], |v153|, s91
	s_nop 1
	v_cndmask_b32_e64 v153, v153, v165, s[6:7]
	v_cndmask_b32_e32 v165, 0, v222, vcc
	v_sub_f32_e32 v166, v153, v165
	v_fma_f32 v153, v51, v204, v131
	v_min_f32_e32 v165, 0, v153
	v_mul_f32_e64 v153, |v153|, s88
	v_exp_f32_e32 v153, v153
	s_nop 0
	v_add_f32_e32 v153, 1.0, v153
	v_cmp_gt_f32_e32 vcc, s89, v153
	s_nop 1
	v_cndmask_b32_e64 v167, 0, 32, vcc
	v_ldexp_f32 v153, v153, v167
	v_log_f32_e32 v153, v153
	s_nop 0
	v_mul_f32_e32 v167, 0x3f317217, v153
	v_fma_f32 v167, v153, s90, -v167
	v_fmac_f32_e32 v167, 0x3377d1cf, v153
	v_fmac_f32_e32 v167, 0x3f317217, v153
	v_cmp_lt_f32_e64 s[6:7], |v153|, s91
	s_nop 1
	v_cndmask_b32_e64 v153, v153, v167, s[6:7]
	v_cndmask_b32_e32 v167, 0, v222, vcc
	v_sub_f32_e32 v167, v153, v167
	v_fma_f32 v153, v52, v204, v132
	v_pk_add_f32 v[164:165], v[164:165], v[166:167] neg_lo:[0,1] neg_hi:[0,1]
	v_min_f32_e32 v166, 0, v153
	v_mul_f32_e64 v153, |v153|, s88
	v_exp_f32_e32 v153, v153
	v_pk_mul_f32 v[164:165], v[164:165], s[28:29] op_sel_hi:[1,0]
	v_add_f32_e32 v153, 1.0, v153
	v_cmp_gt_f32_e32 vcc, s89, v153
	v_cvt_pk_bf16_f32 v156, v164, v165
	v_fma_f32 v165, v35, v202, v131
	v_cndmask_b32_e64 v167, 0, 32, vcc
	v_ldexp_f32 v153, v153, v167
	v_log_f32_e32 v153, v153
	s_nop 0
	v_mul_f32_e32 v167, 0x3f317217, v153
	v_fma_f32 v167, v153, s90, -v167
	v_fmac_f32_e32 v167, 0x3377d1cf, v153
	v_fmac_f32_e32 v167, 0x3f317217, v153
	v_cmp_lt_f32_e64 s[6:7], |v153|, s91
	s_nop 1
	v_cndmask_b32_e64 v153, v153, v167, s[6:7]
	v_cndmask_b32_e32 v167, 0, v222, vcc
	v_sub_f32_e32 v168, v153, v167
	v_fma_f32 v153, v53, v204, v133
	v_min_f32_e32 v167, 0, v153
	v_mul_f32_e64 v153, |v153|, s88
	v_exp_f32_e32 v153, v153
	s_nop 0
	v_add_f32_e32 v153, 1.0, v153
	v_cmp_gt_f32_e32 vcc, s89, v153
	s_nop 1
	v_cndmask_b32_e64 v169, 0, 32, vcc
	v_ldexp_f32 v153, v153, v169
	v_log_f32_e32 v153, v153
	s_nop 0
	v_mul_f32_e32 v169, 0x3f317217, v153
	v_fma_f32 v169, v153, s90, -v169
	v_fmac_f32_e32 v169, 0x3377d1cf, v153
	v_fmac_f32_e32 v169, 0x3f317217, v153
	v_cmp_lt_f32_e64 s[6:7], |v153|, s91
	s_nop 1
	v_cndmask_b32_e64 v153, v153, v169, s[6:7]
	v_cndmask_b32_e32 v169, 0, v222, vcc
	v_sub_f32_e32 v169, v153, v169
	v_pk_add_f32 v[166:167], v[166:167], v[168:169] neg_lo:[0,1] neg_hi:[0,1]
	v_ashrrev_i32_e32 v153, 31, v152
	v_pk_mul_f32 v[166:167], v[166:167], s[28:29] op_sel_hi:[1,0]
	v_lshlrev_b64 v[152:153], 9, v[152:153]
	v_cvt_pk_bf16_f32 v157, v166, v167
	ds_write_b128 v160, v[146:149]
	ds_write_b128 v161, v[154:157]
	ds_read_b128 v[146:149], v163
	ds_read_b128 v[154:157], v163 offset:1024
	v_lshl_add_u64 v[152:153], s[24:25], 0, v[152:153]
	v_lshl_add_u64 v[152:153], v[152:153], 0, v[184:185]
	v_fma_f32 v167, v37, v202, v133
	s_waitcnt lgkmcnt(1)
; __device__ __forceinline__ v4u pack8(const f32x4 a, const f32x4 b) { v4u w; w.x = pk2(a[0], a[1]); w.y = pk2(a[2], a[3]); w.z = pk2(b[0], b[1]); w.w = pk2(b[2], b[3]); return w; }
; __device__ __forceinline__ float fast_exp(float x) { return __builtin_amdgcn_exp2f(x * LOG2E); }
;     __device__ __forceinline__ void operator()(const f32x4 (&acc)[2][2][4][2], const pg8::Unit& u, int wr, int wc, int fr, int fq) const {
;     ...
;                             const f32x4 z = acc[ai][bj][m][n] * rs + bg[bj][n];
; #pragma unroll
;                             for (int j = 0; j < 4; ++j) { const float az = fabsf(z[j]); r2[n][j] = (fminf(z[j], 0.f) - __logf(1.0f + fast_exp(-az))) * (1.0f / 16.0f); }
;                         }
;                         pk[bj] = pack8(r2[0], r2[1]);
;                     }
;                     v4u a, b; tt.bf(pk[0], pk[1], a, b);
;                     bf16* d = (bf16*)(ws + WS_LOGA) + (size_t)rowa * 256 + 64 * wc + 8 * tt.p; *(v4u*)d = a; *(v4u*)(d + 8 * 256) = b;
	global_store_dwordx4 v[152:153], v[146:149], off nt
	s_nop 1
	v_add_co_u32_e32 v146, vcc, s92, v152
	v_fma_f32 v149, v47, v202, v143
	s_nop 0
	v_addc_co_u32_e32 v147, vcc, 0, v153, vcc
	s_waitcnt lgkmcnt(0)
	global_store_dwordx4 v[146:147], v[154:157], off nt
	v_fma_f32 v147, v46, v202, v142
	v_min_f32_e32 v146, 0, v147
	v_mul_f32_e64 v147, |v147|, s88
	v_exp_f32_e32 v147, v147
	v_fma_f32 v153, v49, v202, v145
	v_fma_f32 v155, v43, v202, v139
	v_fma_f32 v157, v45, v202, v141
	v_add_f32_e32 v147, 1.0, v147
	v_cmp_gt_f32_e32 vcc, s89, v147
	s_nop 1
	v_cndmask_b32_e64 v148, 0, 32, vcc
	v_ldexp_f32 v147, v147, v148
	v_log_f32_e32 v147, v147
	s_nop 0
	v_mul_f32_e32 v148, 0x3f317217, v147
	v_fma_f32 v148, v147, s90, -v148
	v_fmac_f32_e32 v148, 0x3377d1cf, v147
	v_fmac_f32_e32 v148, 0x3f317217, v147
	v_cmp_lt_f32_e64 s[6:7], |v147|, s91
	s_nop 1
	v_cndmask_b32_e64 v147, v147, v148, s[6:7]
	v_cndmask_b32_e32 v148, 0, v222, vcc
	v_sub_f32_e32 v148, v147, v148
	v_min_f32_e32 v147, 0, v149
	v_mul_f32_e64 v149, |v149|, s88
	v_exp_f32_e32 v149, v149
	s_nop 0
	v_add_f32_e32 v149, 1.0, v149
	v_cmp_gt_f32_e32 vcc, s89, v149
	s_nop 1
	v_cndmask_b32_e64 v152, 0, 32, vcc
	v_ldexp_f32 v149, v149, v152
	v_log_f32_e32 v149, v149
	s_nop 0
	v_mul_f32_e32 v152, 0x3f317217, v149
	v_fma_f32 v152, v149, s90, -v152
	v_fmac_f32_e32 v152, 0x3377d1cf, v149
	v_fmac_f32_e32 v152, 0x3f317217, v149
	v_cmp_lt_f32_e64 s[6:7], |v149|, s91
	s_nop 1
	v_cndmask_b32_e64 v149, v149, v152, s[6:7]
	v_cndmask_b32_e32 v152, 0, v222, vcc
	v_sub_f32_e32 v149, v149, v152
	v_pk_add_f32 v[146:147], v[146:147], v[148:149] neg_lo:[0,1] neg_hi:[0,1]
	v_fma_f32 v149, v48, v202, v144
	v_min_f32_e32 v148, 0, v149
	v_mul_f32_e64 v149, |v149|, s88
	v_exp_f32_e32 v149, v149
	v_pk_mul_f32 v[146:147], v[146:147], s[28:29] op_sel_hi:[1,0]
	v_add_f32_e32 v149, 1.0, v149
	v_cmp_gt_f32_e32 vcc, s89, v149
	v_cvt_pk_bf16_f32 v146, v146, v147
	s_nop 0
	v_cndmask_b32_e64 v152, 0, 32, vcc
	v_ldexp_f32 v149, v149, v152
	v_log_f32_e32 v149, v149
	s_nop 0
	v_mul_f32_e32 v152, 0x3f317217, v149
	v_fma_f32 v152, v149, s90, -v152
	v_fmac_f32_e32 v152, 0x3377d1cf, v149
	v_fmac_f32_e32 v152, 0x3f317217, v149
	v_cmp_lt_f32_e64 s[6:7], |v149|, s91
	s_nop 1
	v_cndmask_b32_e64 v149, v149, v152, s[6:7]
	v_cndmask_b32_e32 v152, 0, v222, vcc
	v_sub_f32_e32 v152, v149, v152
	v_min_f32_e32 v149, 0, v153
	v_mul_f32_e64 v153, |v153|, s88
	v_exp_f32_e32 v153, v153
	s_nop 0
	v_add_f32_e32 v153, 1.0, v153
	v_cmp_gt_f32_e32 vcc, s89, v153
	s_nop 1
	v_cndmask_b32_e64 v154, 0, 32, vcc
	v_ldexp_f32 v153, v153, v154
	v_log_f32_e32 v153, v153
	s_nop 0
	v_mul_f32_e32 v154, 0x3f317217, v153
	v_fma_f32 v154, v153, s90, -v154
	v_fmac_f32_e32 v154, 0x3377d1cf, v153
	v_fmac_f32_e32 v154, 0x3f317217, v153
	v_cmp_lt_f32_e64 s[6:7], |v153|, s91
	s_nop 1
	v_cndmask_b32_e64 v153, v153, v154, s[6:7]
	v_cndmask_b32_e32 v154, 0, v222, vcc
	v_sub_f32_e32 v153, v153, v154
	v_pk_add_f32 v[148:149], v[148:149], v[152:153] neg_lo:[0,1] neg_hi:[0,1]
	v_fma_f32 v153, v42, v202, v138
	v_min_f32_e32 v152, 0, v153
	v_mul_f32_e64 v153, |v153|, s88
	v_exp_f32_e32 v153, v153
	v_pk_mul_f32 v[148:149], v[148:149], s[28:29] op_sel_hi:[1,0]
	v_add_f32_e32 v153, 1.0, v153
	v_cmp_gt_f32_e32 vcc, s89, v153
	v_cvt_pk_bf16_f32 v147, v148, v149
	s_nop 0
	v_cndmask_b32_e64 v154, 0, 32, vcc
	v_ldexp_f32 v153, v153, v154
	v_log_f32_e32 v153, v153
	s_nop 0
	v_mul_f32_e32 v154, 0x3f317217, v153
	v_fma_f32 v154, v153, s90, -v154
	v_fmac_f32_e32 v154, 0x3377d1cf, v153
	v_fmac_f32_e32 v154, 0x3f317217, v153
	v_cmp_lt_f32_e64 s[6:7], |v153|, s91
	s_nop 1
	v_cndmask_b32_e64 v153, v153, v154, s[6:7]
	v_cndmask_b32_e32 v154, 0, v222, vcc
	v_sub_f32_e32 v154, v153, v154
	v_min_f32_e32 v153, 0, v155
	v_mul_f32_e64 v155, |v155|, s88
	v_exp_f32_e32 v155, v155
	s_nop 0
	v_add_f32_e32 v155, 1.0, v155
	v_cmp_gt_f32_e32 vcc, s89, v155
	s_nop 1
	v_cndmask_b32_e64 v156, 0, 32, vcc
	v_ldexp_f32 v155, v155, v156
	v_log_f32_e32 v155, v155
	s_nop 0
	v_mul_f32_e32 v156, 0x3f317217, v155
	v_fma_f32 v156, v155, s90, -v156
	v_fmac_f32_e32 v156, 0x3377d1cf, v155
	v_fmac_f32_e32 v156, 0x3f317217, v155
	v_cmp_lt_f32_e64 s[6:7], |v155|, s91
	s_nop 1
	v_cndmask_b32_e64 v155, v155, v156, s[6:7]
	v_cndmask_b32_e32 v156, 0, v222, vcc
	v_sub_f32_e32 v155, v155, v156
	v_pk_add_f32 v[152:153], v[152:153], v[154:155] neg_lo:[0,1] neg_hi:[0,1]
	v_fma_f32 v155, v44, v202, v140
	v_min_f32_e32 v154, 0, v155
	v_mul_f32_e64 v155, |v155|, s88
	v_exp_f32_e32 v155, v155
	v_pk_mul_f32 v[152:153], v[152:153], s[28:29] op_sel_hi:[1,0]
	v_add_f32_e32 v155, 1.0, v155
	v_cmp_gt_f32_e32 vcc, s89, v155
	v_cvt_pk_bf16_f32 v148, v152, v153
	v_fma_f32 v153, v38, v202, v134
	v_cndmask_b32_e64 v156, 0, 32, vcc
	v_ldexp_f32 v155, v155, v156
	v_log_f32_e32 v155, v155
	v_min_f32_e32 v152, 0, v153
	v_mul_f32_e64 v153, |v153|, s88
	v_exp_f32_e32 v153, v153
	v_mul_f32_e32 v156, 0x3f317217, v155
	v_fma_f32 v156, v155, s90, -v156
	v_fmac_f32_e32 v156, 0x3377d1cf, v155
	v_fmac_f32_e32 v156, 0x3f317217, v155
	v_cmp_lt_f32_e64 s[6:7], |v155|, s91
	v_add_f32_e32 v153, 1.0, v153
	s_nop 0
	v_cndmask_b32_e64 v155, v155, v156, s[6:7]
	v_cndmask_b32_e32 v156, 0, v222, vcc
	v_sub_f32_e32 v156, v155, v156
	v_min_f32_e32 v155, 0, v157
	v_mul_f32_e64 v157, |v157|, s88
	v_exp_f32_e32 v157, v157
	s_nop 0
	v_add_f32_e32 v157, 1.0, v157
	v_cmp_gt_f32_e32 vcc, s89, v157
	s_nop 1
	v_cndmask_b32_e64 v164, 0, 32, vcc
	v_ldexp_f32 v157, v157, v164
	v_log_f32_e32 v157, v157
	s_nop 0
	v_mul_f32_e32 v164, 0x3f317217, v157
	v_fma_f32 v164, v157, s90, -v164
	v_fmac_f32_e32 v164, 0x3377d1cf, v157
	v_fmac_f32_e32 v164, 0x3f317217, v157
	v_cmp_lt_f32_e64 s[6:7], |v157|, s91
; __device__ __forceinline__ v4u pack8(const f32x4 a, const f32x4 b) { v4u w; w.x = pk2(a[0], a[1]); w.y = pk2(a[2], a[3]); w.z = pk2(b[0], b[1]); w.w = pk2(b[2], b[3]); return w; }
; __device__ __forceinline__ float fast_exp(float x) { return __builtin_amdgcn_exp2f(x * LOG2E); }
;     __device__ __forceinline__ void operator()(const f32x4 (&acc)[2][2][4][2], const pg8::Unit& u, int wr, int wc, int fr, int fq) const {
;     ...
;                             const f32x4 z = acc[ai][bj][m][n] * rs + bg[bj][n];
; #pragma unroll
;                             for (int j = 0; j < 4; ++j) { const float az = fabsf(z[j]); r2[n][j] = (fminf(z[j], 0.f) - __logf(1.0f + fast_exp(-az))) * (1.0f / 16.0f); }
;                         }
;                         pk[bj] = pack8(r2[0], r2[1]);
;                     }
;                     v4u a, b; tt.bf(pk[0], pk[1], a, b);
;                     bf16* d = (bf16*)(ws + WS_LOGA) + (size_t)rowa * 256 + 64 * wc + 8 * tt.p; *(v4u*)d = a; *(v4u*)(d + 8 * 256) = b;
	s_nop 1
	v_cndmask_b32_e64 v157, v157, v164, s[6:7]
	v_cndmask_b32_e32 v164, 0, v222, vcc
	v_sub_f32_e32 v157, v157, v164
	v_pk_add_f32 v[154:155], v[154:155], v[156:157] neg_lo:[0,1] neg_hi:[0,1]
	v_cmp_gt_f32_e32 vcc, s89, v153
	v_pk_mul_f32 v[154:155], v[154:155], s[28:29] op_sel_hi:[1,0]
	v_fma_f32 v157, v41, v202, v137
	v_cvt_pk_bf16_f32 v149, v154, v155
	v_cndmask_b32_e64 v154, 0, 32, vcc
	v_ldexp_f32 v153, v153, v154
	v_log_f32_e32 v153, v153
	v_fma_f32 v155, v39, v202, v135
	v_mul_f32_e32 v154, 0x3f317217, v153
	v_fma_f32 v154, v153, s90, -v154
	v_fmac_f32_e32 v154, 0x3377d1cf, v153
	v_fmac_f32_e32 v154, 0x3f317217, v153
	v_cmp_lt_f32_e64 s[6:7], |v153|, s91
	s_nop 1
	v_cndmask_b32_e64 v153, v153, v154, s[6:7]
	v_cndmask_b32_e32 v154, 0, v222, vcc
	v_sub_f32_e32 v154, v153, v154
	v_min_f32_e32 v153, 0, v155
	v_mul_f32_e64 v155, |v155|, s88
	v_exp_f32_e32 v155, v155
	s_nop 0
	v_add_f32_e32 v155, 1.0, v155
	v_cmp_gt_f32_e32 vcc, s89, v155
	s_nop 1
	v_cndmask_b32_e64 v156, 0, 32, vcc
	v_ldexp_f32 v155, v155, v156
	v_log_f32_e32 v155, v155
	s_nop 0
	v_mul_f32_e32 v156, 0x3f317217, v155
	v_fma_f32 v156, v155, s90, -v156
	v_fmac_f32_e32 v156, 0x3377d1cf, v155
	v_fmac_f32_e32 v156, 0x3f317217, v155
	v_cmp_lt_f32_e64 s[6:7], |v155|, s91
	s_nop 1
	v_cndmask_b32_e64 v155, v155, v156, s[6:7]
	v_cndmask_b32_e32 v156, 0, v222, vcc
	v_sub_f32_e32 v155, v155, v156
	v_pk_add_f32 v[152:153], v[152:153], v[154:155] neg_lo:[0,1] neg_hi:[0,1]
	v_fma_f32 v155, v40, v202, v136
	v_min_f32_e32 v154, 0, v155
	v_mul_f32_e64 v155, |v155|, s88
	v_exp_f32_e32 v155, v155
	v_pk_mul_f32 v[152:153], v[152:153], s[28:29] op_sel_hi:[1,0]
	v_add_f32_e32 v155, 1.0, v155
	v_cmp_gt_f32_e32 vcc, s89, v155
	v_cvt_pk_bf16_f32 v152, v152, v153
	s_nop 0
	v_cndmask_b32_e64 v156, 0, 32, vcc
	v_ldexp_f32 v155, v155, v156
	v_log_f32_e32 v155, v155
	s_nop 0
	v_mul_f32_e32 v156, 0x3f317217, v155
	v_fma_f32 v156, v155, s90, -v156
	v_fmac_f32_e32 v156, 0x3377d1cf, v155
	v_fmac_f32_e32 v156, 0x3f317217, v155
	v_cmp_lt_f32_e64 s[6:7], |v155|, s91
	s_nop 1
	v_cndmask_b32_e64 v155, v155, v156, s[6:7]
	v_cndmask_b32_e32 v156, 0, v222, vcc
	v_sub_f32_e32 v156, v155, v156
	v_min_f32_e32 v155, 0, v157
	v_mul_f32_e64 v157, |v157|, s88
	v_exp_f32_e32 v157, v157
	s_nop 0
	v_add_f32_e32 v157, 1.0, v157
	v_cmp_gt_f32_e32 vcc, s89, v157
	s_nop 1
	v_cndmask_b32_e64 v164, 0, 32, vcc
	v_ldexp_f32 v157, v157, v164
	v_log_f32_e32 v157, v157
	s_nop 0
	v_mul_f32_e32 v164, 0x3f317217, v157
	v_fma_f32 v164, v157, s90, -v164
	v_fmac_f32_e32 v164, 0x3377d1cf, v157
	v_fmac_f32_e32 v164, 0x3f317217, v157
	v_cmp_lt_f32_e64 s[6:7], |v157|, s91
	s_nop 1
	v_cndmask_b32_e64 v157, v157, v164, s[6:7]
	v_cndmask_b32_e32 v164, 0, v222, vcc
	v_sub_f32_e32 v157, v157, v164
	v_pk_add_f32 v[154:155], v[154:155], v[156:157] neg_lo:[0,1] neg_hi:[0,1]
	v_fma_f32 v157, v34, v202, v130
	v_min_f32_e32 v156, 0, v157
	v_mul_f32_e64 v157, |v157|, s88
	v_exp_f32_e32 v157, v157
	v_pk_mul_f32 v[154:155], v[154:155], s[28:29] op_sel_hi:[1,0]
	v_add_f32_e32 v157, 1.0, v157
	v_cmp_gt_f32_e32 vcc, s89, v157
	v_cvt_pk_bf16_f32 v153, v154, v155
	s_nop 0
	v_cndmask_b32_e64 v164, 0, 32, vcc
	v_ldexp_f32 v157, v157, v164
	v_log_f32_e32 v157, v157
	s_nop 0
	v_mul_f32_e32 v164, 0x3f317217, v157
	v_fma_f32 v164, v157, s90, -v164
	v_fmac_f32_e32 v164, 0x3377d1cf, v157
	v_fmac_f32_e32 v164, 0x3f317217, v157
	v_cmp_lt_f32_e64 s[6:7], |v157|, s91
	s_nop 1
	v_cndmask_b32_e64 v157, v157, v164, s[6:7]
	v_cndmask_b32_e32 v164, 0, v222, vcc
	v_sub_f32_e32 v164, v157, v164
	v_min_f32_e32 v157, 0, v165
	v_mul_f32_e64 v165, |v165|, s88
	v_exp_f32_e32 v165, v165
	s_nop 0
	v_add_f32_e32 v165, 1.0, v165
	v_cmp_gt_f32_e32 vcc, s89, v165
	s_nop 1
	v_cndmask_b32_e64 v166, 0, 32, vcc
	v_ldexp_f32 v165, v165, v166
	v_log_f32_e32 v165, v165
	s_nop 0
	v_mul_f32_e32 v166, 0x3f317217, v165
	v_fma_f32 v166, v165, s90, -v166
	v_fmac_f32_e32 v166, 0x3377d1cf, v165
	v_fmac_f32_e32 v166, 0x3f317217, v165
	v_cmp_lt_f32_e64 s[6:7], |v165|, s91
	s_nop 1
	v_cndmask_b32_e64 v165, v165, v166, s[6:7]
	v_cndmask_b32_e32 v166, 0, v222, vcc
	v_sub_f32_e32 v165, v165, v166
	v_pk_add_f32 v[156:157], v[156:157], v[164:165] neg_lo:[0,1] neg_hi:[0,1]
	v_fma_f32 v165, v36, v202, v132
	v_min_f32_e32 v164, 0, v165
	v_mul_f32_e64 v165, |v165|, s88
	v_exp_f32_e32 v165, v165
	v_pk_mul_f32 v[156:157], v[156:157], s[28:29] op_sel_hi:[1,0]
	v_add_f32_e32 v165, 1.0, v165
	v_cmp_gt_f32_e32 vcc, s89, v165
	v_cvt_pk_bf16_f32 v154, v156, v157
	v_add_u32_e32 v156, 0x90, v150
	v_cndmask_b32_e64 v166, 0, 32, vcc
	v_ldexp_f32 v165, v165, v166
	v_log_f32_e32 v165, v165
	v_ashrrev_i32_e32 v157, 31, v156
	v_lshlrev_b64 v[156:157], 9, v[156:157]
	v_lshl_add_u64 v[156:157], s[24:25], 0, v[156:157]
	v_mul_f32_e32 v166, 0x3f317217, v165
	v_fma_f32 v166, v165, s90, -v166
	v_fmac_f32_e32 v166, 0x3377d1cf, v165
	v_fmac_f32_e32 v166, 0x3f317217, v165
	v_cmp_lt_f32_e64 s[6:7], |v165|, s91
	v_lshl_add_u64 v[156:157], v[156:157], 0, v[184:185]
	s_nop 0
	v_cndmask_b32_e64 v165, v165, v166, s[6:7]
	v_cndmask_b32_e32 v166, 0, v222, vcc
	v_sub_f32_e32 v166, v165, v166
	v_min_f32_e32 v165, 0, v167
	v_mul_f32_e64 v167, |v167|, s88
	v_exp_f32_e32 v167, v167
	s_nop 0
	v_add_f32_e32 v167, 1.0, v167
	v_cmp_gt_f32_e32 vcc, s89, v167
	s_nop 1
	v_cndmask_b32_e64 v168, 0, 32, vcc
	v_ldexp_f32 v167, v167, v168
	v_log_f32_e32 v167, v167
	s_nop 0
	v_mul_f32_e32 v168, 0x3f317217, v167
	v_fma_f32 v168, v167, s90, -v168
	v_fmac_f32_e32 v168, 0x3377d1cf, v167
	v_fmac_f32_e32 v168, 0x3f317217, v167
	v_cmp_lt_f32_e64 s[6:7], |v167|, s91
	s_nop 1
	v_cndmask_b32_e64 v167, v167, v168, s[6:7]
	v_cndmask_b32_e32 v168, 0, v222, vcc
	v_sub_f32_e32 v167, v167, v168
	v_pk_add_f32 v[164:165], v[164:165], v[166:167] neg_lo:[0,1] neg_hi:[0,1]
	v_fma_f32 v167, v21, v198, v133
	v_pk_mul_f32 v[164:165], v[164:165], s[28:29] op_sel_hi:[1,0]
	v_fmac_f32_e32 v133, v5, v196
	v_cvt_pk_bf16_f32 v155, v164, v165
	ds_write_b128 v160, v[146:149]
	ds_write_b128 v161, v[152:155]
	ds_read_b128 v[146:149], v163
	ds_read_b128 v[152:155], v163 offset:1024
	v_fma_f32 v165, v19, v198, v131
	s_waitcnt lgkmcnt(1)
; __device__ __forceinline__ v4u pack8(const f32x4 a, const f32x4 b) { v4u w; w.x = pk2(a[0], a[1]); w.y = pk2(a[2], a[3]); w.z = pk2(b[0], b[1]); w.w = pk2(b[2], b[3]); return w; }
; __device__ __forceinline__ float fast_exp(float x) { return __builtin_amdgcn_exp2f(x * LOG2E); }
;     __device__ __forceinline__ void operator()(const f32x4 (&acc)[2][2][4][2], const pg8::Unit& u, int wr, int wc, int fr, int fq) const {
;     ...
;                             const f32x4 z = acc[ai][bj][m][n] * rs + bg[bj][n];
; #pragma unroll
;                             for (int j = 0; j < 4; ++j) { const float az = fabsf(z[j]); r2[n][j] = (fminf(z[j], 0.f) - __logf(1.0f + fast_exp(-az))) * (1.0f / 16.0f); }
;                         }
;                         pk[bj] = pack8(r2[0], r2[1]);
;                     }
;                     v4u a, b; tt.bf(pk[0], pk[1], a, b);
;                     bf16* d = (bf16*)(ws + WS_LOGA) + (size_t)rowa * 256 + 64 * wc + 8 * tt.p; *(v4u*)d = a; *(v4u*)(d + 8 * 256) = b;
	global_store_dwordx4 v[156:157], v[146:149], off nt
	s_nop 1
	v_add_co_u32_e32 v146, vcc, s92, v156
	v_fma_f32 v149, v31, v198, v143
	s_nop 0
	v_addc_co_u32_e32 v147, vcc, 0, v157, vcc
	s_waitcnt lgkmcnt(0)
	global_store_dwordx4 v[146:147], v[152:155], off nt
	v_fma_f32 v147, v30, v198, v142
	v_min_f32_e32 v146, 0, v147
	v_mul_f32_e64 v147, |v147|, s88
	v_exp_f32_e32 v147, v147
	v_fma_f32 v153, v33, v198, v145
	v_fma_f32 v155, v27, v198, v139
	v_fma_f32 v157, v29, v198, v141
	v_add_f32_e32 v147, 1.0, v147
	v_cmp_gt_f32_e32 vcc, s89, v147
	v_fmac_f32_e32 v145, v17, v196
	v_fmac_f32_e32 v141, v13, v196
	v_cndmask_b32_e64 v148, 0, 32, vcc
	v_ldexp_f32 v147, v147, v148
	v_log_f32_e32 v147, v147
	s_nop 0
	v_mul_f32_e32 v148, 0x3f317217, v147
	v_fma_f32 v148, v147, s90, -v148
	v_fmac_f32_e32 v148, 0x3377d1cf, v147
	v_fmac_f32_e32 v148, 0x3f317217, v147
	v_cmp_lt_f32_e64 s[6:7], |v147|, s91
	s_nop 1
	v_cndmask_b32_e64 v147, v147, v148, s[6:7]
	v_cndmask_b32_e32 v148, 0, v222, vcc
	v_sub_f32_e32 v148, v147, v148
	v_min_f32_e32 v147, 0, v149
	v_mul_f32_e64 v149, |v149|, s88
	v_exp_f32_e32 v149, v149
	s_nop 0
	v_add_f32_e32 v149, 1.0, v149
	v_cmp_gt_f32_e32 vcc, s89, v149
	s_nop 1
	v_cndmask_b32_e64 v152, 0, 32, vcc
	v_ldexp_f32 v149, v149, v152
	v_log_f32_e32 v149, v149
	s_nop 0
	v_mul_f32_e32 v152, 0x3f317217, v149
	v_fma_f32 v152, v149, s90, -v152
	v_fmac_f32_e32 v152, 0x3377d1cf, v149
	v_fmac_f32_e32 v152, 0x3f317217, v149
	v_cmp_lt_f32_e64 s[6:7], |v149|, s91
	s_nop 1
	v_cndmask_b32_e64 v149, v149, v152, s[6:7]
	v_cndmask_b32_e32 v152, 0, v222, vcc
	v_sub_f32_e32 v149, v149, v152
	v_pk_add_f32 v[146:147], v[146:147], v[148:149] neg_lo:[0,1] neg_hi:[0,1]
	v_fma_f32 v149, v32, v198, v144
	v_min_f32_e32 v148, 0, v149
	v_mul_f32_e64 v149, |v149|, s88
	v_exp_f32_e32 v149, v149
	v_pk_mul_f32 v[146:147], v[146:147], s[28:29] op_sel_hi:[1,0]
	v_fma_f32 v144, v16, v196, v144
	v_cvt_pk_bf16_f32 v146, v146, v147
	v_add_f32_e32 v149, 1.0, v149
	v_cmp_gt_f32_e32 vcc, s89, v149
	s_nop 1
	v_cndmask_b32_e64 v152, 0, 32, vcc
	v_ldexp_f32 v149, v149, v152
	v_log_f32_e32 v149, v149
	s_nop 0
	v_mul_f32_e32 v152, 0x3f317217, v149
	v_fma_f32 v152, v149, s90, -v152
	v_fmac_f32_e32 v152, 0x3377d1cf, v149
	v_fmac_f32_e32 v152, 0x3f317217, v149
	v_cmp_lt_f32_e64 s[6:7], |v149|, s91
	s_nop 1
	v_cndmask_b32_e64 v149, v149, v152, s[6:7]
	v_cndmask_b32_e32 v152, 0, v222, vcc
	v_sub_f32_e32 v152, v149, v152
	v_min_f32_e32 v149, 0, v153
	v_mul_f32_e64 v153, |v153|, s88
	v_exp_f32_e32 v153, v153
	s_nop 0
	v_add_f32_e32 v153, 1.0, v153
	v_cmp_gt_f32_e32 vcc, s89, v153
	s_nop 1
	v_cndmask_b32_e64 v154, 0, 32, vcc
	v_ldexp_f32 v153, v153, v154
	v_log_f32_e32 v153, v153
	s_nop 0
	v_mul_f32_e32 v154, 0x3f317217, v153
	v_fma_f32 v154, v153, s90, -v154
	v_fmac_f32_e32 v154, 0x3377d1cf, v153
	v_fmac_f32_e32 v154, 0x3f317217, v153
	v_cmp_lt_f32_e64 s[6:7], |v153|, s91
	s_nop 1
	v_cndmask_b32_e64 v153, v153, v154, s[6:7]
	v_cndmask_b32_e32 v154, 0, v222, vcc
	v_sub_f32_e32 v153, v153, v154
	v_pk_add_f32 v[148:149], v[148:149], v[152:153] neg_lo:[0,1] neg_hi:[0,1]
	v_fma_f32 v153, v26, v198, v138
	v_min_f32_e32 v152, 0, v153
	v_mul_f32_e64 v153, |v153|, s88
	v_exp_f32_e32 v153, v153
	v_pk_mul_f32 v[148:149], v[148:149], s[28:29] op_sel_hi:[1,0]
	v_add_f32_e32 v153, 1.0, v153
	v_cmp_gt_f32_e32 vcc, s89, v153
	v_cvt_pk_bf16_f32 v147, v148, v149
	s_nop 0
	v_cndmask_b32_e64 v154, 0, 32, vcc
	v_ldexp_f32 v153, v153, v154
	v_log_f32_e32 v153, v153
	s_nop 0
	v_mul_f32_e32 v154, 0x3f317217, v153
	v_fma_f32 v154, v153, s90, -v154
	v_fmac_f32_e32 v154, 0x3377d1cf, v153
	v_fmac_f32_e32 v154, 0x3f317217, v153
	v_cmp_lt_f32_e64 s[6:7], |v153|, s91
	s_nop 1
	v_cndmask_b32_e64 v153, v153, v154, s[6:7]
	v_cndmask_b32_e32 v154, 0, v222, vcc
	v_sub_f32_e32 v154, v153, v154
	v_min_f32_e32 v153, 0, v155
	v_mul_f32_e64 v155, |v155|, s88
	v_exp_f32_e32 v155, v155
	s_nop 0
	v_add_f32_e32 v155, 1.0, v155
	v_cmp_gt_f32_e32 vcc, s89, v155
	s_nop 1
	v_cndmask_b32_e64 v156, 0, 32, vcc
	v_ldexp_f32 v155, v155, v156
	v_log_f32_e32 v155, v155
	s_nop 0
	v_mul_f32_e32 v156, 0x3f317217, v155
	v_fma_f32 v156, v155, s90, -v156
	v_fmac_f32_e32 v156, 0x3377d1cf, v155
	v_fmac_f32_e32 v156, 0x3f317217, v155
	v_cmp_lt_f32_e64 s[6:7], |v155|, s91
	s_nop 1
	v_cndmask_b32_e64 v155, v155, v156, s[6:7]
	v_cndmask_b32_e32 v156, 0, v222, vcc
	v_sub_f32_e32 v155, v155, v156
	v_pk_add_f32 v[152:153], v[152:153], v[154:155] neg_lo:[0,1] neg_hi:[0,1]
	v_fma_f32 v155, v28, v198, v140
	v_min_f32_e32 v154, 0, v155
	v_mul_f32_e64 v155, |v155|, s88
	v_exp_f32_e32 v155, v155
	v_pk_mul_f32 v[152:153], v[152:153], s[28:29] op_sel_hi:[1,0]
	v_add_f32_e32 v155, 1.0, v155
	v_cmp_gt_f32_e32 vcc, s89, v155
	v_cvt_pk_bf16_f32 v148, v152, v153
	v_fma_f32 v153, v22, v198, v134
	v_cndmask_b32_e64 v156, 0, 32, vcc
	v_ldexp_f32 v155, v155, v156
	v_log_f32_e32 v155, v155
	v_min_f32_e32 v152, 0, v153
	v_mul_f32_e64 v153, |v153|, s88
	v_exp_f32_e32 v153, v153
	v_mul_f32_e32 v156, 0x3f317217, v155
	v_fma_f32 v156, v155, s90, -v156
	v_fmac_f32_e32 v156, 0x3377d1cf, v155
	v_fmac_f32_e32 v156, 0x3f317217, v155
	v_cmp_lt_f32_e64 s[6:7], |v155|, s91
	v_add_f32_e32 v153, 1.0, v153
	s_nop 0
	v_cndmask_b32_e64 v155, v155, v156, s[6:7]
	v_cndmask_b32_e32 v156, 0, v222, vcc
	v_sub_f32_e32 v156, v155, v156
	v_min_f32_e32 v155, 0, v157
	v_mul_f32_e64 v157, |v157|, s88
	v_exp_f32_e32 v157, v157
	s_nop 0
	v_add_f32_e32 v157, 1.0, v157
	v_cmp_gt_f32_e32 vcc, s89, v157
	s_nop 1
	v_cndmask_b32_e64 v164, 0, 32, vcc
	v_ldexp_f32 v157, v157, v164
	v_log_f32_e32 v157, v157
	s_nop 0
	v_mul_f32_e32 v164, 0x3f317217, v157
	v_fma_f32 v164, v157, s90, -v164
	v_fmac_f32_e32 v164, 0x3377d1cf, v157
; __device__ __forceinline__ v4u pack8(const f32x4 a, const f32x4 b) { v4u w; w.x = pk2(a[0], a[1]); w.y = pk2(a[2], a[3]); w.z = pk2(b[0], b[1]); w.w = pk2(b[2], b[3]); return w; }
; __device__ __forceinline__ float fast_exp(float x) { return __builtin_amdgcn_exp2f(x * LOG2E); }
;     __device__ __forceinline__ void operator()(const f32x4 (&acc)[2][2][4][2], const pg8::Unit& u, int wr, int wc, int fr, int fq) const {
;     ...
;                             const f32x4 z = acc[ai][bj][m][n] * rs + bg[bj][n];
; #pragma unroll
;                             for (int j = 0; j < 4; ++j) { const float az = fabsf(z[j]); r2[n][j] = (fminf(z[j], 0.f) - __logf(1.0f + fast_exp(-az))) * (1.0f / 16.0f); }
;                         }
;                         pk[bj] = pack8(r2[0], r2[1]);
;                     }
;                     v4u a, b; tt.bf(pk[0], pk[1], a, b);
;                     bf16* d = (bf16*)(ws + WS_LOGA) + (size_t)rowa * 256 + 64 * wc + 8 * tt.p; *(v4u*)d = a; *(v4u*)(d + 8 * 256) = b;
	v_fmac_f32_e32 v164, 0x3f317217, v157
	v_cmp_lt_f32_e64 s[6:7], |v157|, s91
	s_nop 1
	v_cndmask_b32_e64 v157, v157, v164, s[6:7]
	v_cndmask_b32_e32 v164, 0, v222, vcc
	v_sub_f32_e32 v157, v157, v164
	v_pk_add_f32 v[154:155], v[154:155], v[156:157] neg_lo:[0,1] neg_hi:[0,1]
	v_cmp_gt_f32_e32 vcc, s89, v153
	v_pk_mul_f32 v[154:155], v[154:155], s[28:29] op_sel_hi:[1,0]
	v_fma_f32 v157, v25, v198, v137
	v_cvt_pk_bf16_f32 v149, v154, v155
	v_cndmask_b32_e64 v154, 0, 32, vcc
	v_ldexp_f32 v153, v153, v154
	v_log_f32_e32 v153, v153
	v_fma_f32 v155, v23, v198, v135
	v_fmac_f32_e32 v137, v9, v196
	v_mul_f32_e32 v154, 0x3f317217, v153
	v_fma_f32 v154, v153, s90, -v154
	v_fmac_f32_e32 v154, 0x3377d1cf, v153
	v_fmac_f32_e32 v154, 0x3f317217, v153
	v_cmp_lt_f32_e64 s[6:7], |v153|, s91
	s_nop 1
	v_cndmask_b32_e64 v153, v153, v154, s[6:7]
	v_cndmask_b32_e32 v154, 0, v222, vcc
	v_sub_f32_e32 v154, v153, v154
	v_min_f32_e32 v153, 0, v155
	v_mul_f32_e64 v155, |v155|, s88
	v_exp_f32_e32 v155, v155
	s_nop 0
	v_add_f32_e32 v155, 1.0, v155
	v_cmp_gt_f32_e32 vcc, s89, v155
	s_nop 1
	v_cndmask_b32_e64 v156, 0, 32, vcc
	v_ldexp_f32 v155, v155, v156
	v_log_f32_e32 v155, v155
	s_nop 0
	v_mul_f32_e32 v156, 0x3f317217, v155
	v_fma_f32 v156, v155, s90, -v156
	v_fmac_f32_e32 v156, 0x3377d1cf, v155
	v_fmac_f32_e32 v156, 0x3f317217, v155
	v_cmp_lt_f32_e64 s[6:7], |v155|, s91
	s_nop 1
	v_cndmask_b32_e64 v155, v155, v156, s[6:7]
	v_cndmask_b32_e32 v156, 0, v222, vcc
	v_sub_f32_e32 v155, v155, v156
	v_pk_add_f32 v[152:153], v[152:153], v[154:155] neg_lo:[0,1] neg_hi:[0,1]
	v_fma_f32 v155, v24, v198, v136
	v_min_f32_e32 v154, 0, v155
	v_mul_f32_e64 v155, |v155|, s88
	v_exp_f32_e32 v155, v155
	v_pk_mul_f32 v[152:153], v[152:153], s[28:29] op_sel_hi:[1,0]
	v_fma_f32 v136, v8, v196, v136
	v_cvt_pk_bf16_f32 v152, v152, v153
	v_add_f32_e32 v155, 1.0, v155
	v_cmp_gt_f32_e32 vcc, s89, v155
	s_nop 1
	v_cndmask_b32_e64 v156, 0, 32, vcc
	v_ldexp_f32 v155, v155, v156
	v_log_f32_e32 v155, v155
	s_nop 0
	v_mul_f32_e32 v156, 0x3f317217, v155
	v_fma_f32 v156, v155, s90, -v156
	v_fmac_f32_e32 v156, 0x3377d1cf, v155
	v_fmac_f32_e32 v156, 0x3f317217, v155
	v_cmp_lt_f32_e64 s[6:7], |v155|, s91
	s_nop 1
	v_cndmask_b32_e64 v155, v155, v156, s[6:7]
	v_cndmask_b32_e32 v156, 0, v222, vcc
	v_sub_f32_e32 v156, v155, v156
	v_min_f32_e32 v155, 0, v157
	v_mul_f32_e64 v157, |v157|, s88
	v_exp_f32_e32 v157, v157
	s_nop 0
	v_add_f32_e32 v157, 1.0, v157
	v_cmp_gt_f32_e32 vcc, s89, v157
	s_nop 1
	v_cndmask_b32_e64 v164, 0, 32, vcc
	v_ldexp_f32 v157, v157, v164
	v_log_f32_e32 v157, v157
	s_nop 0
	v_mul_f32_e32 v164, 0x3f317217, v157
	v_fma_f32 v164, v157, s90, -v164
	v_fmac_f32_e32 v164, 0x3377d1cf, v157
	v_fmac_f32_e32 v164, 0x3f317217, v157
	v_cmp_lt_f32_e64 s[6:7], |v157|, s91
	s_nop 1
	v_cndmask_b32_e64 v157, v157, v164, s[6:7]
	v_cndmask_b32_e32 v164, 0, v222, vcc
	v_sub_f32_e32 v157, v157, v164
	v_pk_add_f32 v[154:155], v[154:155], v[156:157] neg_lo:[0,1] neg_hi:[0,1]
	v_fma_f32 v157, v18, v198, v130
	v_min_f32_e32 v156, 0, v157
	v_mul_f32_e64 v157, |v157|, s88
	v_exp_f32_e32 v157, v157
	v_pk_mul_f32 v[154:155], v[154:155], s[28:29] op_sel_hi:[1,0]
	v_add_f32_e32 v157, 1.0, v157
	v_cmp_gt_f32_e32 vcc, s89, v157
	v_cvt_pk_bf16_f32 v153, v154, v155
	s_nop 0
	v_cndmask_b32_e64 v164, 0, 32, vcc
	v_ldexp_f32 v157, v157, v164
	v_log_f32_e32 v157, v157
	s_nop 0
	v_mul_f32_e32 v164, 0x3f317217, v157
	v_fma_f32 v164, v157, s90, -v164
	v_fmac_f32_e32 v164, 0x3377d1cf, v157
	v_fmac_f32_e32 v164, 0x3f317217, v157
	v_cmp_lt_f32_e64 s[6:7], |v157|, s91
	s_nop 1
	v_cndmask_b32_e64 v157, v157, v164, s[6:7]
	v_cndmask_b32_e32 v164, 0, v222, vcc
	v_sub_f32_e32 v164, v157, v164
	v_min_f32_e32 v157, 0, v165
	v_mul_f32_e64 v165, |v165|, s88
	v_exp_f32_e32 v165, v165
	s_nop 0
	v_add_f32_e32 v165, 1.0, v165
	v_cmp_gt_f32_e32 vcc, s89, v165
	s_nop 1
	v_cndmask_b32_e64 v166, 0, 32, vcc
	v_ldexp_f32 v165, v165, v166
	v_log_f32_e32 v165, v165
	s_nop 0
	v_mul_f32_e32 v166, 0x3f317217, v165
	v_fma_f32 v166, v165, s90, -v166
	v_fmac_f32_e32 v166, 0x3377d1cf, v165
	v_fmac_f32_e32 v166, 0x3f317217, v165
	v_cmp_lt_f32_e64 s[6:7], |v165|, s91
	s_nop 1
	v_cndmask_b32_e64 v165, v165, v166, s[6:7]
	v_cndmask_b32_e32 v166, 0, v222, vcc
	v_sub_f32_e32 v165, v165, v166
	v_pk_add_f32 v[156:157], v[156:157], v[164:165] neg_lo:[0,1] neg_hi:[0,1]
	v_fma_f32 v165, v20, v198, v132
	v_min_f32_e32 v164, 0, v165
	v_mul_f32_e64 v165, |v165|, s88
	v_exp_f32_e32 v165, v165
	v_pk_mul_f32 v[156:157], v[156:157], s[28:29] op_sel_hi:[1,0]
	v_add_f32_e32 v165, 1.0, v165
	v_cmp_gt_f32_e32 vcc, s89, v165
	v_cvt_pk_bf16_f32 v154, v156, v157
	v_add_u32_e32 v156, 0xa0, v150
	v_cndmask_b32_e64 v166, 0, 32, vcc
	v_ldexp_f32 v165, v165, v166
	v_log_f32_e32 v165, v165
	v_ashrrev_i32_e32 v157, 31, v156
	v_lshlrev_b64 v[156:157], 9, v[156:157]
	v_lshl_add_u64 v[156:157], s[24:25], 0, v[156:157]
	v_mul_f32_e32 v166, 0x3f317217, v165
	v_fma_f32 v166, v165, s90, -v166
	v_fmac_f32_e32 v166, 0x3377d1cf, v165
	v_fmac_f32_e32 v166, 0x3f317217, v165
	v_cmp_lt_f32_e64 s[6:7], |v165|, s91
	v_lshl_add_u64 v[156:157], v[156:157], 0, v[184:185]
	s_nop 0
	v_cndmask_b32_e64 v165, v165, v166, s[6:7]
	v_cndmask_b32_e32 v166, 0, v222, vcc
	v_sub_f32_e32 v166, v165, v166
	v_min_f32_e32 v165, 0, v167
	v_mul_f32_e64 v167, |v167|, s88
	v_exp_f32_e32 v167, v167
	s_nop 0
	v_add_f32_e32 v167, 1.0, v167
	v_cmp_gt_f32_e32 vcc, s89, v167
	s_nop 1
	v_cndmask_b32_e64 v168, 0, 32, vcc
	v_ldexp_f32 v167, v167, v168
	v_log_f32_e32 v167, v167
	s_nop 0
	v_mul_f32_e32 v168, 0x3f317217, v167
	v_fma_f32 v168, v167, s90, -v168
	v_fmac_f32_e32 v168, 0x3377d1cf, v167
	v_fmac_f32_e32 v168, 0x3f317217, v167
	v_cmp_lt_f32_e64 s[6:7], |v167|, s91
	s_nop 1
	v_cndmask_b32_e64 v167, v167, v168, s[6:7]
	v_cndmask_b32_e32 v168, 0, v222, vcc
	v_sub_f32_e32 v167, v167, v168
	v_pk_add_f32 v[164:165], v[164:165], v[166:167] neg_lo:[0,1] neg_hi:[0,1]
	s_nop 0
	v_pk_mul_f32 v[164:165], v[164:165], s[28:29] op_sel_hi:[1,0]
	s_nop 0
	v_cvt_pk_bf16_f32 v155, v164, v165
	ds_write_b128 v160, v[146:149]
	ds_write_b128 v161, v[152:155]
	ds_read_b128 v[146:149], v163
	ds_read_b128 v[152:155], v163 offset:1024
	s_waitcnt lgkmcnt(1)
; __device__ __forceinline__ v4u pack8(const f32x4 a, const f32x4 b) { v4u w; w.x = pk2(a[0], a[1]); w.y = pk2(a[2], a[3]); w.z = pk2(b[0], b[1]); w.w = pk2(b[2], b[3]); return w; }
; __device__ __forceinline__ float fast_exp(float x) { return __builtin_amdgcn_exp2f(x * LOG2E); }
;     __device__ __forceinline__ void operator()(const f32x4 (&acc)[2][2][4][2], const pg8::Unit& u, int wr, int wc, int fr, int fq) const {
;     ...
;                             const f32x4 z = acc[ai][bj][m][n] * rs + bg[bj][n];
; #pragma unroll
;                             for (int j = 0; j < 4; ++j) { const float az = fabsf(z[j]); r2[n][j] = (fminf(z[j], 0.f) - __logf(1.0f + fast_exp(-az))) * (1.0f / 16.0f); }
;                         }
;                         pk[bj] = pack8(r2[0], r2[1]);
;                     }
;                     v4u a, b; tt.bf(pk[0], pk[1], a, b);
;                     bf16* d = (bf16*)(ws + WS_LOGA) + (size_t)rowa * 256 + 64 * wc + 8 * tt.p; *(v4u*)d = a; *(v4u*)(d + 8 * 256) = b;
	global_store_dwordx4 v[156:157], v[146:149], off nt
	s_nop 1
	v_add_co_u32_e32 v146, vcc, s92, v156
	s_nop 1
	v_addc_co_u32_e32 v147, vcc, 0, v157, vcc
	s_waitcnt lgkmcnt(0)
	global_store_dwordx4 v[146:147], v[152:155], off nt
	v_fma_f32 v146, v14, v196, v142
	v_min_f32_e32 v142, 0, v146
	v_mul_f32_e64 v146, |v146|, s88
	v_exp_f32_e32 v146, v146
	s_nop 0
	v_add_f32_e32 v146, 1.0, v146
	v_cmp_gt_f32_e32 vcc, s89, v146
	s_nop 1
	v_cndmask_b32_e64 v147, 0, 32, vcc
	v_ldexp_f32 v146, v146, v147
	v_log_f32_e32 v146, v146
	s_nop 0
	v_mul_f32_e32 v147, 0x3f317217, v146
	v_fma_f32 v147, v146, s90, -v147
	v_fmac_f32_e32 v147, 0x3377d1cf, v146
	v_fmac_f32_e32 v147, 0x3f317217, v146
	v_cmp_lt_f32_e64 s[6:7], |v146|, s91
	s_nop 1
	v_cndmask_b32_e64 v146, v146, v147, s[6:7]
	v_cndmask_b32_e32 v147, 0, v222, vcc
	v_sub_f32_e32 v146, v146, v147
	v_fma_f32 v147, v15, v196, v143
	v_min_f32_e32 v143, 0, v147
	v_mul_f32_e64 v147, |v147|, s88
	v_exp_f32_e32 v147, v147
	s_nop 0
	v_add_f32_e32 v147, 1.0, v147
	v_cmp_gt_f32_e32 vcc, s89, v147
	s_nop 1
	v_cndmask_b32_e64 v148, 0, 32, vcc
	v_ldexp_f32 v147, v147, v148
	v_log_f32_e32 v147, v147
	s_nop 0
	v_mul_f32_e32 v148, 0x3f317217, v147
	v_fma_f32 v148, v147, s90, -v148
	v_fmac_f32_e32 v148, 0x3377d1cf, v147
	v_fmac_f32_e32 v148, 0x3f317217, v147
	v_cmp_lt_f32_e64 s[6:7], |v147|, s91
	s_nop 1
	v_cndmask_b32_e64 v147, v147, v148, s[6:7]
	v_cndmask_b32_e32 v148, 0, v222, vcc
	v_sub_f32_e32 v147, v147, v148
	v_pk_add_f32 v[142:143], v[142:143], v[146:147] neg_lo:[0,1] neg_hi:[0,1]
	v_min_f32_e32 v146, 0, v144
	v_mul_f32_e64 v144, |v144|, s88
	v_exp_f32_e32 v144, v144
	v_pk_mul_f32 v[142:143], v[142:143], s[28:29] op_sel_hi:[1,0]
	v_add_f32_e32 v144, 1.0, v144
	v_cmp_gt_f32_e32 vcc, s89, v144
	s_nop 1
	v_cndmask_b32_e64 v147, 0, 32, vcc
	v_ldexp_f32 v144, v144, v147
	v_log_f32_e32 v144, v144
	s_nop 0
	v_mul_f32_e32 v147, 0x3f317217, v144
	v_fma_f32 v147, v144, s90, -v147
	v_fmac_f32_e32 v147, 0x3377d1cf, v144
	v_fmac_f32_e32 v147, 0x3f317217, v144
	v_cmp_lt_f32_e64 s[6:7], |v144|, s91
	s_nop 1
	v_cndmask_b32_e64 v144, v144, v147, s[6:7]
	v_cndmask_b32_e32 v147, 0, v222, vcc
	v_sub_f32_e32 v144, v144, v147
	v_min_f32_e32 v147, 0, v145
	v_mul_f32_e64 v145, |v145|, s88
	v_exp_f32_e32 v145, v145
	s_nop 0
	v_add_f32_e32 v145, 1.0, v145
	v_cmp_gt_f32_e32 vcc, s89, v145
	s_nop 1
	v_cndmask_b32_e64 v148, 0, 32, vcc
	v_ldexp_f32 v145, v145, v148
	v_log_f32_e32 v145, v145
	s_nop 0
	v_mul_f32_e32 v148, 0x3f317217, v145
	v_fma_f32 v148, v145, s90, -v148
	v_fmac_f32_e32 v148, 0x3377d1cf, v145
	v_fmac_f32_e32 v148, 0x3f317217, v145
	v_cmp_lt_f32_e64 s[6:7], |v145|, s91
	s_nop 1
	v_cndmask_b32_e64 v145, v145, v148, s[6:7]
	v_cndmask_b32_e32 v148, 0, v222, vcc
	v_sub_f32_e32 v145, v145, v148
	v_pk_add_f32 v[144:145], v[146:147], v[144:145] neg_lo:[0,1] neg_hi:[0,1]
	v_fma_f32 v146, v10, v196, v138
	v_min_f32_e32 v138, 0, v146
	v_mul_f32_e64 v146, |v146|, s88
	v_exp_f32_e32 v146, v146
	v_pk_mul_f32 v[144:145], v[144:145], s[28:29] op_sel_hi:[1,0]
	v_add_f32_e32 v146, 1.0, v146
	v_cmp_gt_f32_e32 vcc, s89, v146
	s_nop 1
	v_cndmask_b32_e64 v147, 0, 32, vcc
	v_ldexp_f32 v146, v146, v147
	v_log_f32_e32 v146, v146
	s_nop 0
	v_mul_f32_e32 v147, 0x3f317217, v146
	v_fma_f32 v147, v146, s90, -v147
	v_fmac_f32_e32 v147, 0x3377d1cf, v146
	v_fmac_f32_e32 v147, 0x3f317217, v146
	v_cmp_lt_f32_e64 s[6:7], |v146|, s91
	s_nop 1
	v_cndmask_b32_e64 v146, v146, v147, s[6:7]
	v_cndmask_b32_e32 v147, 0, v222, vcc
	v_sub_f32_e32 v146, v146, v147
	v_fma_f32 v147, v11, v196, v139
	v_min_f32_e32 v139, 0, v147
	v_mul_f32_e64 v147, |v147|, s88
	v_exp_f32_e32 v147, v147
	s_nop 0
	v_add_f32_e32 v147, 1.0, v147
	v_cmp_gt_f32_e32 vcc, s89, v147
	s_nop 1
	v_cndmask_b32_e64 v148, 0, 32, vcc
	v_ldexp_f32 v147, v147, v148
	v_log_f32_e32 v147, v147
	s_nop 0
	v_mul_f32_e32 v148, 0x3f317217, v147
	v_fma_f32 v148, v147, s90, -v148
	v_fmac_f32_e32 v148, 0x3377d1cf, v147
	v_fmac_f32_e32 v148, 0x3f317217, v147
	v_cmp_lt_f32_e64 s[6:7], |v147|, s91
	s_nop 1
	v_cndmask_b32_e64 v147, v147, v148, s[6:7]
	v_cndmask_b32_e32 v148, 0, v222, vcc
	v_sub_f32_e32 v147, v147, v148
	v_pk_add_f32 v[138:139], v[138:139], v[146:147] neg_lo:[0,1] neg_hi:[0,1]
	s_nop 0
	v_pk_mul_f32 v[146:147], v[138:139], s[28:29] op_sel_hi:[1,0]
	v_fma_f32 v139, v12, v196, v140
	v_min_f32_e32 v138, 0, v139
	v_mul_f32_e64 v139, |v139|, s88
	v_exp_f32_e32 v139, v139
	s_nop 0
	v_add_f32_e32 v139, 1.0, v139
	v_cmp_gt_f32_e32 vcc, s89, v139
	s_nop 1
	v_cndmask_b32_e64 v140, 0, 32, vcc
	v_ldexp_f32 v139, v139, v140
	v_log_f32_e32 v139, v139
	s_nop 0
	v_mul_f32_e32 v140, 0x3f317217, v139
	v_fma_f32 v140, v139, s90, -v140
	v_fmac_f32_e32 v140, 0x3377d1cf, v139
	v_fmac_f32_e32 v140, 0x3f317217, v139
	v_cmp_lt_f32_e64 s[6:7], |v139|, s91
	s_nop 1
	v_cndmask_b32_e64 v139, v139, v140, s[6:7]
	v_cndmask_b32_e32 v140, 0, v222, vcc
	v_sub_f32_e32 v140, v139, v140
	v_min_f32_e32 v139, 0, v141
	v_mul_f32_e64 v141, |v141|, s88
	v_exp_f32_e32 v141, v141
	s_nop 0
	v_add_f32_e32 v141, 1.0, v141
	v_cmp_gt_f32_e32 vcc, s89, v141
	s_nop 1
	v_cndmask_b32_e64 v148, 0, 32, vcc
	v_ldexp_f32 v141, v141, v148
	v_log_f32_e32 v141, v141
	s_nop 0
	v_mul_f32_e32 v148, 0x3f317217, v141
	v_fma_f32 v148, v141, s90, -v148
	v_fmac_f32_e32 v148, 0x3377d1cf, v141
	v_fmac_f32_e32 v148, 0x3f317217, v141
	v_cmp_lt_f32_e64 s[6:7], |v141|, s91
	s_nop 1
	v_cndmask_b32_e64 v141, v141, v148, s[6:7]
	v_cndmask_b32_e32 v148, 0, v222, vcc
	v_sub_f32_e32 v141, v141, v148
	v_pk_add_f32 v[138:139], v[138:139], v[140:141] neg_lo:[0,1] neg_hi:[0,1]
	v_cvt_pk_bf16_f32 v140, v146, v147
	v_pk_mul_f32 v[148:149], v[138:139], s[28:29] op_sel_hi:[1,0]
; __device__ __forceinline__ v4u pack8(const f32x4 a, const f32x4 b) { v4u w; w.x = pk2(a[0], a[1]); w.y = pk2(a[2], a[3]); w.z = pk2(b[0], b[1]); w.w = pk2(b[2], b[3]); return w; }
; __device__ __forceinline__ float fast_exp(float x) { return __builtin_amdgcn_exp2f(x * LOG2E); }
;     __device__ __forceinline__ void operator()(const f32x4 (&acc)[2][2][4][2], const pg8::Unit& u, int wr, int wc, int fr, int fq) const {
;     ...
;                             const f32x4 z = acc[ai][bj][m][n] * rs + bg[bj][n];
; #pragma unroll
;                             for (int j = 0; j < 4; ++j) { const float az = fabsf(z[j]); r2[n][j] = (fminf(z[j], 0.f) - __logf(1.0f + fast_exp(-az))) * (1.0f / 16.0f); }
;                         }
;                         pk[bj] = pack8(r2[0], r2[1]);
;                     }
;                     v4u a, b; tt.bf(pk[0], pk[1], a, b);
;                     bf16* d = (bf16*)(ws + WS_LOGA) + (size_t)rowa * 256 + 64 * wc + 8 * tt.p; *(v4u*)d = a; *(v4u*)(d + 8 * 256) = b;
;                 }
	v_cvt_pk_bf16_f32 v138, v142, v143
	v_fma_f32 v142, v6, v196, v134
	v_min_f32_e32 v134, 0, v142
	v_mul_f32_e64 v142, |v142|, s88
	v_exp_f32_e32 v142, v142
	v_cvt_pk_bf16_f32 v139, v144, v145
	v_cvt_pk_bf16_f32 v141, v148, v149
	v_add_f32_e32 v142, 1.0, v142
	v_cmp_gt_f32_e32 vcc, s89, v142
	s_nop 1
	v_cndmask_b32_e64 v143, 0, 32, vcc
	v_ldexp_f32 v142, v142, v143
	v_log_f32_e32 v142, v142
	s_nop 0
	v_mul_f32_e32 v143, 0x3f317217, v142
	v_fma_f32 v143, v142, s90, -v143
	v_fmac_f32_e32 v143, 0x3377d1cf, v142
	v_fmac_f32_e32 v143, 0x3f317217, v142
	v_cmp_lt_f32_e64 s[6:7], |v142|, s91
	s_nop 1
	v_cndmask_b32_e64 v142, v142, v143, s[6:7]
	v_cndmask_b32_e32 v143, 0, v222, vcc
	v_sub_f32_e32 v142, v142, v143
	v_fma_f32 v143, v7, v196, v135
	v_min_f32_e32 v135, 0, v143
	v_mul_f32_e64 v143, |v143|, s88
	v_exp_f32_e32 v143, v143
	s_nop 0
	v_add_f32_e32 v143, 1.0, v143
	v_cmp_gt_f32_e32 vcc, s89, v143
	s_nop 1
	v_cndmask_b32_e64 v144, 0, 32, vcc
	v_ldexp_f32 v143, v143, v144
	v_log_f32_e32 v143, v143
	s_nop 0
	v_mul_f32_e32 v144, 0x3f317217, v143
	v_fma_f32 v144, v143, s90, -v144
	v_fmac_f32_e32 v144, 0x3377d1cf, v143
	v_fmac_f32_e32 v144, 0x3f317217, v143
	v_cmp_lt_f32_e64 s[6:7], |v143|, s91
	s_nop 1
	v_cndmask_b32_e64 v143, v143, v144, s[6:7]
	v_cndmask_b32_e32 v144, 0, v222, vcc
	v_sub_f32_e32 v143, v143, v144
	v_pk_add_f32 v[134:135], v[134:135], v[142:143] neg_lo:[0,1] neg_hi:[0,1]
	v_min_f32_e32 v142, 0, v136
	v_mul_f32_e64 v136, |v136|, s88
	v_exp_f32_e32 v136, v136
	v_pk_mul_f32 v[134:135], v[134:135], s[28:29] op_sel_hi:[1,0]
	v_add_f32_e32 v136, 1.0, v136
	v_cmp_gt_f32_e32 vcc, s89, v136
	s_nop 1
	v_cndmask_b32_e64 v143, 0, 32, vcc
	v_ldexp_f32 v136, v136, v143
	v_log_f32_e32 v136, v136
	s_nop 0
	v_mul_f32_e32 v143, 0x3f317217, v136
	v_fma_f32 v143, v136, s90, -v143
	v_fmac_f32_e32 v143, 0x3377d1cf, v136
	v_fmac_f32_e32 v143, 0x3f317217, v136
	v_cmp_lt_f32_e64 s[6:7], |v136|, s91
	s_nop 1
	v_cndmask_b32_e64 v136, v136, v143, s[6:7]
	v_cndmask_b32_e32 v143, 0, v222, vcc
	v_sub_f32_e32 v136, v136, v143
	v_min_f32_e32 v143, 0, v137
	v_mul_f32_e64 v137, |v137|, s88
	v_exp_f32_e32 v137, v137
	s_nop 0
	v_add_f32_e32 v137, 1.0, v137
	v_cmp_gt_f32_e32 vcc, s89, v137
	s_nop 1
	v_cndmask_b32_e64 v144, 0, 32, vcc
	v_ldexp_f32 v137, v137, v144
	v_log_f32_e32 v137, v137
	s_nop 0
	v_mul_f32_e32 v144, 0x3f317217, v137
	v_fma_f32 v144, v137, s90, -v144
	v_fmac_f32_e32 v144, 0x3377d1cf, v137
	v_fmac_f32_e32 v144, 0x3f317217, v137
	v_cmp_lt_f32_e64 s[6:7], |v137|, s91
	s_nop 1
	v_cndmask_b32_e64 v137, v137, v144, s[6:7]
	v_cndmask_b32_e32 v144, 0, v222, vcc
	v_sub_f32_e32 v137, v137, v144
	v_pk_add_f32 v[136:137], v[142:143], v[136:137] neg_lo:[0,1] neg_hi:[0,1]
	v_fma_f32 v142, v2, v196, v130
	v_min_f32_e32 v130, 0, v142
	v_mul_f32_e64 v142, |v142|, s88
	v_exp_f32_e32 v142, v142
	v_pk_mul_f32 v[136:137], v[136:137], s[28:29] op_sel_hi:[1,0]
	v_add_f32_e32 v142, 1.0, v142
	v_cmp_gt_f32_e32 vcc, s89, v142
	s_nop 1
	v_cndmask_b32_e64 v143, 0, 32, vcc
	v_ldexp_f32 v142, v142, v143
	v_log_f32_e32 v142, v142
	s_nop 0
	v_mul_f32_e32 v143, 0x3f317217, v142
	v_fma_f32 v143, v142, s90, -v143
	v_fmac_f32_e32 v143, 0x3377d1cf, v142
	v_fmac_f32_e32 v143, 0x3f317217, v142
	v_cmp_lt_f32_e64 s[6:7], |v142|, s91
	s_nop 1
	v_cndmask_b32_e64 v142, v142, v143, s[6:7]
	v_cndmask_b32_e32 v143, 0, v222, vcc
	v_sub_f32_e32 v142, v142, v143
	v_fma_f32 v143, v3, v196, v131
	v_min_f32_e32 v131, 0, v143
	v_mul_f32_e64 v143, |v143|, s88
	v_exp_f32_e32 v143, v143
	s_nop 0
	v_add_f32_e32 v143, 1.0, v143
	v_cmp_gt_f32_e32 vcc, s89, v143
	s_nop 1
	v_cndmask_b32_e64 v144, 0, 32, vcc
	v_ldexp_f32 v143, v143, v144
	v_log_f32_e32 v143, v143
	s_nop 0
	v_mul_f32_e32 v144, 0x3f317217, v143
	v_fma_f32 v144, v143, s90, -v144
	v_fmac_f32_e32 v144, 0x3377d1cf, v143
	v_fmac_f32_e32 v144, 0x3f317217, v143
	v_cmp_lt_f32_e64 s[6:7], |v143|, s91
	s_nop 1
	v_cndmask_b32_e64 v143, v143, v144, s[6:7]
	v_cndmask_b32_e32 v144, 0, v222, vcc
	v_sub_f32_e32 v143, v143, v144
	v_pk_add_f32 v[130:131], v[130:131], v[142:143] neg_lo:[0,1] neg_hi:[0,1]
	s_nop 0
	v_pk_mul_f32 v[142:143], v[130:131], s[28:29] op_sel_hi:[1,0]
	v_fma_f32 v131, v4, v196, v132
	v_min_f32_e32 v130, 0, v131
	v_mul_f32_e64 v131, |v131|, s88
	v_exp_f32_e32 v131, v131
	s_nop 0
	v_add_f32_e32 v131, 1.0, v131
	v_cmp_gt_f32_e32 vcc, s89, v131
	s_nop 1
	v_cndmask_b32_e64 v132, 0, 32, vcc
	v_ldexp_f32 v131, v131, v132
	v_log_f32_e32 v131, v131
	s_nop 0
	v_mul_f32_e32 v132, 0x3f317217, v131
	v_fma_f32 v132, v131, s90, -v132
	v_fmac_f32_e32 v132, 0x3377d1cf, v131
	v_fmac_f32_e32 v132, 0x3f317217, v131
	v_cmp_lt_f32_e64 s[6:7], |v131|, s91
	s_nop 1
	v_cndmask_b32_e64 v131, v131, v132, s[6:7]
	v_cndmask_b32_e32 v132, 0, v222, vcc
	v_sub_f32_e32 v132, v131, v132
	v_min_f32_e32 v131, 0, v133
	v_mul_f32_e64 v133, |v133|, s88
	v_exp_f32_e32 v133, v133
	s_nop 0
	v_add_f32_e32 v133, 1.0, v133
	v_cmp_gt_f32_e32 vcc, s89, v133
	s_nop 1
	v_cndmask_b32_e64 v144, 0, 32, vcc
	v_ldexp_f32 v133, v133, v144
	v_log_f32_e32 v133, v133
	s_nop 0
	v_mul_f32_e32 v144, 0x3f317217, v133
	v_fma_f32 v144, v133, s90, -v144
	v_fmac_f32_e32 v144, 0x3377d1cf, v133
	v_fmac_f32_e32 v144, 0x3f317217, v133
	v_cmp_lt_f32_e64 s[6:7], |v133|, s91
	s_nop 1
	v_cndmask_b32_e64 v133, v133, v144, s[6:7]
	v_cndmask_b32_e32 v144, 0, v222, vcc
	v_sub_f32_e32 v133, v133, v144
	v_pk_add_f32 v[130:131], v[130:131], v[132:133] neg_lo:[0,1] neg_hi:[0,1]
	v_cvt_pk_bf16_f32 v132, v142, v143
	v_pk_mul_f32 v[144:145], v[130:131], s[28:29] op_sel_hi:[1,0]
	v_cvt_pk_bf16_f32 v130, v134, v135
	v_cvt_pk_bf16_f32 v131, v136, v137
	v_cvt_pk_bf16_f32 v133, v144, v145
	v_add_u32_e32 v142, 0xb0, v150
	ds_write_b128 v160, v[138:141]
	ds_write_b128 v161, v[130:133]
	ds_read_b128 v[130:133], v163
	ds_read_b128 v[134:137], v163 offset:1024
	v_ashrrev_i32_e32 v143, 31, v142
	v_lshlrev_b64 v[138:139], 9, v[142:143]
	v_lshl_add_u64 v[138:139], s[24:25], 0, v[138:139]
	v_lshl_add_u64 v[138:139], v[138:139], 0, v[184:185]
	s_waitcnt lgkmcnt(1)
	global_store_dwordx4 v[138:139], v[130:133], off nt
	s_mov_b64 s[6:7], 0
	s_nop 0
	v_add_co_u32_e32 v130, vcc, 0x1000, v138
	s_nop 1
	v_addc_co_u32_e32 v131, vcc, 0, v139, vcc
	s_waitcnt lgkmcnt(0)
	global_store_dwordx4 v[130:131], v[134:137], off nt

; __device__ __forceinline__ v4u pack8(const f32x4 a, const f32x4 b) { v4u w; w.x = pk2(a[0], a[1]); w.y = pk2(a[2], a[3]); w.z = pk2(b[0], b[1]); w.w = pk2(b[2], b[3]); return w; }
; __device__ __forceinline__ float silu_f(float x) { return x * __builtin_amdgcn_rcpf(1.0f + fast_exp(-x)); }
;     __device__ __forceinline__ void operator()(const f32x4 (&acc)[2][2][4][2], const pg8::Unit& u, int wr, int wc, int fr, int fq) const {
;     ...
;             bf16* dst = (bf16*)(ws + (pn < 10 ? WS_VB : (pn < 12 ? WS_GA : WS_GB))); const bool act = pn >= 10;
;             const int cb = 256 * (pn & 1) + 64 * wc + 8 * tt.p;
; #pragma unroll
;             for (int ai = 0; ai < 2; ++ai)
; #pragma unroll
;                 for (int m = 0; m < 4; ++m) {
;                     const int rowa = 256 * pm + 128 * ai + 64 * wr + 16 * m + tt.rr;
;                     const float rs = rs8[ai][m];
;                     v4u pk[2];
; #pragma unroll
;                     for (int bj = 0; bj < 2; ++bj) {
;                         f32x4 a = acc[ai][bj][m][0] * rs, b = acc[ai][bj][m][1] * rs;
;                         if (act) {
; #pragma unroll
;                             for (int j = 0; j < 4; ++j) { a[j] = silu_f(a[j]); b[j] = silu_f(b[j]); }
;                         }
;                         pk[bj] = pack8(a, b);
;                     }
;                     v4u a, b; tt.bf(pk[0], pk[1], a, b);
;                     bf16* d = dst + (size_t)rowa * 512 + cb; *(v4u*)d = a; *(v4u*)(d + 8 * 512) = b;
.LBB0_424:
	s_cmp_lt_u32 s42, 12
	s_mov_b32 s0, 0x23800000
	s_cselect_b32 s0, s0, 0x27c00000
	s_cmp_gt_u32 s42, 9
	s_cselect_b32 s0, s0, 0x1b000000
	s_add_u32 s0, s58, s0
	s_addc_u32 s1, s59, 0
	s_lshl_b32 s12, s42, 8
	s_and_b32 s12, s12, 0x100
	v_cvt_pk_bf16_f32 v153, v130, v131
	v_lshl_or_b32 v130, v213, 3, s12
	v_or_b32_e32 v130, s69, v130
	v_cvt_pk_bf16_f32 v152, v132, v133
	v_cvt_pk_bf16_f32 v154, v136, v137
	v_cvt_pk_bf16_f32 v155, v134, v135
	v_lshlrev_b32_e32 v184, 1, v130
	v_cvt_pk_bf16_f32 v130, v140, v141
	v_cvt_pk_bf16_f32 v131, v138, v139
	v_cvt_pk_bf16_f32 v132, v144, v145
	v_cvt_pk_bf16_f32 v133, v142, v143
	v_add_u32_e32 v148, s77, v229
	v_add_u32_e32 v149, s77, v228
	ds_write_b128 v148, v[152:155]
	ds_write_b128 v149, v[130:133]
	v_add_u32_e32 v152, s77, v230
	ds_read_b128 v[132:135], v152
	ds_read_b128 v[136:139], v152 offset:1024
	v_lshl_add_u64 v[130:131], s[0:1], 0, v[184:185]
	v_lshlrev_b64 v[140:141], 10, v[150:151]
	v_lshl_add_u64 v[140:141], v[130:131], 0, v[140:141]
	s_waitcnt lgkmcnt(1)
	global_store_dwordx4 v[140:141], v[132:135], off nt
	s_nop 1
	v_add_co_u32_e32 v132, vcc, s55, v140
	v_pk_mul_f32 v[134:135], v[110:111], v[210:211] op_sel_hi:[1,0]
	s_nop 0
	v_addc_co_u32_e32 v133, vcc, 0, v141, vcc
	s_waitcnt lgkmcnt(0)
	global_store_dwordx4 v[132:133], v[136:139], off nt
	v_pk_mul_f32 v[132:133], v[112:113], v[210:211] op_sel_hi:[1,0]
	s_and_b64 vcc, exec, s[6:7]
	v_pk_mul_f32 v[136:137], v[108:109], v[210:211] op_sel_hi:[1,0]
	v_pk_mul_f32 v[138:139], v[106:107], v[210:211] op_sel_hi:[1,0]
	s_cbranch_vccnz .LBB0_426
	v_mul_f32_e32 v141, 0xbfb8aa3b, v138
	v_mul_f32_e32 v142, 0xbfb8aa3b, v135
	v_exp_f32_e32 v141, v141
	v_exp_f32_e32 v143, v142
	v_mul_f32_e32 v145, 0xbfb8aa3b, v136
	v_mul_f32_e32 v146, 0xbfb8aa3b, v133
	v_add_f32_e32 v141, 1.0, v141
	v_mul_f32_e32 v140, 0xbfb8aa3b, v134
	v_rcp_f32_e32 v142, v141
	v_add_f32_e32 v141, 1.0, v143
	v_mul_f32_e32 v143, 0xbfb8aa3b, v139
	v_mul_f32_e32 v144, 0xbfb8aa3b, v132
	v_exp_f32_e32 v145, v145
	v_exp_f32_e32 v147, v146
	v_mul_f32_e32 v146, 0xbfb8aa3b, v137
	v_exp_f32_e32 v140, v140
	v_exp_f32_e32 v143, v143
	v_exp_f32_e32 v144, v144
	v_exp_f32_e32 v151, v146
	v_add_f32_e32 v145, 1.0, v145
	v_add_f32_e32 v140, 1.0, v140
	v_add_f32_e32 v143, 1.0, v143
	v_add_f32_e32 v144, 1.0, v144
	v_rcp_f32_e32 v146, v145
	v_add_f32_e32 v145, 1.0, v147
	v_add_f32_e32 v147, 1.0, v151
	v_rcp_f32_e32 v140, v140
	v_rcp_f32_e32 v141, v141
	v_rcp_f32_e32 v144, v144
	v_rcp_f32_e32 v145, v145
	v_rcp_f32_e32 v147, v147
	v_rcp_f32_e32 v143, v143
	v_pk_mul_f32 v[134:135], v[134:135], v[140:141]
	v_pk_mul_f32 v[132:133], v[132:133], v[144:145]
	v_pk_mul_f32 v[136:137], v[136:137], v[146:147]
	v_pk_mul_f32 v[138:139], v[138:139], v[142:143]

; __device__ __forceinline__ v4u pack8(const f32x4 a, const f32x4 b) { v4u w; w.x = pk2(a[0], a[1]); w.y = pk2(a[2], a[3]); w.z = pk2(b[0], b[1]); w.w = pk2(b[2], b[3]); return w; }
; __device__ __forceinline__ float silu_f(float x) { return x * __builtin_amdgcn_rcpf(1.0f + fast_exp(-x)); }
;     __device__ __forceinline__ void operator()(const f32x4 (&acc)[2][2][4][2], const pg8::Unit& u, int wr, int wc, int fr, int fq) const {
;     ...
;             for (int ai = 0; ai < 2; ++ai)
; #pragma unroll
;                 for (int m = 0; m < 4; ++m) {
;                     const int rowa = 256 * pm + 128 * ai + 64 * wr + 16 * m + tt.rr;
;                     const float rs = rs8[ai][m];
;                     v4u pk[2];
; #pragma unroll
;                     for (int bj = 0; bj < 2; ++bj) {
;                         f32x4 a = acc[ai][bj][m][0] * rs, b = acc[ai][bj][m][1] * rs;
;                         if (act) {
; #pragma unroll
;                             for (int j = 0; j < 4; ++j) { a[j] = silu_f(a[j]); b[j] = silu_f(b[j]); }
;                         }
;                         pk[bj] = pack8(a, b);
;                     }
;                     v4u a, b; tt.bf(pk[0], pk[1], a, b);
;                     bf16* d = dst + (size_t)rowa * 512 + cb; *(v4u*)d = a; *(v4u*)(d + 8 * 512) = b;
.LBB0_428:
	v_cvt_pk_bf16_f32 v154, v134, v135
	v_cvt_pk_bf16_f32 v155, v132, v133
	v_cvt_pk_bf16_f32 v156, v138, v139
	v_cvt_pk_bf16_f32 v157, v136, v137
	v_cvt_pk_bf16_f32 v132, v142, v143
	v_cvt_pk_bf16_f32 v133, v140, v141
	v_cvt_pk_bf16_f32 v134, v146, v147
	v_cvt_pk_bf16_f32 v135, v144, v145
	ds_write_b128 v148, v[154:157]
	ds_write_b128 v149, v[132:135]
	v_add_u32_e32 v140, 16, v150
	ds_read_b128 v[132:135], v152
	ds_read_b128 v[136:139], v152 offset:1024
	v_ashrrev_i32_e32 v141, 31, v140
	v_lshlrev_b64 v[140:141], 10, v[140:141]
	v_lshl_add_u64 v[140:141], v[130:131], 0, v[140:141]
	s_waitcnt lgkmcnt(1)
	global_store_dwordx4 v[140:141], v[132:135], off nt
	s_nop 1
	v_add_co_u32_e32 v132, vcc, s55, v140
	v_pk_mul_f32 v[134:135], v[94:95], v[208:209] op_sel_hi:[1,0]
	s_nop 0
	v_addc_co_u32_e32 v133, vcc, 0, v141, vcc
	s_waitcnt lgkmcnt(0)
	global_store_dwordx4 v[132:133], v[136:139], off nt
	v_pk_mul_f32 v[132:133], v[96:97], v[208:209] op_sel_hi:[1,0]
	s_and_b64 vcc, exec, s[6:7]
	v_pk_mul_f32 v[136:137], v[92:93], v[208:209] op_sel_hi:[1,0]
	v_pk_mul_f32 v[138:139], v[90:91], v[208:209] op_sel_hi:[1,0]
	s_cbranch_vccnz .LBB0_430
	v_mul_f32_e32 v141, 0xbfb8aa3b, v138
	v_mul_f32_e32 v142, 0xbfb8aa3b, v135
	v_exp_f32_e32 v141, v141
	v_exp_f32_e32 v143, v142
	v_mul_f32_e32 v145, 0xbfb8aa3b, v136
	v_mul_f32_e32 v146, 0xbfb8aa3b, v133
	v_add_f32_e32 v141, 1.0, v141
	v_mul_f32_e32 v140, 0xbfb8aa3b, v134
	v_rcp_f32_e32 v142, v141
	v_add_f32_e32 v141, 1.0, v143
	v_mul_f32_e32 v143, 0xbfb8aa3b, v139
	v_mul_f32_e32 v144, 0xbfb8aa3b, v132
	v_exp_f32_e32 v145, v145
	v_exp_f32_e32 v147, v146
	v_mul_f32_e32 v146, 0xbfb8aa3b, v137
	v_exp_f32_e32 v140, v140
	v_exp_f32_e32 v143, v143
	v_exp_f32_e32 v144, v144
	v_exp_f32_e32 v151, v146
	v_add_f32_e32 v145, 1.0, v145
	v_add_f32_e32 v140, 1.0, v140
	v_add_f32_e32 v143, 1.0, v143
	v_add_f32_e32 v144, 1.0, v144
	v_rcp_f32_e32 v146, v145
	v_add_f32_e32 v145, 1.0, v147
	v_add_f32_e32 v147, 1.0, v151
	v_rcp_f32_e32 v140, v140
	v_rcp_f32_e32 v141, v141
	v_rcp_f32_e32 v144, v144
	v_rcp_f32_e32 v145, v145
	v_rcp_f32_e32 v147, v147
	v_rcp_f32_e32 v143, v143
	v_pk_mul_f32 v[134:135], v[134:135], v[140:141]
	v_pk_mul_f32 v[132:133], v[132:133], v[144:145]
	v_pk_mul_f32 v[136:137], v[136:137], v[146:147]
	v_pk_mul_f32 v[138:139], v[138:139], v[142:143]

; __device__ __forceinline__ v4u pack8(const f32x4 a, const f32x4 b) { v4u w; w.x = pk2(a[0], a[1]); w.y = pk2(a[2], a[3]); w.z = pk2(b[0], b[1]); w.w = pk2(b[2], b[3]); return w; }
; __device__ __forceinline__ float silu_f(float x) { return x * __builtin_amdgcn_rcpf(1.0f + fast_exp(-x)); }
;     __device__ __forceinline__ void operator()(const f32x4 (&acc)[2][2][4][2], const pg8::Unit& u, int wr, int wc, int fr, int fq) const {
;     ...
;             for (int ai = 0; ai < 2; ++ai)
; #pragma unroll
;                 for (int m = 0; m < 4; ++m) {
;                     const int rowa = 256 * pm + 128 * ai + 64 * wr + 16 * m + tt.rr;
;                     const float rs = rs8[ai][m];
;                     v4u pk[2];
; #pragma unroll
;                     for (int bj = 0; bj < 2; ++bj) {
;                         f32x4 a = acc[ai][bj][m][0] * rs, b = acc[ai][bj][m][1] * rs;
;                         if (act) {
; #pragma unroll
;                             for (int j = 0; j < 4; ++j) { a[j] = silu_f(a[j]); b[j] = silu_f(b[j]); }
;                         }
;                         pk[bj] = pack8(a, b);
;                     }
;                     v4u a, b; tt.bf(pk[0], pk[1], a, b);
;                     bf16* d = dst + (size_t)rowa * 512 + cb; *(v4u*)d = a; *(v4u*)(d + 8 * 512) = b;
.LBB0_432:
	v_cvt_pk_bf16_f32 v154, v134, v135
	v_cvt_pk_bf16_f32 v155, v132, v133
	v_cvt_pk_bf16_f32 v156, v138, v139
	v_cvt_pk_bf16_f32 v157, v136, v137
	v_cvt_pk_bf16_f32 v132, v142, v143
	v_cvt_pk_bf16_f32 v133, v140, v141
	v_cvt_pk_bf16_f32 v134, v146, v147
	v_cvt_pk_bf16_f32 v135, v144, v145
	ds_write_b128 v148, v[154:157]
	ds_write_b128 v149, v[132:135]
	v_add_u32_e32 v140, 32, v150
	ds_read_b128 v[132:135], v152
	ds_read_b128 v[136:139], v152 offset:1024
	v_ashrrev_i32_e32 v141, 31, v140
	v_lshlrev_b64 v[140:141], 10, v[140:141]
	v_lshl_add_u64 v[140:141], v[130:131], 0, v[140:141]
	s_waitcnt lgkmcnt(1)
	global_store_dwordx4 v[140:141], v[132:135], off nt
	s_nop 1
	v_add_co_u32_e32 v132, vcc, s55, v140
	v_pk_mul_f32 v[134:135], v[78:79], v[206:207] op_sel_hi:[1,0]
	s_nop 0
	v_addc_co_u32_e32 v133, vcc, 0, v141, vcc
	s_waitcnt lgkmcnt(0)
	global_store_dwordx4 v[132:133], v[136:139], off nt
	v_pk_mul_f32 v[132:133], v[80:81], v[206:207] op_sel_hi:[1,0]
	s_and_b64 vcc, exec, s[6:7]
	v_pk_mul_f32 v[136:137], v[76:77], v[206:207] op_sel_hi:[1,0]
	v_pk_mul_f32 v[138:139], v[74:75], v[206:207] op_sel_hi:[1,0]
	s_cbranch_vccnz .LBB0_434
	v_mul_f32_e32 v141, 0xbfb8aa3b, v138
	v_mul_f32_e32 v142, 0xbfb8aa3b, v135
	v_exp_f32_e32 v141, v141
	v_exp_f32_e32 v143, v142
	v_mul_f32_e32 v145, 0xbfb8aa3b, v136
	v_mul_f32_e32 v146, 0xbfb8aa3b, v133
	v_add_f32_e32 v141, 1.0, v141
	v_mul_f32_e32 v140, 0xbfb8aa3b, v134
	v_rcp_f32_e32 v142, v141
	v_add_f32_e32 v141, 1.0, v143
	v_mul_f32_e32 v143, 0xbfb8aa3b, v139
	v_mul_f32_e32 v144, 0xbfb8aa3b, v132
	v_exp_f32_e32 v145, v145
	v_exp_f32_e32 v147, v146
	v_mul_f32_e32 v146, 0xbfb8aa3b, v137
	v_exp_f32_e32 v140, v140
	v_exp_f32_e32 v143, v143
	v_exp_f32_e32 v144, v144
	v_exp_f32_e32 v151, v146
	v_add_f32_e32 v145, 1.0, v145
	v_add_f32_e32 v140, 1.0, v140
	v_add_f32_e32 v143, 1.0, v143
	v_add_f32_e32 v144, 1.0, v144
	v_rcp_f32_e32 v146, v145
	v_add_f32_e32 v145, 1.0, v147
	v_add_f32_e32 v147, 1.0, v151
	v_rcp_f32_e32 v140, v140
	v_rcp_f32_e32 v141, v141
	v_rcp_f32_e32 v144, v144
	v_rcp_f32_e32 v145, v145
	v_rcp_f32_e32 v147, v147
	v_rcp_f32_e32 v143, v143
	v_pk_mul_f32 v[134:135], v[134:135], v[140:141]
	v_pk_mul_f32 v[132:133], v[132:133], v[144:145]
	v_pk_mul_f32 v[136:137], v[136:137], v[146:147]
	v_pk_mul_f32 v[138:139], v[138:139], v[142:143]

; __device__ __forceinline__ v4u pack8(const f32x4 a, const f32x4 b) { v4u w; w.x = pk2(a[0], a[1]); w.y = pk2(a[2], a[3]); w.z = pk2(b[0], b[1]); w.w = pk2(b[2], b[3]); return w; }
; __device__ __forceinline__ float silu_f(float x) { return x * __builtin_amdgcn_rcpf(1.0f + fast_exp(-x)); }
;     __device__ __forceinline__ void operator()(const f32x4 (&acc)[2][2][4][2], const pg8::Unit& u, int wr, int wc, int fr, int fq) const {
;     ...
;             for (int ai = 0; ai < 2; ++ai)
; #pragma unroll
;                 for (int m = 0; m < 4; ++m) {
;                     const int rowa = 256 * pm + 128 * ai + 64 * wr + 16 * m + tt.rr;
;                     const float rs = rs8[ai][m];
;                     v4u pk[2];
; #pragma unroll
;                     for (int bj = 0; bj < 2; ++bj) {
;                         f32x4 a = acc[ai][bj][m][0] * rs, b = acc[ai][bj][m][1] * rs;
;                         if (act) {
; #pragma unroll
;                             for (int j = 0; j < 4; ++j) { a[j] = silu_f(a[j]); b[j] = silu_f(b[j]); }
;                         }
;                         pk[bj] = pack8(a, b);
;                     }
;                     v4u a, b; tt.bf(pk[0], pk[1], a, b);
;                     bf16* d = dst + (size_t)rowa * 512 + cb; *(v4u*)d = a; *(v4u*)(d + 8 * 512) = b;
.LBB0_436:
	v_cvt_pk_bf16_f32 v154, v134, v135
	v_cvt_pk_bf16_f32 v155, v132, v133
	v_cvt_pk_bf16_f32 v156, v138, v139
	v_cvt_pk_bf16_f32 v157, v136, v137
	v_cvt_pk_bf16_f32 v132, v142, v143
	v_cvt_pk_bf16_f32 v133, v140, v141
	v_cvt_pk_bf16_f32 v134, v146, v147
	v_cvt_pk_bf16_f32 v135, v144, v145
	ds_write_b128 v148, v[154:157]
	ds_write_b128 v149, v[132:135]
	v_add_u32_e32 v140, 48, v150
	ds_read_b128 v[132:135], v152
	ds_read_b128 v[136:139], v152 offset:1024
	v_ashrrev_i32_e32 v141, 31, v140
	v_lshlrev_b64 v[140:141], 10, v[140:141]
	v_lshl_add_u64 v[140:141], v[130:131], 0, v[140:141]
	s_waitcnt lgkmcnt(1)
	global_store_dwordx4 v[140:141], v[132:135], off nt
	s_nop 1
	v_add_co_u32_e32 v132, vcc, s55, v140
	v_pk_mul_f32 v[134:135], v[62:63], v[204:205] op_sel_hi:[1,0]
	s_nop 0
	v_addc_co_u32_e32 v133, vcc, 0, v141, vcc
	s_waitcnt lgkmcnt(0)
	global_store_dwordx4 v[132:133], v[136:139], off nt
	v_pk_mul_f32 v[132:133], v[64:65], v[204:205] op_sel_hi:[1,0]
	s_and_b64 vcc, exec, s[6:7]
	v_pk_mul_f32 v[136:137], v[60:61], v[204:205] op_sel_hi:[1,0]
	v_pk_mul_f32 v[138:139], v[58:59], v[204:205] op_sel_hi:[1,0]
	s_cbranch_vccnz .LBB0_438
	v_mul_f32_e32 v141, 0xbfb8aa3b, v138
	v_mul_f32_e32 v142, 0xbfb8aa3b, v135
	v_exp_f32_e32 v141, v141
	v_exp_f32_e32 v143, v142
	v_mul_f32_e32 v145, 0xbfb8aa3b, v136
	v_mul_f32_e32 v146, 0xbfb8aa3b, v133
	v_add_f32_e32 v141, 1.0, v141
	v_mul_f32_e32 v140, 0xbfb8aa3b, v134
	v_rcp_f32_e32 v142, v141
	v_add_f32_e32 v141, 1.0, v143
	v_mul_f32_e32 v143, 0xbfb8aa3b, v139
	v_mul_f32_e32 v144, 0xbfb8aa3b, v132
	v_exp_f32_e32 v145, v145
	v_exp_f32_e32 v147, v146
	v_mul_f32_e32 v146, 0xbfb8aa3b, v137
	v_exp_f32_e32 v140, v140
	v_exp_f32_e32 v143, v143
	v_exp_f32_e32 v144, v144
	v_exp_f32_e32 v151, v146
	v_add_f32_e32 v145, 1.0, v145
	v_add_f32_e32 v140, 1.0, v140
	v_add_f32_e32 v143, 1.0, v143
	v_add_f32_e32 v144, 1.0, v144
	v_rcp_f32_e32 v146, v145
	v_add_f32_e32 v145, 1.0, v147
	v_add_f32_e32 v147, 1.0, v151
	v_rcp_f32_e32 v140, v140
	v_rcp_f32_e32 v141, v141
	v_rcp_f32_e32 v144, v144
	v_rcp_f32_e32 v145, v145
	v_rcp_f32_e32 v147, v147
	v_rcp_f32_e32 v143, v143
	v_pk_mul_f32 v[134:135], v[134:135], v[140:141]
	v_pk_mul_f32 v[132:133], v[132:133], v[144:145]
	v_pk_mul_f32 v[136:137], v[136:137], v[146:147]
	v_pk_mul_f32 v[138:139], v[138:139], v[142:143]

; __device__ __forceinline__ v4u pack8(const f32x4 a, const f32x4 b) { v4u w; w.x = pk2(a[0], a[1]); w.y = pk2(a[2], a[3]); w.z = pk2(b[0], b[1]); w.w = pk2(b[2], b[3]); return w; }
; __device__ __forceinline__ float silu_f(float x) { return x * __builtin_amdgcn_rcpf(1.0f + fast_exp(-x)); }
;     __device__ __forceinline__ void operator()(const f32x4 (&acc)[2][2][4][2], const pg8::Unit& u, int wr, int wc, int fr, int fq) const {
;     ...
;             for (int ai = 0; ai < 2; ++ai)
; #pragma unroll
;                 for (int m = 0; m < 4; ++m) {
;                     const int rowa = 256 * pm + 128 * ai + 64 * wr + 16 * m + tt.rr;
;                     const float rs = rs8[ai][m];
;                     v4u pk[2];
; #pragma unroll
;                     for (int bj = 0; bj < 2; ++bj) {
;                         f32x4 a = acc[ai][bj][m][0] * rs, b = acc[ai][bj][m][1] * rs;
;                         if (act) {
; #pragma unroll
;                             for (int j = 0; j < 4; ++j) { a[j] = silu_f(a[j]); b[j] = silu_f(b[j]); }
;                         }
;                         pk[bj] = pack8(a, b);
;                     }
;                     v4u a, b; tt.bf(pk[0], pk[1], a, b);
;                     bf16* d = dst + (size_t)rowa * 512 + cb; *(v4u*)d = a; *(v4u*)(d + 8 * 512) = b;
.LBB0_440:
	v_cvt_pk_bf16_f32 v154, v134, v135
	v_cvt_pk_bf16_f32 v155, v132, v133
	v_cvt_pk_bf16_f32 v156, v138, v139
	v_cvt_pk_bf16_f32 v157, v136, v137
	v_cvt_pk_bf16_f32 v132, v142, v143
	v_cvt_pk_bf16_f32 v133, v140, v141
	v_cvt_pk_bf16_f32 v134, v146, v147
	v_cvt_pk_bf16_f32 v135, v144, v145
	ds_write_b128 v148, v[154:157]
	ds_write_b128 v149, v[132:135]
	v_add_u32_e32 v160, 0x80, v150
	ds_read_b128 v[132:135], v152
	ds_read_b128 v[136:139], v152 offset:1024
	v_ashrrev_i32_e32 v161, 31, v160
	v_lshlrev_b64 v[140:141], 10, v[160:161]
	v_lshl_add_u64 v[140:141], v[130:131], 0, v[140:141]
	s_waitcnt lgkmcnt(1)
	global_store_dwordx4 v[140:141], v[132:135], off nt
	s_nop 1
	v_add_co_u32_e32 v132, vcc, s55, v140
	v_pk_mul_f32 v[134:135], v[46:47], v[202:203] op_sel_hi:[1,0]
	s_nop 0
	v_addc_co_u32_e32 v133, vcc, 0, v141, vcc
	s_waitcnt lgkmcnt(0)
	global_store_dwordx4 v[132:133], v[136:139], off nt
	v_pk_mul_f32 v[132:133], v[48:49], v[202:203] op_sel_hi:[1,0]
	s_and_b64 vcc, exec, s[6:7]
	v_pk_mul_f32 v[136:137], v[44:45], v[202:203] op_sel_hi:[1,0]
	v_pk_mul_f32 v[138:139], v[42:43], v[202:203] op_sel_hi:[1,0]
	s_cbranch_vccnz .LBB0_442
	v_mul_f32_e32 v141, 0xbfb8aa3b, v138
	v_mul_f32_e32 v142, 0xbfb8aa3b, v135
	v_exp_f32_e32 v141, v141
	v_exp_f32_e32 v143, v142
	v_mul_f32_e32 v145, 0xbfb8aa3b, v136
	v_mul_f32_e32 v146, 0xbfb8aa3b, v133
	v_add_f32_e32 v141, 1.0, v141
	v_mul_f32_e32 v140, 0xbfb8aa3b, v134
	v_rcp_f32_e32 v142, v141
	v_add_f32_e32 v141, 1.0, v143
	v_mul_f32_e32 v143, 0xbfb8aa3b, v139
	v_mul_f32_e32 v144, 0xbfb8aa3b, v132
	v_exp_f32_e32 v145, v145
	v_exp_f32_e32 v147, v146
	v_mul_f32_e32 v146, 0xbfb8aa3b, v137
	v_exp_f32_e32 v140, v140
	v_exp_f32_e32 v143, v143
	v_exp_f32_e32 v144, v144
	v_exp_f32_e32 v151, v146
	v_add_f32_e32 v145, 1.0, v145
	v_add_f32_e32 v140, 1.0, v140
	v_add_f32_e32 v143, 1.0, v143
	v_add_f32_e32 v144, 1.0, v144
	v_rcp_f32_e32 v146, v145
	v_add_f32_e32 v145, 1.0, v147
	v_add_f32_e32 v147, 1.0, v151
	v_rcp_f32_e32 v140, v140
	v_rcp_f32_e32 v141, v141
	v_rcp_f32_e32 v144, v144
	v_rcp_f32_e32 v145, v145
	v_rcp_f32_e32 v147, v147
	v_rcp_f32_e32 v143, v143
	v_pk_mul_f32 v[134:135], v[134:135], v[140:141]
	v_pk_mul_f32 v[132:133], v[132:133], v[144:145]
	v_pk_mul_f32 v[136:137], v[136:137], v[146:147]
	v_pk_mul_f32 v[138:139], v[138:139], v[142:143]

; __device__ __forceinline__ v4u pack8(const f32x4 a, const f32x4 b) { v4u w; w.x = pk2(a[0], a[1]); w.y = pk2(a[2], a[3]); w.z = pk2(b[0], b[1]); w.w = pk2(b[2], b[3]); return w; }
; __device__ __forceinline__ float silu_f(float x) { return x * __builtin_amdgcn_rcpf(1.0f + fast_exp(-x)); }
;     __device__ __forceinline__ void operator()(const f32x4 (&acc)[2][2][4][2], const pg8::Unit& u, int wr, int wc, int fr, int fq) const {
;     ...
;             for (int ai = 0; ai < 2; ++ai)
; #pragma unroll
;                 for (int m = 0; m < 4; ++m) {
;                     const int rowa = 256 * pm + 128 * ai + 64 * wr + 16 * m + tt.rr;
;                     const float rs = rs8[ai][m];
;                     v4u pk[2];
; #pragma unroll
;                     for (int bj = 0; bj < 2; ++bj) {
;                         f32x4 a = acc[ai][bj][m][0] * rs, b = acc[ai][bj][m][1] * rs;
;                         if (act) {
; #pragma unroll
;                             for (int j = 0; j < 4; ++j) { a[j] = silu_f(a[j]); b[j] = silu_f(b[j]); }
;                         }
;                         pk[bj] = pack8(a, b);
;                     }
;                     v4u a, b; tt.bf(pk[0], pk[1], a, b);
;                     bf16* d = dst + (size_t)rowa * 512 + cb; *(v4u*)d = a; *(v4u*)(d + 8 * 512) = b;
.LBB0_444:
	v_cvt_pk_bf16_f32 v154, v134, v135
	v_cvt_pk_bf16_f32 v155, v132, v133
	v_cvt_pk_bf16_f32 v156, v138, v139
	v_cvt_pk_bf16_f32 v157, v136, v137
	v_cvt_pk_bf16_f32 v132, v142, v143
	v_cvt_pk_bf16_f32 v133, v140, v141
	v_cvt_pk_bf16_f32 v134, v146, v147
	v_cvt_pk_bf16_f32 v135, v144, v145
	ds_write_b128 v148, v[154:157]
	ds_write_b128 v149, v[132:135]
	v_add_u32_e32 v140, 0x90, v150
	ds_read_b128 v[132:135], v152
	ds_read_b128 v[136:139], v152 offset:1024
	v_ashrrev_i32_e32 v141, 31, v140
	v_lshlrev_b64 v[140:141], 10, v[140:141]
	v_lshl_add_u64 v[140:141], v[130:131], 0, v[140:141]
	s_waitcnt lgkmcnt(1)
	global_store_dwordx4 v[140:141], v[132:135], off nt
	s_nop 1
	v_add_co_u32_e32 v132, vcc, s55, v140
	v_pk_mul_f32 v[134:135], v[30:31], v[198:199] op_sel_hi:[1,0]
	s_nop 0
	v_addc_co_u32_e32 v133, vcc, 0, v141, vcc
	s_waitcnt lgkmcnt(0)
	global_store_dwordx4 v[132:133], v[136:139], off nt
	v_pk_mul_f32 v[132:133], v[32:33], v[198:199] op_sel_hi:[1,0]
	s_and_b64 vcc, exec, s[6:7]
	v_pk_mul_f32 v[136:137], v[28:29], v[198:199] op_sel_hi:[1,0]
	v_pk_mul_f32 v[138:139], v[26:27], v[198:199] op_sel_hi:[1,0]
	s_cbranch_vccnz .LBB0_446
	v_mul_f32_e32 v141, 0xbfb8aa3b, v138
	v_mul_f32_e32 v142, 0xbfb8aa3b, v135
	v_exp_f32_e32 v141, v141
	v_exp_f32_e32 v143, v142
	v_mul_f32_e32 v145, 0xbfb8aa3b, v136
	v_mul_f32_e32 v146, 0xbfb8aa3b, v133
	v_add_f32_e32 v141, 1.0, v141
	v_mul_f32_e32 v140, 0xbfb8aa3b, v134
	v_rcp_f32_e32 v142, v141
	v_add_f32_e32 v141, 1.0, v143
	v_mul_f32_e32 v143, 0xbfb8aa3b, v139
	v_mul_f32_e32 v144, 0xbfb8aa3b, v132
	v_exp_f32_e32 v145, v145
	v_exp_f32_e32 v147, v146
	v_mul_f32_e32 v146, 0xbfb8aa3b, v137
	v_exp_f32_e32 v140, v140
	v_exp_f32_e32 v143, v143
	v_exp_f32_e32 v144, v144
	v_exp_f32_e32 v151, v146
	v_add_f32_e32 v145, 1.0, v145
	v_add_f32_e32 v140, 1.0, v140
	v_add_f32_e32 v143, 1.0, v143
	v_add_f32_e32 v144, 1.0, v144
	v_rcp_f32_e32 v146, v145
	v_add_f32_e32 v145, 1.0, v147
	v_add_f32_e32 v147, 1.0, v151
	v_rcp_f32_e32 v140, v140
	v_rcp_f32_e32 v141, v141
	v_rcp_f32_e32 v144, v144
	v_rcp_f32_e32 v145, v145
	v_rcp_f32_e32 v147, v147
	v_rcp_f32_e32 v143, v143
	v_pk_mul_f32 v[134:135], v[134:135], v[140:141]
	v_pk_mul_f32 v[132:133], v[132:133], v[144:145]
	v_pk_mul_f32 v[136:137], v[136:137], v[146:147]
	v_pk_mul_f32 v[138:139], v[138:139], v[142:143]

; __device__ __forceinline__ v4u pack8(const f32x4 a, const f32x4 b) { v4u w; w.x = pk2(a[0], a[1]); w.y = pk2(a[2], a[3]); w.z = pk2(b[0], b[1]); w.w = pk2(b[2], b[3]); return w; }
; __device__ __forceinline__ float silu_f(float x) { return x * __builtin_amdgcn_rcpf(1.0f + fast_exp(-x)); }
;     __device__ __forceinline__ void operator()(const f32x4 (&acc)[2][2][4][2], const pg8::Unit& u, int wr, int wc, int fr, int fq) const {
;     ...
;             for (int ai = 0; ai < 2; ++ai)
; #pragma unroll
;                 for (int m = 0; m < 4; ++m) {
;                     const int rowa = 256 * pm + 128 * ai + 64 * wr + 16 * m + tt.rr;
;                     const float rs = rs8[ai][m];
;                     v4u pk[2];
; #pragma unroll
;                     for (int bj = 0; bj < 2; ++bj) {
;                         f32x4 a = acc[ai][bj][m][0] * rs, b = acc[ai][bj][m][1] * rs;
;                         if (act) {
; #pragma unroll
;                             for (int j = 0; j < 4; ++j) { a[j] = silu_f(a[j]); b[j] = silu_f(b[j]); }
;                         }
;                         pk[bj] = pack8(a, b);
;                     }
;                     v4u a, b; tt.bf(pk[0], pk[1], a, b);
;                     bf16* d = dst + (size_t)rowa * 512 + cb; *(v4u*)d = a; *(v4u*)(d + 8 * 512) = b;
.LBB0_448:
	v_cvt_pk_bf16_f32 v154, v134, v135
	v_cvt_pk_bf16_f32 v155, v132, v133
	v_cvt_pk_bf16_f32 v156, v138, v139
	v_cvt_pk_bf16_f32 v157, v136, v137
	v_cvt_pk_bf16_f32 v132, v142, v143
	v_cvt_pk_bf16_f32 v133, v140, v141
	v_cvt_pk_bf16_f32 v134, v146, v147
	v_cvt_pk_bf16_f32 v135, v144, v145
	ds_write_b128 v148, v[154:157]
	ds_write_b128 v149, v[132:135]
	v_add_u32_e32 v140, 0xa0, v150
	ds_read_b128 v[132:135], v152
	ds_read_b128 v[136:139], v152 offset:1024
	v_ashrrev_i32_e32 v141, 31, v140
	v_lshlrev_b64 v[140:141], 10, v[140:141]
	v_lshl_add_u64 v[140:141], v[130:131], 0, v[140:141]
	s_waitcnt lgkmcnt(1)
	global_store_dwordx4 v[140:141], v[132:135], off nt
	s_nop 1
	v_add_co_u32_e32 v132, vcc, s55, v140
	v_pk_mul_f32 v[134:135], v[14:15], v[196:197] op_sel_hi:[1,0]
	s_nop 0
	v_addc_co_u32_e32 v133, vcc, 0, v141, vcc
	s_waitcnt lgkmcnt(0)
	global_store_dwordx4 v[132:133], v[136:139], off nt
	v_pk_mul_f32 v[132:133], v[16:17], v[196:197] op_sel_hi:[1,0]
	s_and_b64 vcc, exec, s[6:7]
	v_pk_mul_f32 v[136:137], v[12:13], v[196:197] op_sel_hi:[1,0]
	v_pk_mul_f32 v[138:139], v[10:11], v[196:197] op_sel_hi:[1,0]
	s_cbranch_vccnz .LBB0_450
	v_mul_f32_e32 v141, 0xbfb8aa3b, v138
	v_mul_f32_e32 v142, 0xbfb8aa3b, v135
	v_exp_f32_e32 v141, v141
	v_exp_f32_e32 v143, v142
	v_mul_f32_e32 v145, 0xbfb8aa3b, v136
	v_mul_f32_e32 v146, 0xbfb8aa3b, v133
	v_add_f32_e32 v141, 1.0, v141
	v_mul_f32_e32 v140, 0xbfb8aa3b, v134
	v_rcp_f32_e32 v142, v141
	v_add_f32_e32 v141, 1.0, v143
	v_mul_f32_e32 v143, 0xbfb8aa3b, v139
	v_mul_f32_e32 v144, 0xbfb8aa3b, v132
	v_exp_f32_e32 v145, v145
	v_exp_f32_e32 v147, v146
	v_mul_f32_e32 v146, 0xbfb8aa3b, v137
	v_exp_f32_e32 v140, v140
	v_exp_f32_e32 v143, v143
	v_exp_f32_e32 v144, v144
	v_exp_f32_e32 v151, v146
	v_add_f32_e32 v145, 1.0, v145
	v_add_f32_e32 v140, 1.0, v140
	v_add_f32_e32 v143, 1.0, v143
	v_add_f32_e32 v144, 1.0, v144
	v_rcp_f32_e32 v146, v145
	v_add_f32_e32 v145, 1.0, v147
	v_add_f32_e32 v147, 1.0, v151
	v_rcp_f32_e32 v140, v140
	v_rcp_f32_e32 v141, v141
	v_rcp_f32_e32 v144, v144
	v_rcp_f32_e32 v145, v145
	v_rcp_f32_e32 v147, v147
	v_rcp_f32_e32 v143, v143
	v_pk_mul_f32 v[134:135], v[134:135], v[140:141]
	v_pk_mul_f32 v[132:133], v[132:133], v[144:145]
	v_pk_mul_f32 v[136:137], v[136:137], v[146:147]
	v_pk_mul_f32 v[138:139], v[138:139], v[142:143]

;     __device__ __forceinline__ void operator()(const f32x4 (&acc)[2][2][4][2], const pg8::Unit& u, int wr, int wc, int fr, int fq) const {
;     ...
;                     v4u a, b; tt.bf(pk[0], pk[1], a, b);
;                     bf16* d = dst + (size_t)rowa * 512 + cb; *(v4u*)d = a; *(v4u*)(d + 8 * 512) = b;
.LBB0_452:
	v_cvt_pk_bf16_f32 v154, v134, v135
	v_cvt_pk_bf16_f32 v155, v132, v133
	v_cvt_pk_bf16_f32 v156, v138, v139
	v_cvt_pk_bf16_f32 v157, v136, v137
	v_cvt_pk_bf16_f32 v132, v142, v143
	v_cvt_pk_bf16_f32 v133, v140, v141
	v_cvt_pk_bf16_f32 v134, v146, v147
	v_cvt_pk_bf16_f32 v135, v144, v145
	ds_write_b128 v148, v[154:157]
	ds_write_b128 v149, v[132:135]
	v_add_u32_e32 v140, 0xb0, v150
	ds_read_b128 v[132:135], v152
	ds_read_b128 v[136:139], v152 offset:1024
	v_ashrrev_i32_e32 v141, 31, v140
	v_lshlrev_b64 v[140:141], 10, v[140:141]
	v_lshl_add_u64 v[130:131], v[130:131], 0, v[140:141]
	s_waitcnt lgkmcnt(1)
	global_store_dwordx4 v[130:131], v[132:135], off nt
	v_add_co_u32_e32 v130, vcc, 0x2000, v130
	s_nop 1
	v_addc_co_u32_e32 v131, vcc, 0, v131, vcc
	s_waitcnt lgkmcnt(0)
	global_store_dwordx4 v[130:131], v[136:139], off nt

; __device__ __forceinline__ v4u pack8(const f32x4 a, const f32x4 b) { v4u w; w.x = pk2(a[0], a[1]); w.y = pk2(a[2], a[3]); w.z = pk2(b[0], b[1]); w.w = pk2(b[2], b[3]); return w; }
;     __device__ __forceinline__ void operator()(const f32x4 (&acc)[2][2][4][2], const pg8::Unit& u, int wr, int wc, int fr, int fq) const {
;     ...
;             bf16* dst = (bf16*)(ws + (pn == 6 ? WS_QB : WS_KB)); const float sc = pn == 6 ? 0.125f : 1.0f;
; #pragma unroll
;             for (int ai = 0; ai < 2; ++ai)
; #pragma unroll
;                 for (int m = 0; m < 4; ++m) {
;                     const int rowa = 256 * pm + 128 * ai + 64 * wr + 16 * m + tt.rr;
;                     const float rs = rs8[ai][m] * sc;
;                     v4u a, b; tt.bf(pack8(acc[ai][0][m][0] * rs, acc[ai][0][m][1] * rs), pack8(acc[ai][1][m][0] * rs, acc[ai][1][m][1] * rs), a, b);
;                     bf16* d = dst + (size_t)rowa * 256 + wc * 64 + 8 * tt.p; *(v4u*)d = a; *(v4u*)(d + 8 * 256) = b;
.LBB0_454:
	s_andn2_b64 vcc, exec, s[6:7]
	s_cbranch_vccnz .LBB0_456
	s_cmp_eq_u32 s42, 6
	s_cselect_b64 vcc, -1, 0
	v_cndmask_b32_e32 v150, 1.0, v223, vcc
	s_waitcnt vmcnt(0)
	v_mul_f32_e32 v138, v150, v162
	s_and_b64 s[0:1], vcc, exec
	v_pk_mul_f32 v[136:137], v[128:129], v[138:139] op_sel_hi:[1,0]
	v_pk_mul_f32 v[134:135], v[126:127], v[138:139] op_sel_hi:[1,0]
	v_pk_mul_f32 v[140:141], v[124:125], v[138:139] op_sel_hi:[1,0]
	v_pk_mul_f32 v[142:143], v[122:123], v[138:139] op_sel_hi:[1,0]
	s_mov_b32 s0, 0x16c00000
	v_add_u32_e32 v151, s77, v229
	v_cvt_pk_bf16_f32 v134, v134, v135
	v_cvt_pk_bf16_f32 v135, v136, v137
	v_cvt_pk_bf16_f32 v136, v142, v143
	v_cvt_pk_bf16_f32 v137, v140, v141
	v_pk_mul_f32 v[140:141], v[120:121], v[138:139] op_sel_hi:[1,0]
	v_pk_mul_f32 v[142:143], v[118:119], v[138:139] op_sel_hi:[1,0]
	v_pk_mul_f32 v[144:145], v[116:117], v[138:139] op_sel_hi:[1,0]
	v_pk_mul_f32 v[146:147], v[114:115], v[138:139] op_sel_hi:[1,0]
	s_cselect_b32 s0, s0, 0x18e00000
	s_add_i32 s1, s9, s66
	v_add_u32_e32 v152, s77, v228
	v_add_u32_e32 v153, s77, v230
	v_cvt_pk_bf16_f32 v138, v142, v143
	v_cvt_pk_bf16_f32 v139, v140, v141
	v_cvt_pk_bf16_f32 v140, v146, v147
	v_cvt_pk_bf16_f32 v141, v144, v145
	ds_write_b128 v151, v[134:137]
	ds_write_b128 v152, v[138:141]
	v_add_u32_e32 v132, s1, v227
	s_add_u32 s0, s73, s0
	ds_read_b128 v[134:137], v153
	ds_read_b128 v[138:141], v153 offset:1024
	s_addc_u32 s1, s74, 0
	v_lshlrev_b32_e32 v184, 4, v213
	v_ashrrev_i32_e32 v133, 31, v132
	v_lshl_add_u64 v[130:131], s[0:1], 0, v[184:185]
	v_lshlrev_b64 v[142:143], 9, v[132:133]
	v_lshl_add_u64 v[142:143], v[130:131], 0, v[142:143]
	s_waitcnt lgkmcnt(1)
	global_store_dwordx4 v[142:143], v[134:137], off nt
	s_nop 1
	v_add_co_u32_e32 v134, vcc, s92, v142
	v_add_u32_e32 v142, 16, v132
	s_nop 0
	v_addc_co_u32_e32 v135, vcc, 0, v143, vcc
	s_waitcnt lgkmcnt(0)
	global_store_dwordx4 v[134:135], v[138:141], off nt
	v_ashrrev_i32_e32 v143, 31, v142
	v_lshlrev_b64 v[142:143], 9, v[142:143]
	v_mul_f32_e32 v138, v150, v210
	v_pk_mul_f32 v[136:137], v[112:113], v[138:139] op_sel_hi:[1,0]
	v_pk_mul_f32 v[134:135], v[110:111], v[138:139] op_sel_hi:[1,0]
	v_pk_mul_f32 v[140:141], v[108:109], v[138:139] op_sel_hi:[1,0]
	v_pk_mul_f32 v[144:145], v[106:107], v[138:139] op_sel_hi:[1,0]
	v_cvt_pk_bf16_f32 v134, v134, v135
	v_cvt_pk_bf16_f32 v135, v136, v137
	v_cvt_pk_bf16_f32 v136, v144, v145
	v_cvt_pk_bf16_f32 v137, v140, v141
	v_pk_mul_f32 v[140:141], v[104:105], v[138:139] op_sel_hi:[1,0]
	v_pk_mul_f32 v[144:145], v[102:103], v[138:139] op_sel_hi:[1,0]
	v_pk_mul_f32 v[146:147], v[100:101], v[138:139] op_sel_hi:[1,0]
	v_pk_mul_f32 v[148:149], v[98:99], v[138:139] op_sel_hi:[1,0]
	v_cvt_pk_bf16_f32 v138, v144, v145
	v_cvt_pk_bf16_f32 v139, v140, v141
	v_cvt_pk_bf16_f32 v140, v148, v149
	v_cvt_pk_bf16_f32 v141, v146, v147
	ds_write_b128 v151, v[134:137]
	ds_write_b128 v152, v[138:141]
	ds_read_b128 v[134:137], v153
	ds_read_b128 v[138:141], v153 offset:1024
	v_lshl_add_u64 v[142:143], v[130:131], 0, v[142:143]
	s_waitcnt lgkmcnt(1)
	global_store_dwordx4 v[142:143], v[134:137], off nt
	s_nop 1
	v_add_co_u32_e32 v134, vcc, s92, v142
	v_add_u32_e32 v142, 32, v132
	s_nop 0
	v_addc_co_u32_e32 v135, vcc, 0, v143, vcc
	s_waitcnt lgkmcnt(0)
	global_store_dwordx4 v[134:135], v[138:141], off nt
	v_ashrrev_i32_e32 v143, 31, v142
	v_lshlrev_b64 v[142:143], 9, v[142:143]
	v_mul_f32_e32 v138, v150, v208
	v_pk_mul_f32 v[136:137], v[96:97], v[138:139] op_sel_hi:[1,0]
	v_pk_mul_f32 v[134:135], v[94:95], v[138:139] op_sel_hi:[1,0]
	v_pk_mul_f32 v[140:141], v[92:93], v[138:139] op_sel_hi:[1,0]
	v_pk_mul_f32 v[144:145], v[90:91], v[138:139] op_sel_hi:[1,0]
	v_cvt_pk_bf16_f32 v134, v134, v135
	v_cvt_pk_bf16_f32 v135, v136, v137
	v_cvt_pk_bf16_f32 v136, v144, v145
	v_cvt_pk_bf16_f32 v137, v140, v141
	v_pk_mul_f32 v[140:141], v[88:89], v[138:139] op_sel_hi:[1,0]
	v_pk_mul_f32 v[144:145], v[86:87], v[138:139] op_sel_hi:[1,0]
	v_pk_mul_f32 v[146:147], v[84:85], v[138:139] op_sel_hi:[1,0]
	v_pk_mul_f32 v[148:149], v[82:83], v[138:139] op_sel_hi:[1,0]
	v_cvt_pk_bf16_f32 v138, v144, v145
	v_cvt_pk_bf16_f32 v139, v140, v141
	v_cvt_pk_bf16_f32 v140, v148, v149
	v_cvt_pk_bf16_f32 v141, v146, v147
	ds_write_b128 v151, v[134:137]
	ds_write_b128 v152, v[138:141]
	ds_read_b128 v[134:137], v153
	ds_read_b128 v[138:141], v153 offset:1024
	v_lshl_add_u64 v[142:143], v[130:131], 0, v[142:143]
	s_waitcnt lgkmcnt(1)
	global_store_dwordx4 v[142:143], v[134:137], off nt
	s_nop 1
	v_add_co_u32_e32 v134, vcc, s92, v142
	v_add_u32_e32 v142, 48, v132
	s_nop 0
	v_addc_co_u32_e32 v135, vcc, 0, v143, vcc
	s_waitcnt lgkmcnt(0)
	global_store_dwordx4 v[134:135], v[138:141], off nt
	v_ashrrev_i32_e32 v143, 31, v142
	v_lshlrev_b64 v[142:143], 9, v[142:143]
	v_mul_f32_e32 v138, v150, v206
	v_pk_mul_f32 v[136:137], v[80:81], v[138:139] op_sel_hi:[1,0]
	v_pk_mul_f32 v[134:135], v[78:79], v[138:139] op_sel_hi:[1,0]
	v_pk_mul_f32 v[140:141], v[76:77], v[138:139] op_sel_hi:[1,0]
	v_pk_mul_f32 v[144:145], v[74:75], v[138:139] op_sel_hi:[1,0]
	v_cvt_pk_bf16_f32 v134, v134, v135
	v_cvt_pk_bf16_f32 v135, v136, v137
	v_cvt_pk_bf16_f32 v136, v144, v145
	v_cvt_pk_bf16_f32 v137, v140, v141
	v_pk_mul_f32 v[140:141], v[72:73], v[138:139] op_sel_hi:[1,0]
	v_pk_mul_f32 v[144:145], v[70:71], v[138:139] op_sel_hi:[1,0]
	v_pk_mul_f32 v[146:147], v[68:69], v[138:139] op_sel_hi:[1,0]
	v_pk_mul_f32 v[148:149], v[66:67], v[138:139] op_sel_hi:[1,0]
	v_cvt_pk_bf16_f32 v138, v144, v145
	v_cvt_pk_bf16_f32 v139, v140, v141
	v_cvt_pk_bf16_f32 v140, v148, v149
	v_cvt_pk_bf16_f32 v141, v146, v147
	ds_write_b128 v151, v[134:137]
	ds_write_b128 v152, v[138:141]
	ds_read_b128 v[134:137], v153
	ds_read_b128 v[138:141], v153 offset:1024
	v_lshl_add_u64 v[142:143], v[130:131], 0, v[142:143]
	s_waitcnt lgkmcnt(1)
; __device__ __forceinline__ v4u pack8(const f32x4 a, const f32x4 b) { v4u w; w.x = pk2(a[0], a[1]); w.y = pk2(a[2], a[3]); w.z = pk2(b[0], b[1]); w.w = pk2(b[2], b[3]); return w; }
;     __device__ __forceinline__ void operator()(const f32x4 (&acc)[2][2][4][2], const pg8::Unit& u, int wr, int wc, int fr, int fq) const {
;     ...
; #pragma unroll
;             for (int ai = 0; ai < 2; ++ai)
; #pragma unroll
;                 for (int m = 0; m < 4; ++m) {
;                     const int rowa = 256 * pm + 128 * ai + 64 * wr + 16 * m + tt.rr;
;                     const float rs = rs8[ai][m] * sc;
;                     v4u a, b; tt.bf(pack8(acc[ai][0][m][0] * rs, acc[ai][0][m][1] * rs), pack8(acc[ai][1][m][0] * rs, acc[ai][1][m][1] * rs), a, b);
;                     bf16* d = dst + (size_t)rowa * 256 + wc * 64 + 8 * tt.p; *(v4u*)d = a; *(v4u*)(d + 8 * 256) = b;
	global_store_dwordx4 v[142:143], v[134:137], off nt
	s_nop 1
	v_add_co_u32_e32 v134, vcc, s92, v142
	v_add_u32_e32 v142, 0x80, v132
	s_nop 0
	v_addc_co_u32_e32 v135, vcc, 0, v143, vcc
	s_waitcnt lgkmcnt(0)
	global_store_dwordx4 v[134:135], v[138:141], off nt
	v_ashrrev_i32_e32 v143, 31, v142
	v_lshlrev_b64 v[142:143], 9, v[142:143]
	v_mul_f32_e32 v138, v150, v204
	v_pk_mul_f32 v[136:137], v[64:65], v[138:139] op_sel_hi:[1,0]
	v_pk_mul_f32 v[134:135], v[62:63], v[138:139] op_sel_hi:[1,0]
	v_pk_mul_f32 v[140:141], v[60:61], v[138:139] op_sel_hi:[1,0]
	v_pk_mul_f32 v[144:145], v[58:59], v[138:139] op_sel_hi:[1,0]
	v_cvt_pk_bf16_f32 v134, v134, v135
	v_cvt_pk_bf16_f32 v135, v136, v137
	v_cvt_pk_bf16_f32 v136, v144, v145
	v_cvt_pk_bf16_f32 v137, v140, v141
	v_pk_mul_f32 v[140:141], v[56:57], v[138:139] op_sel_hi:[1,0]
	v_pk_mul_f32 v[144:145], v[54:55], v[138:139] op_sel_hi:[1,0]
	v_pk_mul_f32 v[146:147], v[52:53], v[138:139] op_sel_hi:[1,0]
	v_pk_mul_f32 v[148:149], v[50:51], v[138:139] op_sel_hi:[1,0]
	v_cvt_pk_bf16_f32 v138, v144, v145
	v_cvt_pk_bf16_f32 v139, v140, v141
	v_cvt_pk_bf16_f32 v140, v148, v149
	v_cvt_pk_bf16_f32 v141, v146, v147
	ds_write_b128 v151, v[134:137]
	ds_write_b128 v152, v[138:141]
	ds_read_b128 v[134:137], v153
	ds_read_b128 v[138:141], v153 offset:1024
	v_lshl_add_u64 v[142:143], v[130:131], 0, v[142:143]
	s_waitcnt lgkmcnt(1)
	global_store_dwordx4 v[142:143], v[134:137], off nt
	s_nop 1
	v_add_co_u32_e32 v134, vcc, s92, v142
	v_add_u32_e32 v142, 0x90, v132
	s_nop 0
	v_addc_co_u32_e32 v135, vcc, 0, v143, vcc
	s_waitcnt lgkmcnt(0)
	global_store_dwordx4 v[134:135], v[138:141], off nt
	v_ashrrev_i32_e32 v143, 31, v142
	v_lshlrev_b64 v[142:143], 9, v[142:143]
	v_mul_f32_e32 v138, v150, v202
	v_pk_mul_f32 v[136:137], v[48:49], v[138:139] op_sel_hi:[1,0]
	v_pk_mul_f32 v[134:135], v[46:47], v[138:139] op_sel_hi:[1,0]
	v_pk_mul_f32 v[140:141], v[44:45], v[138:139] op_sel_hi:[1,0]
	v_pk_mul_f32 v[144:145], v[42:43], v[138:139] op_sel_hi:[1,0]
	v_cvt_pk_bf16_f32 v134, v134, v135
	v_cvt_pk_bf16_f32 v135, v136, v137
	v_cvt_pk_bf16_f32 v136, v144, v145
	v_cvt_pk_bf16_f32 v137, v140, v141
	v_pk_mul_f32 v[140:141], v[40:41], v[138:139] op_sel_hi:[1,0]
	v_pk_mul_f32 v[144:145], v[38:39], v[138:139] op_sel_hi:[1,0]
	v_pk_mul_f32 v[146:147], v[36:37], v[138:139] op_sel_hi:[1,0]
	v_pk_mul_f32 v[148:149], v[34:35], v[138:139] op_sel_hi:[1,0]
	v_cvt_pk_bf16_f32 v138, v144, v145
	v_cvt_pk_bf16_f32 v139, v140, v141
	v_cvt_pk_bf16_f32 v140, v148, v149
	v_cvt_pk_bf16_f32 v141, v146, v147
	ds_write_b128 v151, v[134:137]
	ds_write_b128 v152, v[138:141]
	ds_read_b128 v[134:137], v153
	ds_read_b128 v[138:141], v153 offset:1024
	v_lshl_add_u64 v[142:143], v[130:131], 0, v[142:143]
	s_waitcnt lgkmcnt(1)
	global_store_dwordx4 v[142:143], v[134:137], off nt
	s_nop 1
	v_add_co_u32_e32 v134, vcc, s92, v142
	v_add_u32_e32 v142, 0xa0, v132
	s_nop 0
	v_addc_co_u32_e32 v135, vcc, 0, v143, vcc
	s_waitcnt lgkmcnt(0)
	global_store_dwordx4 v[134:135], v[138:141], off nt
	v_ashrrev_i32_e32 v143, 31, v142
	v_lshlrev_b64 v[142:143], 9, v[142:143]
	v_mul_f32_e32 v138, v150, v198
	v_pk_mul_f32 v[136:137], v[32:33], v[138:139] op_sel_hi:[1,0]
	v_pk_mul_f32 v[134:135], v[30:31], v[138:139] op_sel_hi:[1,0]
	v_pk_mul_f32 v[140:141], v[28:29], v[138:139] op_sel_hi:[1,0]
	v_pk_mul_f32 v[144:145], v[26:27], v[138:139] op_sel_hi:[1,0]
	v_cvt_pk_bf16_f32 v134, v134, v135
	v_cvt_pk_bf16_f32 v135, v136, v137
	v_cvt_pk_bf16_f32 v136, v144, v145
	v_cvt_pk_bf16_f32 v137, v140, v141
	v_pk_mul_f32 v[140:141], v[24:25], v[138:139] op_sel_hi:[1,0]
	v_pk_mul_f32 v[144:145], v[22:23], v[138:139] op_sel_hi:[1,0]
	v_pk_mul_f32 v[146:147], v[20:21], v[138:139] op_sel_hi:[1,0]
	v_pk_mul_f32 v[148:149], v[18:19], v[138:139] op_sel_hi:[1,0]
	v_cvt_pk_bf16_f32 v138, v144, v145
	v_cvt_pk_bf16_f32 v139, v140, v141
	v_cvt_pk_bf16_f32 v140, v148, v149
	v_cvt_pk_bf16_f32 v141, v146, v147
	ds_write_b128 v151, v[134:137]
	ds_write_b128 v152, v[138:141]
	ds_read_b128 v[134:137], v153
	ds_read_b128 v[138:141], v153 offset:1024
	v_lshl_add_u64 v[142:143], v[130:131], 0, v[142:143]
	s_waitcnt lgkmcnt(1)
	global_store_dwordx4 v[142:143], v[134:137], off nt
	s_nop 1
	v_add_co_u32_e32 v134, vcc, s92, v142
	v_mul_f32_e32 v136, v150, v196
	s_nop 0
	v_addc_co_u32_e32 v135, vcc, 0, v143, vcc
	s_waitcnt lgkmcnt(0)
	global_store_dwordx4 v[134:135], v[138:141], off nt
	v_pk_mul_f32 v[134:135], v[16:17], v[136:137] op_sel_hi:[1,0]
	v_pk_mul_f32 v[142:143], v[10:11], v[136:137] op_sel_hi:[1,0]
	v_add_u32_e32 v140, 0xb0, v132
	v_pk_mul_f32 v[132:133], v[14:15], v[136:137] op_sel_hi:[1,0]
	v_pk_mul_f32 v[138:139], v[12:13], v[136:137] op_sel_hi:[1,0]
	v_cvt_pk_bf16_f32 v132, v132, v133
	v_cvt_pk_bf16_f32 v133, v134, v135
	v_cvt_pk_bf16_f32 v134, v142, v143
	v_cvt_pk_bf16_f32 v135, v138, v139
	v_pk_mul_f32 v[138:139], v[8:9], v[136:137] op_sel_hi:[1,0]
	v_pk_mul_f32 v[142:143], v[6:7], v[136:137] op_sel_hi:[1,0]
	v_pk_mul_f32 v[144:145], v[4:5], v[136:137] op_sel_hi:[1,0]
	v_pk_mul_f32 v[146:147], v[2:3], v[136:137] op_sel_hi:[1,0]
	v_cvt_pk_bf16_f32 v136, v142, v143
	v_cvt_pk_bf16_f32 v137, v138, v139
	v_cvt_pk_bf16_f32 v138, v146, v147
	v_cvt_pk_bf16_f32 v139, v144, v145
	ds_write_b128 v151, v[132:135]
	ds_write_b128 v152, v[136:139]
	ds_read_b128 v[132:135], v153
	ds_read_b128 v[136:139], v153 offset:1024
	v_ashrrev_i32_e32 v141, 31, v140
	v_lshlrev_b64 v[140:141], 9, v[140:141]
	v_lshl_add_u64 v[130:131], v[130:131], 0, v[140:141]
	s_waitcnt lgkmcnt(1)
	global_store_dwordx4 v[130:131], v[132:135], off nt
	v_add_co_u32_e32 v130, vcc, 0x1000, v130
	s_nop 1
	v_addc_co_u32_e32 v131, vcc, 0, v131, vcc
	s_waitcnt lgkmcnt(0)
	global_store_dwordx4 v[130:131], v[136:139], off nt
